# GEMM k-loops: persistent LDS-DMA pointers (no 64-bit VALU between reads and first MFMA; +64 bumps inside ladder)
# speedup vs baseline: 1.0054x; 1.0023x over previous
.LBB0_29:
	s_ashr_i32 s13, s12, 31
	s_lshr_b32 s13, s13, 28
	s_add_i32 s13, s12, s13
	s_and_b32 s40, s13, 0x1fffff0
	s_sub_i32 s12, s12, s40
	s_add_i32 s12, s12, s15
	s_lshl_b32 s57, s12, 7
	s_lshl_b32 s12, s13, 4
	s_waitcnt vmcnt(6)
	v_mov_b32_e32 v58, v224
	s_and_b32 s54, s12, 0xffffff00
	s_waitcnt vmcnt(0)
	s_nop 0
	v_readfirstlane_b32 s12, v58
	v_bfe_u32 v59, v58, 4, 2
	s_and_b32 s40, s12, 0xffffffc0
	s_waitcnt vmcnt(4)
	v_bfe_u32 v42, v58, 2, 4
	v_sub_u32_e32 v60, 0, v59
	s_add_i32 s40, s40, s54
	v_xor_b32_e32 v0, v58, v60
	v_or_b32_e32 v6, s40, v42
	v_lshlrev_b32_e32 v0, 4, v0
	v_min_i32_e32 v4, 0x3ff, v6
	v_and_b32_e32 v0, 48, v0
	v_ashrrev_i32_e32 v5, 31, v4
	v_lshl_add_u64 v[2:3], s[48:49], 0, v[0:1]
	v_lshlrev_b64 v[4:5], 11, v[4:5]
	v_lshl_add_u64 v[34:35], v[2:3], 0, v[4:5]
	v_or_b32_e32 v4, 16, v6
	v_min_i32_e32 v4, 0x3ff, v4
	v_ashrrev_i32_e32 v5, 31, v4
	v_lshlrev_b64 v[4:5], 11, v[4:5]
	v_lshl_add_u64 v[36:37], v[2:3], 0, v[4:5]
	v_or_b32_e32 v4, 32, v6
	v_min_i32_e32 v4, 0x3ff, v4
	s_ashr_i32 s13, s12, 6
	v_ashrrev_i32_e32 v5, 31, v4
	s_and_b32 s42, s13, 1
	v_lshlrev_b64 v[4:5], 11, v[4:5]
	v_lshl_add_u64 v[38:39], v[2:3], 0, v[4:5]
	v_or_b32_e32 v4, 48, v6
	s_lshl_b32 s40, s42, 6
	v_min_i32_e32 v4, 0x3ff, v4
	v_and_b32_e32 v61, 15, v58
	s_or_b32 s40, s40, s57
	v_ashrrev_i32_e32 v5, 31, v4
	s_waitcnt vmcnt(1)
	v_or_b32_e32 v14, s40, v61
	v_lshlrev_b64 v[4:5], 11, v[4:5]
	v_ashrrev_i32_e32 v15, 31, v14
	v_lshl_add_u64 v[40:41], v[2:3], 0, v[4:5]
	v_lshlrev_b64 v[2:3], 5, v[14:15]
	v_lshl_add_u64 v[2:3], s[46:47], 0, v[2:3]
	s_barrier
	global_load_dwordx4 v[6:9], v[2:3], off offset:16
	global_load_dwordx4 v[22:25], v[2:3], off
	v_or_b32_e32 v2, 16, v14
	v_ashrrev_i32_e32 v3, 31, v2
	v_lshlrev_b64 v[2:3], 5, v[2:3]
	v_lshl_add_u64 v[10:11], s[46:47], 0, v[2:3]
	global_load_dwordx4 v[2:5], v[10:11], off offset:16
	global_load_dwordx4 v[18:21], v[10:11], off
	v_or_b32_e32 v10, 32, v14
	v_or_b32_e32 v14, 48, v14
	v_ashrrev_i32_e32 v11, 31, v10
	v_ashrrev_i32_e32 v15, 31, v14
	v_lshlrev_b64 v[10:11], 5, v[10:11]
	v_lshlrev_b64 v[14:15], 5, v[14:15]
	v_lshl_add_u64 v[16:17], s[46:47], 0, v[10:11]
	v_lshl_add_u64 v[30:31], s[46:47], 0, v[14:15]
	global_load_dwordx4 v[10:13], v[16:17], off offset:16
	global_load_dwordx4 v[26:29], v[16:17], off
	s_nop 0
	global_load_dwordx4 v[14:17], v[30:31], off offset:16
	s_nop 0
	global_load_dwordx4 v[30:33], v[30:31], off
	s_lshl_b32 s40, s13, 1
	s_waitcnt vmcnt(8)
	v_or_b32_e32 v46, s57, v42
	v_lshl_add_u32 v44, s13, 5, v46
	s_lshl_b32 s41, s40, 10
	s_or_b32 s40, s40, 1
	v_ashrrev_i32_e32 v45, 31, v44
	v_lshl_add_u32 v46, s40, 4, v46
	v_lshl_add_u64 v[42:43], s[0:1], 0, v[0:1]
	v_lshlrev_b64 v[162:163], 10, v[44:45]
	v_lshlrev_b64 v[44:45], 11, v[44:45]
	v_ashrrev_i32_e32 v47, 31, v46
	v_lshl_add_u64 v[44:45], v[42:43], 0, v[44:45]
	v_lshlrev_b64 v[164:165], 10, v[46:47]
	v_lshlrev_b64 v[46:47], 11, v[46:47]
	s_mov_b32 s45, m0
	s_mov_b32 m0, s41
	s_nop 0
	global_load_lds_dwordx4 v[44:45], off
	s_mov_b32 m0, s45
	v_lshl_add_u64 v[42:43], v[42:43], 0, v[46:47]
	s_lshl_b32 s43, s13, 12
	s_add_i32 s44, s41, 0x6000
	s_lshl_b32 s40, s40, 10
	s_mov_b32 s41, m0
	s_mov_b32 m0, s40
	s_nop 0
	global_load_lds_dwordx4 v[42:43], off
	s_mov_b32 m0, s41
	s_add_i32 s41, s43, 0x2000
	s_mov_b32 s45, m0
	s_mov_b32 m0, s41
	s_nop 0
	global_load_lds_dwordx4 v[34:35], off
	s_mov_b32 m0, s45
	s_add_i32 s45, s43, 0x2400
	s_mov_b32 s55, m0
	s_mov_b32 m0, s45
	s_nop 0
	global_load_lds_dwordx4 v[36:37], off
	s_mov_b32 m0, s55
	s_add_i32 s45, s43, 0x2800
	s_mov_b32 s55, m0
	s_mov_b32 m0, s45
	s_nop 0
	global_load_lds_dwordx4 v[38:39], off
	s_mov_b32 m0, s55
	s_add_i32 s45, s43, 0x2c00
	s_mov_b32 s55, m0
	s_mov_b32 m0, s45
	s_nop 0
	global_load_lds_dwordx4 v[40:41], off
	s_mov_b32 m0, s55
	v_lshl_add_u64 v[46:47], v[44:45], 0, 64
	s_mov_b32 s45, m0
	s_mov_b32 m0, s44
	s_nop 0
	global_load_lds_dwordx4 v[46:47], off
	s_mov_b32 m0, s45
	v_lshl_add_u64 v[48:49], v[42:43], 0, 64
	s_add_i32 s44, s40, 0x6000
	s_mov_b32 s45, m0
	s_mov_b32 m0, s44
	s_nop 0
	global_load_lds_dwordx4 v[48:49], off
	s_mov_b32 m0, s45
	v_lshrrev_b32_e32 v0, 2, v58
	v_lshl_add_u64 v[50:51], v[34:35], 0, 64
	s_add_i32 s44, s43, 0x8000
	s_mov_b32 s45, m0
	s_mov_b32 m0, s44
	s_nop 0
	global_load_lds_dwordx4 v[50:51], off
	s_mov_b32 m0, s45
	v_sub_u32_e32 v0, 0, v0
	v_lshl_add_u64 v[52:53], v[36:37], 0, 64
	s_add_i32 s44, s43, 0x8400
	s_mov_b32 s45, m0
	s_mov_b32 m0, s44
	s_nop 0
	global_load_lds_dwordx4 v[52:53], off
	s_mov_b32 m0, s45
	v_bitop3_b32 v0, v59, v0, 3 bitop3:0x78
	s_and_b32 s12, s12, 0x3ffff80
	v_lshl_add_u64 v[54:55], v[38:39], 0, 64
	s_add_i32 s44, s43, 0x8800
	s_mov_b32 s45, m0
	s_mov_b32 m0, s44
	s_nop 0
	global_load_lds_dwordx4 v[54:55], off
	s_mov_b32 m0, s45
	v_lshlrev_b32_e32 v176, 4, v0
	v_or_b32_e32 v0, s12, v61
	v_lshl_add_u64 v[56:57], v[40:41], 0, 64
	s_add_i32 s43, s43, 0x8c00
	s_mov_b32 s44, m0
	s_mov_b32 m0, s43
	s_nop 0
	global_load_lds_dwordx4 v[56:57], off
	s_mov_b32 m0, s44
	v_lshlrev_b32_e32 v178, 6, v0
	v_bitop3_b32 v0, v58, 3, v60 bitop3:0x48
	v_lshl_add_u64 v[172:173], v[34:35], 0, s[6:7]
	v_lshlrev_b32_e32 v0, 4, v0
	v_mov_b32_e32 v34, 0
	s_lshl_b32 s55, s42, 12
	v_lshlrev_b32_e32 v177, 6, v61
	s_lshl_b32 s42, s13, 11
	v_lshl_add_u64 v[166:167], v[40:41], 0, s[6:7]
	v_lshl_add_u64 v[168:169], v[38:39], 0, s[6:7]
	v_lshl_add_u64 v[170:171], v[36:37], 0, s[6:7]
	v_lshl_add_u64 v[174:175], s[52:53], 0, v[0:1]
	s_mov_b64 s[12:13], 0
	s_mov_b32 s43, 0
	v_mov_b32_e32 v35, v34
	v_mov_b32_e32 v36, v34
	v_mov_b32_e32 v37, v34
	v_mov_b32_e32 v38, v34
	v_mov_b32_e32 v39, v34
	v_mov_b32_e32 v40, v34
	v_mov_b32_e32 v41, v34
	v_mov_b32_e32 v42, v34
	v_mov_b32_e32 v43, v34
	v_mov_b32_e32 v44, v34
	v_mov_b32_e32 v45, v34
	v_mov_b32_e32 v46, v34
	v_mov_b32_e32 v47, v34
	v_mov_b32_e32 v48, v34
	v_mov_b32_e32 v49, v34
	v_mov_b32_e32 v50, v34
	v_mov_b32_e32 v51, v34
	v_mov_b32_e32 v52, v34
	v_mov_b32_e32 v53, v34
	v_mov_b32_e32 v54, v34
	v_mov_b32_e32 v55, v34
	v_mov_b32_e32 v56, v34
	v_mov_b32_e32 v57, v34
	v_mov_b32_e32 v58, v34
	v_mov_b32_e32 v59, v34
	v_mov_b32_e32 v60, v34
	v_mov_b32_e32 v61, v34
	v_mov_b32_e32 v62, v34
	v_mov_b32_e32 v63, v34
	v_mov_b32_e32 v64, v34
	v_mov_b32_e32 v65, v34
	v_mov_b32_e32 v66, v34
	v_mov_b32_e32 v67, v34
	v_mov_b32_e32 v68, v34
	v_mov_b32_e32 v69, v34
	v_mov_b32_e32 v70, v34
	v_mov_b32_e32 v71, v34
	v_mov_b32_e32 v72, v34
	v_mov_b32_e32 v73, v34
	v_mov_b32_e32 v74, v34
	v_mov_b32_e32 v75, v34
	v_mov_b32_e32 v76, v34
	v_mov_b32_e32 v77, v34
	v_mov_b32_e32 v78, v34
	v_mov_b32_e32 v79, v34
	v_mov_b32_e32 v80, v34
	v_mov_b32_e32 v81, v34
	v_mov_b32_e32 v82, v34
	v_mov_b32_e32 v83, v34
	v_mov_b32_e32 v84, v34
	v_mov_b32_e32 v85, v34
	v_mov_b32_e32 v86, v34
	v_mov_b32_e32 v87, v34
	v_mov_b32_e32 v88, v34
	v_mov_b32_e32 v89, v34
	v_mov_b32_e32 v90, v34
	v_mov_b32_e32 v91, v34
	v_mov_b32_e32 v92, v34
	v_mov_b32_e32 v93, v34
	v_mov_b32_e32 v94, v34
	v_mov_b32_e32 v95, v34
	v_mov_b32_e32 v96, v34
	v_mov_b32_e32 v97, v34
	v_mov_b32_e32 v98, v34
	v_mov_b32_e32 v99, v34
	v_mov_b32_e32 v100, v34
	v_mov_b32_e32 v101, v34
	v_mov_b32_e32 v102, v34
	v_mov_b32_e32 v103, v34
	v_mov_b32_e32 v104, v34
	v_mov_b32_e32 v105, v34
	v_mov_b32_e32 v106, v34
	v_mov_b32_e32 v107, v34
	v_mov_b32_e32 v108, v34
	v_mov_b32_e32 v109, v34
	v_mov_b32_e32 v110, v34
	v_mov_b32_e32 v111, v34
	v_mov_b32_e32 v112, v34
	v_mov_b32_e32 v113, v34
	v_mov_b32_e32 v114, v34
	v_mov_b32_e32 v115, v34
	v_mov_b32_e32 v116, v34
	v_mov_b32_e32 v117, v34
	v_mov_b32_e32 v118, v34
	v_mov_b32_e32 v119, v34
	v_mov_b32_e32 v120, v34
	v_mov_b32_e32 v121, v34
	v_mov_b32_e32 v122, v34
	v_mov_b32_e32 v123, v34
	v_mov_b32_e32 v124, v34
	v_mov_b32_e32 v125, v34
	v_mov_b32_e32 v126, v34
	v_mov_b32_e32 v127, v34
	v_mov_b32_e32 v128, v34
	v_mov_b32_e32 v129, v34
	v_mov_b32_e32 v130, v34
	v_mov_b32_e32 v131, v34
	v_mov_b32_e32 v132, v34
	v_mov_b32_e32 v133, v34
	v_mov_b32_e32 v134, v34
	v_mov_b32_e32 v135, v34
	v_mov_b32_e32 v136, v34
	v_mov_b32_e32 v137, v34
	v_mov_b32_e32 v138, v34
	v_mov_b32_e32 v139, v34
	v_mov_b32_e32 v140, v34
	v_mov_b32_e32 v141, v34
	v_mov_b32_e32 v142, v34
	v_mov_b32_e32 v143, v34
	v_mov_b32_e32 v144, v34
	v_mov_b32_e32 v145, v34
	v_mov_b32_e32 v146, v34
	v_mov_b32_e32 v147, v34
	v_mov_b32_e32 v148, v34
	v_mov_b32_e32 v149, v34
	v_mov_b32_e32 v150, v34
	v_mov_b32_e32 v151, v34
	v_mov_b32_e32 v152, v34
	v_mov_b32_e32 v153, v34
	v_mov_b32_e32 v154, v34
	v_mov_b32_e32 v155, v34
	v_mov_b32_e32 v156, v34
	v_mov_b32_e32 v157, v34
	v_mov_b32_e32 v158, v34
	v_mov_b32_e32 v159, v34
	v_mov_b32_e32 v160, v34
	v_mov_b32_e32 v161, v34
	v_lshl_add_u64 v[162:163], v[162:163], 1, v[174:175]
	v_lshl_add_u64 v[164:165], v[164:165], 1, v[174:175]
.LBB0_30:
	s_mul_i32 s44, s43, 0x6000
	s_add_i32 s45, s44, 0xffffa000
	s_cmp_gt_i32 s43, 0
	s_waitcnt vmcnt(6)
	s_cselect_b32 s45, s45, 0xc000
	s_waitcnt lgkmcnt(0)
	s_barrier
	s_setprio 2
	v_add3_u32 v0, s44, v177, v176
	v_add_u32_e32 v0, s55, v0
	v_add3_u32 v212, s44, v178, v176
	ds_read_b128 v[196:199], v212 offset:8192
	ds_read_b128 v[180:183], v0
	ds_read_b128 v[184:187], v0 offset:1024
	ds_read_b128 v[188:191], v0 offset:2048
	ds_read_b128 v[192:195], v0 offset:3072
	ds_read_b128 v[200:203], v212 offset:9216
	ds_read_b128 v[204:207], v212 offset:10240
	ds_read_b128 v[208:211], v212 offset:11264
	ds_read_b128 v[216:219], v212 offset:12288
	ds_read_b128 v[226:229], v212 offset:13312
	ds_read_b128 v[230:233], v212 offset:14336
	ds_read_b128 v[234:237], v212 offset:15360
	s_add_i32 s68, s45, s42
	s_mov_b32 m0, s68
	s_nop 0
	global_load_lds_dwordx4 v[162:163], off
	s_add_i32 s68, s45, s40
	s_mov_b32 m0, s68
	s_nop 0
	global_load_lds_dwordx4 v[164:165], off
	s_add_i32 s45, s41, s45
	s_mov_b32 m0, s45
	s_nop 0
	global_load_lds_dwordx4 v[172:173], off
	s_add_i32 s68, s45, 0x400
	s_mov_b32 m0, s68
	s_nop 0
	global_load_lds_dwordx4 v[170:171], off
	s_add_i32 s68, s45, 0x800
	s_mov_b32 m0, s68
	s_nop 0
	global_load_lds_dwordx4 v[168:169], off
	s_addk_i32 s45, 0xc00
	s_mov_b32 m0, s45
	s_nop 0
	global_load_lds_dwordx4 v[166:167], off
	s_setprio 0
	s_waitcnt lgkmcnt(10)
	v_mfma_f32_16x16x32_bf16 v[34:37], v[196:199], v[180:183], v[34:37]
	s_waitcnt lgkmcnt(9)
	v_mfma_f32_16x16x32_bf16 v[38:41], v[196:199], v[184:187], v[38:41]
	s_waitcnt lgkmcnt(8)
	v_mfma_f32_16x16x32_bf16 v[42:45], v[196:199], v[188:191], v[42:45]
	s_waitcnt lgkmcnt(7)
	v_mfma_f32_16x16x32_bf16 v[46:49], v[196:199], v[192:195], v[46:49]
	s_waitcnt lgkmcnt(6)
	v_mfma_f32_16x16x32_bf16 v[50:53], v[200:203], v[180:183], v[50:53]
	v_mfma_f32_16x16x32_bf16 v[54:57], v[200:203], v[184:187], v[54:57]
	v_lshl_add_u64 v[162:163], v[162:163], 0, 64
	v_mfma_f32_16x16x32_bf16 v[58:61], v[200:203], v[188:191], v[58:61]
	v_mfma_f32_16x16x32_bf16 v[62:65], v[200:203], v[192:195], v[62:65]
	s_waitcnt lgkmcnt(5)
	v_mfma_f32_16x16x32_bf16 v[66:69], v[204:207], v[180:183], v[66:69]
	v_mfma_f32_16x16x32_bf16 v[70:73], v[204:207], v[184:187], v[70:73]
	v_lshl_add_u64 v[164:165], v[164:165], 0, 64
	v_mfma_f32_16x16x32_bf16 v[74:77], v[204:207], v[188:191], v[74:77]
	v_mfma_f32_16x16x32_bf16 v[78:81], v[204:207], v[192:195], v[78:81]
	s_waitcnt lgkmcnt(4)
	v_mfma_f32_16x16x32_bf16 v[82:85], v[208:211], v[180:183], v[82:85]
	v_mfma_f32_16x16x32_bf16 v[86:89], v[208:211], v[184:187], v[86:89]
	v_lshl_add_u64 v[172:173], v[172:173], 0, 64
	v_mfma_f32_16x16x32_bf16 v[90:93], v[208:211], v[188:191], v[90:93]
	v_mfma_f32_16x16x32_bf16 v[94:97], v[208:211], v[192:195], v[94:97]
	s_waitcnt lgkmcnt(3)
	v_mfma_f32_16x16x32_bf16 v[98:101], v[216:219], v[180:183], v[98:101]
	v_mfma_f32_16x16x32_bf16 v[102:105], v[216:219], v[184:187], v[102:105]
	v_lshl_add_u64 v[170:171], v[170:171], 0, 64
	v_mfma_f32_16x16x32_bf16 v[106:109], v[216:219], v[188:191], v[106:109]
	v_mfma_f32_16x16x32_bf16 v[110:113], v[216:219], v[192:195], v[110:113]
	s_waitcnt lgkmcnt(2)
	v_mfma_f32_16x16x32_bf16 v[114:117], v[226:229], v[180:183], v[114:117]
	v_mfma_f32_16x16x32_bf16 v[118:121], v[226:229], v[184:187], v[118:121]
	v_lshl_add_u64 v[168:169], v[168:169], 0, 64
	v_mfma_f32_16x16x32_bf16 v[122:125], v[226:229], v[188:191], v[122:125]
	v_mfma_f32_16x16x32_bf16 v[126:129], v[226:229], v[192:195], v[126:129]
	s_waitcnt lgkmcnt(1)
	v_mfma_f32_16x16x32_bf16 v[130:133], v[230:233], v[180:183], v[130:133]
	v_mfma_f32_16x16x32_bf16 v[134:137], v[230:233], v[184:187], v[134:137]
	v_lshl_add_u64 v[166:167], v[166:167], 0, 64
	v_mfma_f32_16x16x32_bf16 v[138:141], v[230:233], v[188:191], v[138:141]
	v_mfma_f32_16x16x32_bf16 v[142:145], v[230:233], v[192:195], v[142:145]
	s_waitcnt lgkmcnt(0)
	v_mfma_f32_16x16x32_bf16 v[146:149], v[234:237], v[180:183], v[146:149]
	v_mfma_f32_16x16x32_bf16 v[150:153], v[234:237], v[184:187], v[150:153]
	v_mfma_f32_16x16x32_bf16 v[154:157], v[234:237], v[188:191], v[154:157]
	v_mfma_f32_16x16x32_bf16 v[158:161], v[234:237], v[192:195], v[158:161]
	s_add_i32 s44, s43, 1
	s_cmp_lg_u32 s43, 2
	s_cselect_b32 s43, s44, 0
	s_add_u32 s12, s12, 64
	s_addc_u32 s13, s13, 0
	s_cmpk_eq_i32 s12, 0x780
	s_cbranch_scc0 .LBB0_30
	s_waitcnt vmcnt(6)
	v_mov_b32_e32 v162, v23
	v_mov_b32_e32 v163, v24
	v_mov_b32_e32 v23, v25
	v_mov_b32_e32 v164, v7
	v_mov_b32_e32 v165, v8
	v_pk_add_f32 v[22:23], v[162:163], v[22:23]
	v_mov_b32_e32 v7, v9
	v_pk_add_f32 v[6:7], v[164:165], v[6:7]
	v_add_f32_e32 v0, v22, v23
	v_add_f32_e32 v0, v0, v6
	v_add_f32_e32 v0, v0, v7
	v_fmamk_f32 v0, v0, 0x3a800000, v250
	s_mov_b32 s12, 0x800000
	s_waitcnt vmcnt(4)
	v_mov_b32_e32 v166, v19
	v_mov_b32_e32 v167, v20
	v_mov_b32_e32 v168, v3
	v_mul_f32_e32 v3, 0x4b800000, v0
	v_cmp_gt_f32_e32 vcc, s12, v0
	v_mov_b32_e32 v19, v21
	v_mov_b32_e32 v169, v4
	v_cndmask_b32_e32 v0, v0, v3, vcc
	v_pk_add_f32 v[6:7], v[166:167], v[18:19]
	v_mov_b32_e32 v3, v5
	v_pk_add_f32 v[2:3], v[168:169], v[2:3]
	v_add_f32_e32 v4, v6, v7
	v_add_f32_e32 v2, v4, v2
	v_add_f32_e32 v2, v2, v3
	v_fmamk_f32 v2, v2, 0x3a800000, v250
	v_mul_f32_e32 v3, 0x4b800000, v2
	v_cmp_gt_f32_e64 s[40:41], s12, v2
	s_waitcnt vmcnt(2)
	v_mov_b32_e32 v170, v27
	v_mov_b32_e32 v171, v28
	v_cndmask_b32_e64 v2, v2, v3, s[40:41]
	v_mov_b32_e32 v27, v29
	v_mov_b32_e32 v172, v11
	v_mov_b32_e32 v173, v12
	v_rsq_f32_e32 v179, v2
	v_pk_add_f32 v[2:3], v[170:171], v[26:27]
	v_mov_b32_e32 v11, v13
	v_pk_add_f32 v[4:5], v[172:173], v[10:11]
	v_add_f32_e32 v2, v2, v3
	v_add_f32_e32 v2, v2, v4
	v_add_f32_e32 v2, v2, v5
	v_fmamk_f32 v2, v2, 0x3a800000, v250
	v_mul_f32_e32 v3, 0x4b800000, v2
	v_cmp_gt_f32_e64 s[42:43], s12, v2
	s_waitcnt vmcnt(0)
	v_mov_b32_e32 v174, v31
	v_mov_b32_e32 v175, v32
	v_cndmask_b32_e64 v2, v2, v3, s[42:43]
	v_mov_b32_e32 v31, v33
	v_mov_b32_e32 v180, v15
	v_mov_b32_e32 v181, v16
	v_rsq_f32_e32 v182, v2
	v_pk_add_f32 v[2:3], v[174:175], v[30:31]
	v_mov_b32_e32 v15, v17
	v_pk_add_f32 v[4:5], v[180:181], v[14:15]
	v_add_f32_e32 v2, v2, v3
	v_add_f32_e32 v2, v2, v4
	v_add_f32_e32 v2, v2, v5
	v_fmamk_f32 v2, v2, 0x3a800000, v250
	v_mul_f32_e32 v3, 0x4b800000, v2
	v_cmp_gt_f32_e64 s[44:45], s12, v2
	s_waitcnt vmcnt(6)
	v_add_u32_e32 v183, v178, v176
	s_waitcnt lgkmcnt(0)
	s_barrier
	v_cndmask_b32_e64 v2, v2, v3, s[44:45]
	v_rsq_f32_e32 v180, v2
	ds_read_b128 v[2:5], v183 offset:15360
	ds_read_b128 v[6:9], v183 offset:14336
	ds_read_b128 v[10:13], v183 offset:13312
	ds_read_b128 v[14:17], v183 offset:12288
	ds_read_b128 v[18:21], v183 offset:11264
	ds_read_b128 v[22:25], v183 offset:10240
	ds_read_b128 v[26:29], v183 offset:9216
	ds_read_b128 v[30:33], v183 offset:8192
	v_add3_u32 v178, s55, v177, v176
	ds_read_b128 v[162:165], v178 offset:3072
	ds_read_b128 v[166:169], v178 offset:2048
	ds_read_b128 v[170:173], v178 offset:1024
	ds_read_b128 v[174:177], v178
	v_rsq_f32_e32 v0, v0
	v_mul_f32_e32 v184, 0x45800000, v179
	v_mul_f32_e32 v185, 0x45800000, v182
	v_mul_f32_e32 v186, 0x45800000, v180
	v_mul_f32_e32 v181, 0x45800000, v0
	s_waitcnt lgkmcnt(0)
	v_mfma_f32_16x16x32_bf16 v[34:37], v[30:33], v[174:177], v[34:37]
	v_mfma_f32_16x16x32_bf16 v[38:41], v[30:33], v[170:173], v[38:41]
	v_mfma_f32_16x16x32_bf16 v[42:45], v[30:33], v[166:169], v[42:45]
	v_mfma_f32_16x16x32_bf16 v[30:33], v[30:33], v[162:165], v[46:49]
	v_mfma_f32_16x16x32_bf16 v[46:49], v[26:29], v[174:177], v[50:53]
	v_mfma_f32_16x16x32_bf16 v[50:53], v[26:29], v[170:173], v[54:57]
	v_mfma_f32_16x16x32_bf16 v[54:57], v[26:29], v[166:169], v[58:61]
	v_mfma_f32_16x16x32_bf16 v[58:61], v[26:29], v[162:165], v[62:65]
	v_mfma_f32_16x16x32_bf16 v[62:65], v[22:25], v[174:177], v[66:69]
	v_mfma_f32_16x16x32_bf16 v[66:69], v[22:25], v[170:173], v[70:73]
	v_mfma_f32_16x16x32_bf16 v[70:73], v[22:25], v[166:169], v[74:77]
	v_mfma_f32_16x16x32_bf16 v[74:77], v[22:25], v[162:165], v[78:81]
	v_mfma_f32_16x16x32_bf16 v[78:81], v[18:21], v[174:177], v[82:85]
	v_mfma_f32_16x16x32_bf16 v[82:85], v[18:21], v[170:173], v[86:89]
	v_mfma_f32_16x16x32_bf16 v[86:89], v[18:21], v[166:169], v[90:93]
	v_mfma_f32_16x16x32_bf16 v[18:21], v[18:21], v[162:165], v[94:97]
	v_mfma_f32_16x16x32_bf16 v[90:93], v[14:17], v[174:177], v[98:101]
	v_mfma_f32_16x16x32_bf16 v[94:97], v[14:17], v[170:173], v[102:105]
	v_mfma_f32_16x16x32_bf16 v[98:101], v[14:17], v[166:169], v[106:109]
	v_mfma_f32_16x16x32_bf16 v[14:17], v[14:17], v[162:165], v[110:113]
	v_mfma_f32_16x16x32_bf16 v[102:105], v[10:13], v[174:177], v[114:117]
	v_mfma_f32_16x16x32_bf16 v[106:109], v[10:13], v[170:173], v[118:121]
	v_mfma_f32_16x16x32_bf16 v[110:113], v[10:13], v[166:169], v[122:125]
	v_mfma_f32_16x16x32_bf16 v[10:13], v[10:13], v[162:165], v[126:129]
	v_mfma_f32_16x16x32_bf16 v[114:117], v[6:9], v[174:177], v[130:133]
	v_mfma_f32_16x16x32_bf16 v[118:121], v[6:9], v[170:173], v[134:137]
	v_mfma_f32_16x16x32_bf16 v[122:125], v[6:9], v[166:169], v[138:141]
	v_mfma_f32_16x16x32_bf16 v[6:9], v[6:9], v[162:165], v[142:145]
	v_mfma_f32_16x16x32_bf16 v[126:129], v[2:5], v[174:177], v[146:149]
	v_mfma_f32_16x16x32_bf16 v[130:133], v[2:5], v[170:173], v[150:153]
	v_mfma_f32_16x16x32_bf16 v[134:137], v[2:5], v[166:169], v[154:157]
	v_mfma_f32_16x16x32_bf16 v[2:5], v[2:5], v[162:165], v[158:161]
	s_waitcnt vmcnt(0)
	v_cndmask_b32_e32 v26, v0, v181, vcc
	v_cndmask_b32_e64 v24, v179, v184, s[40:41]
	v_cndmask_b32_e64 v22, v182, v185, s[42:43]
	v_cndmask_b32_e64 v0, v180, v186, s[44:45]
	s_waitcnt lgkmcnt(0)
	s_barrier
	ds_read_b128 v[138:141], v178 offset:24576
	ds_read_b128 v[142:145], v178 offset:25600
	ds_read_b128 v[146:149], v178 offset:26624
	ds_read_b128 v[150:153], v178 offset:27648
	ds_read_b128 v[154:157], v183 offset:32768
	ds_read_b128 v[158:161], v183 offset:33792
	ds_read_b128 v[162:165], v183 offset:34816
	ds_read_b128 v[166:169], v183 offset:35840
	ds_read_b128 v[170:173], v183 offset:36864
	ds_read_b128 v[174:177], v183 offset:37888
	ds_read_b128 v[178:181], v183 offset:38912
	ds_read_b128 v[182:185], v183 offset:39936
	s_waitcnt lgkmcnt(7)
	v_mfma_f32_16x16x32_bf16 v[34:37], v[154:157], v[138:141], v[34:37]
	v_mfma_f32_16x16x32_bf16 v[38:41], v[154:157], v[142:145], v[38:41]
	v_mfma_f32_16x16x32_bf16 v[42:45], v[154:157], v[146:149], v[42:45]
	v_mfma_f32_16x16x32_bf16 v[28:31], v[154:157], v[150:153], v[30:33]
	s_waitcnt lgkmcnt(6)
	v_mfma_f32_16x16x32_bf16 v[46:49], v[158:161], v[138:141], v[46:49]
	v_mfma_f32_16x16x32_bf16 v[50:53], v[158:161], v[142:145], v[50:53]
	v_mfma_f32_16x16x32_bf16 v[54:57], v[158:161], v[146:149], v[54:57]
	v_mfma_f32_16x16x32_bf16 v[58:61], v[158:161], v[150:153], v[58:61]
	s_waitcnt lgkmcnt(5)
	v_mfma_f32_16x16x32_bf16 v[62:65], v[162:165], v[138:141], v[62:65]
	v_mfma_f32_16x16x32_bf16 v[66:69], v[162:165], v[142:145], v[66:69]
	v_mfma_f32_16x16x32_bf16 v[70:73], v[162:165], v[146:149], v[70:73]
	v_mfma_f32_16x16x32_bf16 v[74:77], v[162:165], v[150:153], v[74:77]
	s_waitcnt lgkmcnt(4)
	v_mfma_f32_16x16x32_bf16 v[78:81], v[166:169], v[138:141], v[78:81]
	v_mfma_f32_16x16x32_bf16 v[82:85], v[166:169], v[142:145], v[82:85]
	v_mfma_f32_16x16x32_bf16 v[86:89], v[166:169], v[146:149], v[86:89]
	v_mfma_f32_16x16x32_bf16 v[154:157], v[166:169], v[150:153], v[18:21]
	s_waitcnt lgkmcnt(3)
	v_mfma_f32_16x16x32_bf16 v[90:93], v[170:173], v[138:141], v[90:93]
	v_mfma_f32_16x16x32_bf16 v[94:97], v[170:173], v[142:145], v[94:97]
	v_mfma_f32_16x16x32_bf16 v[98:101], v[170:173], v[146:149], v[98:101]
	v_mfma_f32_16x16x32_bf16 v[158:161], v[170:173], v[150:153], v[14:17]
	s_waitcnt lgkmcnt(2)
	v_mfma_f32_16x16x32_bf16 v[102:105], v[174:177], v[138:141], v[102:105]
	v_mfma_f32_16x16x32_bf16 v[106:109], v[174:177], v[142:145], v[106:109]
	v_mfma_f32_16x16x32_bf16 v[110:113], v[174:177], v[146:149], v[110:113]
	v_mfma_f32_16x16x32_bf16 v[162:165], v[174:177], v[150:153], v[10:13]
	s_waitcnt lgkmcnt(1)
	v_mfma_f32_16x16x32_bf16 v[114:117], v[178:181], v[138:141], v[114:117]
	v_mfma_f32_16x16x32_bf16 v[118:121], v[178:181], v[142:145], v[118:121]
	v_mfma_f32_16x16x32_bf16 v[122:125], v[178:181], v[146:149], v[122:125]
	v_mfma_f32_16x16x32_bf16 v[18:21], v[178:181], v[150:153], v[6:9]
	s_waitcnt lgkmcnt(0)
	v_mfma_f32_16x16x32_bf16 v[14:17], v[182:185], v[138:141], v[126:129]
	v_mfma_f32_16x16x32_bf16 v[10:13], v[182:185], v[142:145], v[130:133]
	v_mfma_f32_16x16x32_bf16 v[6:9], v[182:185], v[146:149], v[134:137]
	v_mfma_f32_16x16x32_bf16 v[2:5], v[182:185], v[150:153], v[2:5]
	v_mov_b32_e32 v23, v224
	s_movk_i32 s12, 0x210
	v_lshrrev_b32_e32 v32, 1, v23
	v_and_b32_e32 v27, 0x7fffff80, v23
	v_and_b32_e32 v32, 24, v32
	v_and_b32_e32 v25, 0x4f, v23
	v_lshl_or_b32 v27, v27, 1, v32
	v_pk_mul_f32 v[32:33], v[26:27], v[34:35] op_sel_hi:[0,1]
	v_pk_mul_f32 v[34:35], v[26:27], v[36:37] op_sel_hi:[0,1]
	v_mad_u32_u24 v25, v25, s12, v27
	v_cvt_pk_bf16_f32 v32, v32, v33
	v_cvt_pk_bf16_f32 v33, v34, v35
	v_pk_mul_f32 v[34:35], v[24:25], v[38:39] op_sel_hi:[0,1]
	v_pk_mul_f32 v[36:37], v[24:25], v[40:41] op_sel_hi:[0,1]
	v_cvt_pk_bf16_f32 v34, v34, v35
	v_cvt_pk_bf16_f32 v35, v36, v37
	v_pk_mul_f32 v[36:37], v[22:23], v[42:43] op_sel_hi:[0,1]
	v_pk_mul_f32 v[38:39], v[22:23], v[44:45] op_sel_hi:[0,1]
	v_pk_mul_f32 v[28:29], v[0:1], v[28:29] op_sel_hi:[0,1]
	v_pk_mul_f32 v[30:31], v[0:1], v[30:31] op_sel_hi:[0,1]
	v_cvt_pk_bf16_f32 v36, v36, v37
	v_cvt_pk_bf16_f32 v37, v38, v39
	v_cvt_pk_bf16_f32 v28, v28, v29
	v_cvt_pk_bf16_f32 v29, v30, v31
	v_pk_mul_f32 v[30:31], v[26:27], v[46:47] op_sel_hi:[0,1]
	v_pk_mul_f32 v[38:39], v[26:27], v[48:49] op_sel_hi:[0,1]
	v_cvt_pk_bf16_f32 v30, v30, v31
	v_cvt_pk_bf16_f32 v31, v38, v39
	s_barrier
	ds_write2_b64 v25, v[32:33], v[30:31] offset1:4
	v_pk_mul_f32 v[30:31], v[24:25], v[50:51] op_sel_hi:[0,1]
	v_pk_mul_f32 v[32:33], v[24:25], v[52:53] op_sel_hi:[0,1]
	v_cvt_pk_bf16_f32 v30, v30, v31
	v_cvt_pk_bf16_f32 v31, v32, v33
	v_add_u32_e32 v27, 0x2000, v25
	ds_write2_b64 v27, v[34:35], v[30:31] offset0:32 offset1:36
	v_pk_mul_f32 v[30:31], v[22:23], v[54:55] op_sel_hi:[0,1]
	v_pk_mul_f32 v[32:33], v[22:23], v[56:57] op_sel_hi:[0,1]
	v_cvt_pk_bf16_f32 v30, v30, v31
	v_cvt_pk_bf16_f32 v31, v32, v33
	v_add_u32_e32 v40, 0x4000, v25
	ds_write2_b64 v40, v[36:37], v[30:31] offset0:64 offset1:68
	v_pk_mul_f32 v[30:31], v[0:1], v[58:59] op_sel_hi:[0,1]
	v_pk_mul_f32 v[32:33], v[0:1], v[60:61] op_sel_hi:[0,1]
	v_cvt_pk_bf16_f32 v30, v30, v31
	v_cvt_pk_bf16_f32 v31, v32, v33
	v_add_u32_e32 v41, 0x6000, v25
	ds_write2_b64 v41, v[28:29], v[30:31] offset0:96 offset1:100
	v_pk_mul_f32 v[28:29], v[26:27], v[62:63] op_sel_hi:[0,1]
	v_pk_mul_f32 v[30:31], v[26:27], v[64:65] op_sel_hi:[0,1]
	v_cvt_pk_bf16_f32 v28, v28, v29
	v_cvt_pk_bf16_f32 v29, v30, v31
	v_pk_mul_f32 v[30:31], v[24:25], v[66:67] op_sel_hi:[0,1]
	v_pk_mul_f32 v[32:33], v[24:25], v[68:69] op_sel_hi:[0,1]
	v_cvt_pk_bf16_f32 v30, v30, v31
	v_cvt_pk_bf16_f32 v31, v32, v33
	v_pk_mul_f32 v[32:33], v[22:23], v[70:71] op_sel_hi:[0,1]
	v_pk_mul_f32 v[34:35], v[22:23], v[72:73] op_sel_hi:[0,1]
	v_cvt_pk_bf16_f32 v32, v32, v33
	v_cvt_pk_bf16_f32 v33, v34, v35
	v_pk_mul_f32 v[34:35], v[0:1], v[74:75] op_sel_hi:[0,1]
	v_pk_mul_f32 v[36:37], v[0:1], v[76:77] op_sel_hi:[0,1]
	v_cvt_pk_bf16_f32 v34, v34, v35
	v_cvt_pk_bf16_f32 v35, v36, v37
	v_pk_mul_f32 v[36:37], v[26:27], v[78:79] op_sel_hi:[0,1]
	v_pk_mul_f32 v[38:39], v[26:27], v[80:81] op_sel_hi:[0,1]
	v_cvt_pk_bf16_f32 v36, v36, v37
	v_cvt_pk_bf16_f32 v37, v38, v39
	ds_write2_b64 v25, v[28:29], v[36:37] offset0:8 offset1:12
	v_pk_mul_f32 v[28:29], v[24:25], v[82:83] op_sel_hi:[0,1]
	v_pk_mul_f32 v[36:37], v[24:25], v[84:85] op_sel_hi:[0,1]
	v_cvt_pk_bf16_f32 v28, v28, v29
	v_cvt_pk_bf16_f32 v29, v36, v37
	ds_write2_b64 v27, v[30:31], v[28:29] offset0:40 offset1:44
	v_pk_mul_f32 v[28:29], v[22:23], v[86:87] op_sel_hi:[0,1]
	v_pk_mul_f32 v[30:31], v[22:23], v[88:89] op_sel_hi:[0,1]
	v_cvt_pk_bf16_f32 v28, v28, v29
	v_cvt_pk_bf16_f32 v29, v30, v31
	ds_write2_b64 v40, v[32:33], v[28:29] offset0:72 offset1:76
	v_pk_mul_f32 v[28:29], v[0:1], v[154:155] op_sel_hi:[0,1]
	v_pk_mul_f32 v[30:31], v[0:1], v[156:157] op_sel_hi:[0,1]
	v_cvt_pk_bf16_f32 v28, v28, v29
	v_cvt_pk_bf16_f32 v29, v30, v31
	ds_write2_b64 v41, v[34:35], v[28:29] offset0:104 offset1:108
	v_pk_mul_f32 v[28:29], v[26:27], v[90:91] op_sel_hi:[0,1]
	v_pk_mul_f32 v[30:31], v[26:27], v[92:93] op_sel_hi:[0,1]
	v_cvt_pk_bf16_f32 v28, v28, v29
	v_cvt_pk_bf16_f32 v29, v30, v31
	v_pk_mul_f32 v[30:31], v[24:25], v[94:95] op_sel_hi:[0,1]
	v_pk_mul_f32 v[32:33], v[24:25], v[96:97] op_sel_hi:[0,1]
	v_cvt_pk_bf16_f32 v30, v30, v31
	v_cvt_pk_bf16_f32 v31, v32, v33
	v_pk_mul_f32 v[32:33], v[22:23], v[98:99] op_sel_hi:[0,1]
	v_pk_mul_f32 v[34:35], v[22:23], v[100:101] op_sel_hi:[0,1]
	v_cvt_pk_bf16_f32 v32, v32, v33
	v_cvt_pk_bf16_f32 v33, v34, v35
	v_pk_mul_f32 v[34:35], v[0:1], v[158:159] op_sel_hi:[0,1]
	v_pk_mul_f32 v[36:37], v[0:1], v[160:161] op_sel_hi:[0,1]
	v_cvt_pk_bf16_f32 v34, v34, v35
	v_cvt_pk_bf16_f32 v35, v36, v37
	v_pk_mul_f32 v[36:37], v[26:27], v[102:103] op_sel_hi:[0,1]
	v_pk_mul_f32 v[38:39], v[26:27], v[104:105] op_sel_hi:[0,1]
	v_cvt_pk_bf16_f32 v36, v36, v37
	v_cvt_pk_bf16_f32 v37, v38, v39
	ds_write2_b64 v25, v[28:29], v[36:37] offset0:16 offset1:20
	v_pk_mul_f32 v[28:29], v[24:25], v[106:107] op_sel_hi:[0,1]
	v_pk_mul_f32 v[36:37], v[24:25], v[108:109] op_sel_hi:[0,1]
	v_cvt_pk_bf16_f32 v28, v28, v29
	v_cvt_pk_bf16_f32 v29, v36, v37
	ds_write2_b64 v27, v[30:31], v[28:29] offset0:48 offset1:52
	v_pk_mul_f32 v[28:29], v[22:23], v[110:111] op_sel_hi:[0,1]
	v_pk_mul_f32 v[30:31], v[22:23], v[112:113] op_sel_hi:[0,1]
	v_cvt_pk_bf16_f32 v28, v28, v29
	v_cvt_pk_bf16_f32 v29, v30, v31
	ds_write2_b64 v40, v[32:33], v[28:29] offset0:80 offset1:84
	v_pk_mul_f32 v[28:29], v[0:1], v[162:163] op_sel_hi:[0,1]
	v_pk_mul_f32 v[30:31], v[0:1], v[164:165] op_sel_hi:[0,1]
	v_cvt_pk_bf16_f32 v28, v28, v29
	v_cvt_pk_bf16_f32 v29, v30, v31
	ds_write2_b64 v41, v[34:35], v[28:29] offset0:112 offset1:116
	v_pk_mul_f32 v[28:29], v[26:27], v[114:115] op_sel_hi:[0,1]
	v_pk_mul_f32 v[30:31], v[26:27], v[116:117] op_sel_hi:[0,1]
	v_pk_mul_f32 v[18:19], v[0:1], v[18:19] op_sel_hi:[0,1]
	v_pk_mul_f32 v[20:21], v[0:1], v[20:21] op_sel_hi:[0,1]
	v_pk_mul_f32 v[2:3], v[0:1], v[2:3] op_sel_hi:[0,1]
	v_pk_mul_f32 v[4:5], v[0:1], v[4:5] op_sel_hi:[0,1]
	v_lshlrev_b32_e32 v0, 3, v23
	v_cvt_pk_bf16_f32 v28, v28, v29
	v_cvt_pk_bf16_f32 v29, v30, v31
	v_pk_mul_f32 v[30:31], v[24:25], v[118:119] op_sel_hi:[0,1]
	v_pk_mul_f32 v[32:33], v[24:25], v[120:121] op_sel_hi:[0,1]
	v_cvt_pk_bf16_f32 v18, v18, v19
	v_cvt_pk_bf16_f32 v19, v20, v21
	v_cvt_pk_bf16_f32 v2, v2, v3
	v_cvt_pk_bf16_f32 v3, v4, v5
	v_and_b32_e32 v0, 0xf8, v0
	v_cvt_pk_bf16_f32 v30, v30, v31
	v_cvt_pk_bf16_f32 v31, v32, v33
	v_pk_mul_f32 v[32:33], v[22:23], v[122:123] op_sel_hi:[0,1]
	v_pk_mul_f32 v[34:35], v[22:23], v[124:125] op_sel_hi:[0,1]
	v_pk_mul_f32 v[14:15], v[26:27], v[14:15] op_sel_hi:[0,1]
	v_pk_mul_f32 v[16:17], v[26:27], v[16:17] op_sel_hi:[0,1]
	v_pk_mul_f32 v[10:11], v[24:25], v[10:11] op_sel_hi:[0,1]
	v_pk_mul_f32 v[12:13], v[24:25], v[12:13] op_sel_hi:[0,1]
	v_pk_mul_f32 v[6:7], v[22:23], v[6:7] op_sel_hi:[0,1]
	v_pk_mul_f32 v[8:9], v[22:23], v[8:9] op_sel_hi:[0,1]
	ds_write2_b64 v41, v[18:19], v[2:3] offset0:120 offset1:124
	v_or_b32_e32 v2, s54, v0
	s_movk_i32 s12, 0x400
	v_cvt_pk_bf16_f32 v32, v32, v33
	v_cvt_pk_bf16_f32 v33, v34, v35
	v_cvt_pk_bf16_f32 v14, v14, v15
	v_cvt_pk_bf16_f32 v15, v16, v17
	v_cvt_pk_bf16_f32 v10, v10, v11
	v_cvt_pk_bf16_f32 v11, v12, v13
	v_cvt_pk_bf16_f32 v6, v6, v7
	v_cvt_pk_bf16_f32 v7, v8, v9
	v_cmp_gt_i32_e32 vcc, s12, v2
	ds_write2_b64 v25, v[28:29], v[14:15] offset0:24 offset1:28
	ds_write2_b64 v27, v[30:31], v[10:11] offset0:56 offset1:60
	ds_write2_b64 v40, v[32:33], v[6:7] offset0:88 offset1:92
	s_waitcnt lgkmcnt(0)
	s_barrier
	s_and_saveexec_b64 s[12:13], vcc
	s_cbranch_execz .LBB0_28
	v_ashrrev_i32_e32 v8, 5, v23
	v_lshlrev_b32_e32 v0, 1, v0
	s_movk_i32 s40, 0x210
	v_mad_u64_u32 v[6:7], s[40:41], v8, s40, v[0:1]
	v_add_u32_e32 v8, s57, v8
	ds_read_b128 v[2:5], v6
	v_ashrrev_i32_e32 v9, 31, v8
	s_ashr_i32 s55, s54, 31
	v_lshlrev_b64 v[10:11], 11, v[8:9]
	v_lshl_add_u64 v[10:11], s[4:5], 0, v[10:11]
	s_lshl_b64 s[40:41], s[54:55], 1
	v_lshl_add_u64 v[10:11], v[10:11], 0, s[40:41]
	v_lshl_add_u64 v[10:11], v[10:11], 0, v[0:1]
	s_waitcnt lgkmcnt(0)
	global_store_dwordx4 v[10:11], v[2:5], off
	v_add_u32_e32 v10, 8, v8
	ds_read_b128 v[2:5], v6 offset:4224
	v_ashrrev_i32_e32 v11, 31, v10
	v_lshlrev_b64 v[10:11], 11, v[10:11]
	v_lshl_add_u64 v[10:11], s[4:5], 0, v[10:11]
	v_lshl_add_u64 v[10:11], v[10:11], 0, s[40:41]
	v_lshl_add_u64 v[10:11], v[10:11], 0, v[0:1]
	s_waitcnt lgkmcnt(0)
	global_store_dwordx4 v[10:11], v[2:5], off
	v_add_u32_e32 v10, 16, v8
	ds_read_b128 v[2:5], v6 offset:8448
	v_ashrrev_i32_e32 v11, 31, v10
	v_lshlrev_b64 v[10:11], 11, v[10:11]
	v_lshl_add_u64 v[10:11], s[4:5], 0, v[10:11]
	v_lshl_add_u64 v[10:11], v[10:11], 0, s[40:41]
	v_lshl_add_u64 v[10:11], v[10:11], 0, v[0:1]
	s_waitcnt lgkmcnt(0)
	global_store_dwordx4 v[10:11], v[2:5], off
	v_add_u32_e32 v10, 24, v8
	ds_read_b128 v[2:5], v6 offset:12672
	v_ashrrev_i32_e32 v11, 31, v10
	v_lshlrev_b64 v[10:11], 11, v[10:11]
	v_lshl_add_u64 v[10:11], s[4:5], 0, v[10:11]
	v_lshl_add_u64 v[10:11], v[10:11], 0, s[40:41]
	v_lshl_add_u64 v[10:11], v[10:11], 0, v[0:1]
	s_waitcnt lgkmcnt(0)
	global_store_dwordx4 v[10:11], v[2:5], off
	v_add_u32_e32 v10, 32, v8
	ds_read_b128 v[2:5], v6 offset:16896
	v_ashrrev_i32_e32 v11, 31, v10
	v_lshlrev_b64 v[10:11], 11, v[10:11]
	v_lshl_add_u64 v[10:11], s[4:5], 0, v[10:11]
	v_lshl_add_u64 v[10:11], v[10:11], 0, s[40:41]
	v_lshl_add_u64 v[10:11], v[10:11], 0, v[0:1]
	s_waitcnt lgkmcnt(0)
	global_store_dwordx4 v[10:11], v[2:5], off
	v_add_u32_e32 v10, 40, v8
	ds_read_b128 v[2:5], v6 offset:21120
	v_ashrrev_i32_e32 v11, 31, v10
	v_lshlrev_b64 v[10:11], 11, v[10:11]
	v_lshl_add_u64 v[10:11], s[4:5], 0, v[10:11]
	v_lshl_add_u64 v[10:11], v[10:11], 0, s[40:41]
	v_lshl_add_u64 v[10:11], v[10:11], 0, v[0:1]
	s_waitcnt lgkmcnt(0)
	global_store_dwordx4 v[10:11], v[2:5], off
	v_add_u32_e32 v10, 48, v8
	ds_read_b128 v[2:5], v6 offset:25344
	v_ashrrev_i32_e32 v11, 31, v10
	v_lshlrev_b64 v[10:11], 11, v[10:11]
	v_lshl_add_u64 v[10:11], s[4:5], 0, v[10:11]
	v_lshl_add_u64 v[10:11], v[10:11], 0, s[40:41]
	v_lshl_add_u64 v[10:11], v[10:11], 0, v[0:1]
	s_waitcnt lgkmcnt(0)
	global_store_dwordx4 v[10:11], v[2:5], off
	v_add_u32_e32 v10, 56, v8
	ds_read_b128 v[2:5], v6 offset:29568
	v_ashrrev_i32_e32 v11, 31, v10
	v_lshlrev_b64 v[10:11], 11, v[10:11]
	v_lshl_add_u64 v[10:11], s[4:5], 0, v[10:11]
	v_lshl_add_u64 v[10:11], v[10:11], 0, s[40:41]
	v_lshl_add_u64 v[10:11], v[10:11], 0, v[0:1]
	s_waitcnt lgkmcnt(0)
	global_store_dwordx4 v[10:11], v[2:5], off
	v_add_u32_e32 v10, 64, v8
	ds_read_b128 v[2:5], v6 offset:33792
	v_ashrrev_i32_e32 v11, 31, v10
	v_lshlrev_b64 v[10:11], 11, v[10:11]
	v_lshl_add_u64 v[10:11], s[4:5], 0, v[10:11]
	v_lshl_add_u64 v[10:11], v[10:11], 0, s[40:41]
	v_lshl_add_u64 v[10:11], v[10:11], 0, v[0:1]
	s_waitcnt lgkmcnt(0)
	global_store_dwordx4 v[10:11], v[2:5], off
	v_add_u32_e32 v10, 0x48, v8
	ds_read_b128 v[2:5], v6 offset:38016
	v_ashrrev_i32_e32 v11, 31, v10
	v_lshlrev_b64 v[10:11], 11, v[10:11]
	v_lshl_add_u64 v[10:11], s[4:5], 0, v[10:11]
	v_lshl_add_u64 v[10:11], v[10:11], 0, s[40:41]
	v_lshl_add_u64 v[10:11], v[10:11], 0, v[0:1]
	s_waitcnt lgkmcnt(0)
	global_store_dwordx4 v[10:11], v[2:5], off
	v_add_u32_e32 v10, 0x50, v8
	ds_read_b128 v[2:5], v6 offset:42240
	v_ashrrev_i32_e32 v11, 31, v10
	v_lshlrev_b64 v[10:11], 11, v[10:11]
	v_lshl_add_u64 v[10:11], s[4:5], 0, v[10:11]
	v_lshl_add_u64 v[10:11], v[10:11], 0, s[40:41]
	v_lshl_add_u64 v[10:11], v[10:11], 0, v[0:1]
	s_waitcnt lgkmcnt(0)
	global_store_dwordx4 v[10:11], v[2:5], off
	v_add_u32_e32 v10, 0x58, v8
	ds_read_b128 v[2:5], v6 offset:46464
	v_ashrrev_i32_e32 v11, 31, v10
	v_lshlrev_b64 v[10:11], 11, v[10:11]
	v_lshl_add_u64 v[10:11], s[4:5], 0, v[10:11]
	v_lshl_add_u64 v[10:11], v[10:11], 0, s[40:41]
	v_lshl_add_u64 v[10:11], v[10:11], 0, v[0:1]
	s_waitcnt lgkmcnt(0)
	global_store_dwordx4 v[10:11], v[2:5], off
	v_add_u32_e32 v10, 0x60, v8
	ds_read_b128 v[2:5], v6 offset:50688
	v_ashrrev_i32_e32 v11, 31, v10
	v_lshlrev_b64 v[10:11], 11, v[10:11]
	v_lshl_add_u64 v[10:11], s[4:5], 0, v[10:11]
	v_lshl_add_u64 v[10:11], v[10:11], 0, s[40:41]
	v_lshl_add_u64 v[10:11], v[10:11], 0, v[0:1]
	s_waitcnt lgkmcnt(0)
	global_store_dwordx4 v[10:11], v[2:5], off
	v_add_u32_e32 v10, 0x68, v8
	ds_read_b128 v[2:5], v6 offset:54912
	v_ashrrev_i32_e32 v11, 31, v10
	v_lshlrev_b64 v[10:11], 11, v[10:11]
	v_lshl_add_u64 v[10:11], s[4:5], 0, v[10:11]
	v_lshl_add_u64 v[10:11], v[10:11], 0, s[40:41]
	v_lshl_add_u64 v[10:11], v[10:11], 0, v[0:1]
	s_waitcnt lgkmcnt(0)
	global_store_dwordx4 v[10:11], v[2:5], off
	v_add_u32_e32 v10, 0x70, v8
	ds_read_b128 v[2:5], v6 offset:59136
	v_ashrrev_i32_e32 v11, 31, v10
	v_lshlrev_b64 v[10:11], 11, v[10:11]
	v_lshl_add_u64 v[10:11], s[4:5], 0, v[10:11]
	v_lshl_add_u64 v[10:11], v[10:11], 0, s[40:41]
	v_lshl_add_u64 v[10:11], v[10:11], 0, v[0:1]
	s_waitcnt lgkmcnt(0)
	global_store_dwordx4 v[10:11], v[2:5], off
	ds_read_b128 v[2:5], v6 offset:63360
	v_add_u32_e32 v6, 0x78, v8
	v_ashrrev_i32_e32 v7, 31, v6
	v_lshlrev_b64 v[6:7], 11, v[6:7]
	v_lshl_add_u64 v[6:7], s[4:5], 0, v[6:7]
	v_lshl_add_u64 v[6:7], v[6:7], 0, s[40:41]
	v_lshl_add_u64 v[6:7], v[6:7], 0, v[0:1]
	s_waitcnt lgkmcnt(0)
	global_store_dwordx4 v[6:7], v[2:5], off
	s_branch .LBB0_28

.LBB0_70:
	s_ashr_i32 s1, s0, 31
	s_lshr_b32 s1, s1, 28
	s_add_i32 s1, s0, s1
	s_and_b32 s12, s1, 0x1fffff0
	s_sub_i32 s12, s0, s12
	s_add_i32 s12, s12, s69
	s_lshl_b32 s1, s1, 4
	s_lshl_b32 s71, s12, 7
	s_and_b32 s82, s1, 0xffffff00
	s_cmpk_gt_i32 s0, 0x7f
	s_cbranch_scc0 .LBB0_74
	s_waitcnt vmcnt(6)
	v_mov_b32_e32 v58, v224
	s_add_i32 s0, s82, 0xfffff800
	v_readfirstlane_b32 s12, v58
	v_bfe_u32 v59, v58, 4, 2
	s_and_b32 s15, s12, 0xffffffc0
	s_waitcnt vmcnt(4)
	v_bfe_u32 v42, v58, 2, 4
	v_sub_u32_e32 v60, 0, v59
	s_add_i32 s15, s15, s0
	v_xor_b32_e32 v0, v58, v60
	v_or_b32_e32 v6, s15, v42
	v_lshlrev_b32_e32 v0, 4, v0
	v_min_i32_e32 v4, 0x3ff, v6
	v_and_b32_e32 v0, 48, v0
	v_ashrrev_i32_e32 v5, 31, v4
	v_lshl_add_u64 v[2:3], s[52:53], 0, v[0:1]
	v_lshlrev_b64 v[4:5], 11, v[4:5]
	v_lshl_add_u64 v[34:35], v[2:3], 0, v[4:5]
	v_or_b32_e32 v4, 16, v6
	v_min_i32_e32 v4, 0x3ff, v4
	v_ashrrev_i32_e32 v5, 31, v4
	v_lshlrev_b64 v[4:5], 11, v[4:5]
	v_lshl_add_u64 v[36:37], v[2:3], 0, v[4:5]
	v_or_b32_e32 v4, 32, v6
	v_min_i32_e32 v4, 0x3ff, v4
	v_ashrrev_i32_e32 v5, 31, v4
	v_lshlrev_b64 v[4:5], 11, v[4:5]
	s_ashr_i32 s13, s12, 6
	v_lshl_add_u64 v[38:39], v[2:3], 0, v[4:5]
	v_or_b32_e32 v4, 48, v6
	s_and_b32 s14, s13, 1
	v_min_i32_e32 v4, 0x3ff, v4
	v_ashrrev_i32_e32 v5, 31, v4
	s_lshl_b32 s15, s14, 6
	v_lshlrev_b64 v[4:5], 11, v[4:5]
	v_and_b32_e32 v61, 15, v58
	s_or_b32 s15, s15, s71
	v_lshl_add_u64 v[40:41], v[2:3], 0, v[4:5]
	v_or_b32_e32 v4, s15, v61
	v_lshlrev_b32_e32 v2, 5, v4
	s_waitcnt vmcnt(0)
	s_barrier
	global_load_dwordx4 v[14:17], v2, s[48:49] offset:16
	global_load_dwordx4 v[30:33], v2, s[48:49]
	v_or_b32_e32 v2, 16, v4
	v_mov_b32_e32 v3, v1
	v_lshlrev_b64 v[2:3], 5, v[2:3]
	v_lshl_add_u64 v[2:3], s[48:49], 0, v[2:3]
	global_load_dwordx4 v[10:13], v[2:3], off offset:16
	global_load_dwordx4 v[26:29], v[2:3], off
	v_or_b32_e32 v2, 32, v4
	v_mov_b32_e32 v3, v1
	v_lshlrev_b64 v[2:3], 5, v[2:3]
	v_lshl_add_u64 v[2:3], s[48:49], 0, v[2:3]
	global_load_dwordx4 v[6:9], v[2:3], off offset:16
	global_load_dwordx4 v[22:25], v[2:3], off
	v_or_b32_e32 v2, 48, v4
	v_mov_b32_e32 v3, v1
	v_lshlrev_b64 v[2:3], 5, v[2:3]
	v_lshl_add_u64 v[18:19], s[48:49], 0, v[2:3]
	global_load_dwordx4 v[2:5], v[18:19], off offset:16
	s_nop 0
	global_load_dwordx4 v[18:21], v[18:19], off
	s_lshl_b32 s15, s13, 1
	s_waitcnt vmcnt(8)
	v_or_b32_e32 v46, s71, v42
	v_lshl_add_u32 v44, s13, 5, v46
	s_lshl_b32 s40, s15, 10
	s_or_b32 s15, s15, 1
	v_ashrrev_i32_e32 v45, 31, v44
	v_lshl_add_u32 v46, s15, 4, v46
	v_lshl_add_u64 v[42:43], s[4:5], 0, v[0:1]
	v_lshlrev_b64 v[162:163], 10, v[44:45]
	v_lshlrev_b64 v[44:45], 11, v[44:45]
	v_ashrrev_i32_e32 v47, 31, v46
	v_lshl_add_u64 v[44:45], v[42:43], 0, v[44:45]
	v_lshlrev_b64 v[164:165], 10, v[46:47]
	v_lshlrev_b64 v[46:47], 11, v[46:47]
	s_mov_b32 s43, m0
	s_mov_b32 m0, s40
	s_nop 0
	global_load_lds_dwordx4 v[44:45], off
	s_mov_b32 m0, s43
	v_lshl_add_u64 v[42:43], v[42:43], 0, v[46:47]
	s_lshl_b32 s41, s13, 12
	s_add_i32 s42, s40, 0x6000
	s_lshl_b32 s15, s15, 10
	s_mov_b32 s40, m0
	s_mov_b32 m0, s15
	s_nop 0
	global_load_lds_dwordx4 v[42:43], off
	s_mov_b32 m0, s40
	s_add_i32 s40, s41, 0x2000
	s_mov_b32 s43, m0
	s_mov_b32 m0, s40
	s_nop 0
	global_load_lds_dwordx4 v[34:35], off
	s_mov_b32 m0, s43
	s_add_i32 s43, s41, 0x2400
	s_mov_b32 s44, m0
	s_mov_b32 m0, s43
	s_nop 0
	global_load_lds_dwordx4 v[36:37], off
	s_mov_b32 m0, s44
	s_add_i32 s43, s41, 0x2800
	s_mov_b32 s44, m0
	s_mov_b32 m0, s43
	s_nop 0
	global_load_lds_dwordx4 v[38:39], off
	s_mov_b32 m0, s44
	s_add_i32 s43, s41, 0x2c00
	s_mov_b32 s44, m0
	s_mov_b32 m0, s43
	s_nop 0
	global_load_lds_dwordx4 v[40:41], off
	s_mov_b32 m0, s44
	v_lshl_add_u64 v[46:47], v[44:45], 0, 64
	s_mov_b32 s43, m0
	s_mov_b32 m0, s42
	s_nop 0
	global_load_lds_dwordx4 v[46:47], off
	s_mov_b32 m0, s43
	v_lshl_add_u64 v[48:49], v[42:43], 0, 64
	s_add_i32 s42, s15, 0x6000
	s_mov_b32 s43, m0
	s_mov_b32 m0, s42
	s_nop 0
	global_load_lds_dwordx4 v[48:49], off
	s_mov_b32 m0, s43
	v_lshrrev_b32_e32 v0, 2, v58
	s_waitcnt vmcnt(25)
	v_lshl_add_u64 v[50:51], v[34:35], 0, 64
	s_add_i32 s42, s41, 0x8000
	s_mov_b32 s43, m0
	s_mov_b32 m0, s42
	s_nop 0
	global_load_lds_dwordx4 v[50:51], off
	s_mov_b32 m0, s43
	v_sub_u32_e32 v0, 0, v0
	v_lshl_add_u64 v[52:53], v[36:37], 0, 64
	s_add_i32 s42, s41, 0x8400
	s_mov_b32 s43, m0
	s_mov_b32 m0, s42
	s_nop 0
	global_load_lds_dwordx4 v[52:53], off
	s_mov_b32 m0, s43
	v_bitop3_b32 v0, v59, v0, 3 bitop3:0x78
	s_and_b32 s12, s12, 0x3ffff80
	v_lshl_add_u64 v[54:55], v[38:39], 0, 64
	s_add_i32 s42, s41, 0x8800
	s_mov_b32 s43, m0
	s_mov_b32 m0, s42
	s_nop 0
	global_load_lds_dwordx4 v[54:55], off
	s_mov_b32 m0, s43
	v_lshlrev_b32_e32 v176, 4, v0
	v_or_b32_e32 v0, s12, v61
	v_lshl_add_u64 v[56:57], v[40:41], 0, 64
	s_add_i32 s41, s41, 0x8c00
	s_mov_b32 s42, m0
	s_mov_b32 m0, s41
	s_nop 0
	global_load_lds_dwordx4 v[56:57], off
	s_mov_b32 m0, s42
	v_lshlrev_b32_e32 v178, 6, v0
	v_bitop3_b32 v0, v58, 3, v60 bitop3:0x48
	v_lshl_add_u64 v[172:173], v[34:35], 0, s[6:7]
	v_lshlrev_b32_e32 v0, 4, v0
	v_mov_b32_e32 v34, 0
	s_mov_b32 s1, 0
	s_lshl_b32 s14, s14, 12
	v_lshlrev_b32_e32 v177, 6, v61
	s_lshl_b32 s41, s13, 11
	v_lshl_add_u64 v[166:167], v[40:41], 0, s[6:7]
	v_lshl_add_u64 v[168:169], v[38:39], 0, s[6:7]
	v_lshl_add_u64 v[170:171], v[36:37], 0, s[6:7]
	v_lshl_add_u64 v[174:175], s[74:75], 0, v[0:1]
	s_mov_b64 s[12:13], 0
	v_mov_b32_e32 v35, v34
	v_mov_b32_e32 v36, v34
	v_mov_b32_e32 v37, v34
	v_mov_b32_e32 v38, v34
	v_mov_b32_e32 v39, v34
	v_mov_b32_e32 v40, v34
	v_mov_b32_e32 v41, v34
	v_mov_b32_e32 v42, v34
	v_mov_b32_e32 v43, v34
	v_mov_b32_e32 v44, v34
	v_mov_b32_e32 v45, v34
	v_mov_b32_e32 v46, v34
	v_mov_b32_e32 v47, v34
	v_mov_b32_e32 v48, v34
	v_mov_b32_e32 v49, v34
	v_mov_b32_e32 v50, v34
	v_mov_b32_e32 v51, v34
	v_mov_b32_e32 v52, v34
	v_mov_b32_e32 v53, v34
	v_mov_b32_e32 v54, v34
	v_mov_b32_e32 v55, v34
	v_mov_b32_e32 v56, v34
	v_mov_b32_e32 v57, v34
	v_mov_b32_e32 v58, v34
	v_mov_b32_e32 v59, v34
	v_mov_b32_e32 v60, v34
	v_mov_b32_e32 v61, v34
	s_waitcnt vmcnt(24)
	v_mov_b32_e32 v62, v34
	v_mov_b32_e32 v63, v34
	v_mov_b32_e32 v64, v34
	v_mov_b32_e32 v65, v34
	v_mov_b32_e32 v66, v34
	v_mov_b32_e32 v67, v34
	v_mov_b32_e32 v68, v34
	v_mov_b32_e32 v69, v34
	v_mov_b32_e32 v70, v34
	v_mov_b32_e32 v71, v34
	v_mov_b32_e32 v72, v34
	v_mov_b32_e32 v73, v34
	v_mov_b32_e32 v74, v34
	v_mov_b32_e32 v75, v34
	v_mov_b32_e32 v76, v34
	v_mov_b32_e32 v77, v34
	v_mov_b32_e32 v78, v34
	v_mov_b32_e32 v79, v34
	v_mov_b32_e32 v80, v34
	v_mov_b32_e32 v81, v34
	v_mov_b32_e32 v82, v34
	v_mov_b32_e32 v83, v34
	v_mov_b32_e32 v84, v34
	v_mov_b32_e32 v85, v34
	v_mov_b32_e32 v86, v34
	v_mov_b32_e32 v87, v34
	v_mov_b32_e32 v88, v34
	v_mov_b32_e32 v89, v34
	v_mov_b32_e32 v90, v34
	v_mov_b32_e32 v91, v34
	v_mov_b32_e32 v92, v34
	v_mov_b32_e32 v93, v34
	v_mov_b32_e32 v94, v34
	v_mov_b32_e32 v95, v34
	v_mov_b32_e32 v96, v34
	v_mov_b32_e32 v97, v34
	v_mov_b32_e32 v98, v34
	v_mov_b32_e32 v99, v34
	v_mov_b32_e32 v100, v34
	v_mov_b32_e32 v101, v34
	v_mov_b32_e32 v102, v34
	v_mov_b32_e32 v103, v34
	v_mov_b32_e32 v104, v34
	v_mov_b32_e32 v105, v34
	v_mov_b32_e32 v106, v34
	v_mov_b32_e32 v107, v34
	v_mov_b32_e32 v108, v34
	v_mov_b32_e32 v109, v34
	v_mov_b32_e32 v110, v34
	v_mov_b32_e32 v111, v34
	v_mov_b32_e32 v112, v34
	v_mov_b32_e32 v113, v34
	v_mov_b32_e32 v114, v34
	v_mov_b32_e32 v115, v34
	v_mov_b32_e32 v116, v34
	v_mov_b32_e32 v117, v34
	v_mov_b32_e32 v118, v34
	v_mov_b32_e32 v119, v34
	v_mov_b32_e32 v120, v34
	v_mov_b32_e32 v121, v34
	v_mov_b32_e32 v122, v34
	v_mov_b32_e32 v123, v34
	v_mov_b32_e32 v124, v34
	v_mov_b32_e32 v125, v34
	v_mov_b32_e32 v126, v34
	v_mov_b32_e32 v127, v34
	v_mov_b32_e32 v128, v34
	v_mov_b32_e32 v129, v34
	v_mov_b32_e32 v130, v34
	v_mov_b32_e32 v131, v34
	v_mov_b32_e32 v132, v34
	v_mov_b32_e32 v133, v34
	v_mov_b32_e32 v134, v34
	v_mov_b32_e32 v135, v34
	v_mov_b32_e32 v136, v34
	v_mov_b32_e32 v137, v34
	v_mov_b32_e32 v138, v34
	v_mov_b32_e32 v139, v34
	v_mov_b32_e32 v140, v34
	v_mov_b32_e32 v141, v34
	v_mov_b32_e32 v142, v34
	v_mov_b32_e32 v143, v34
	v_mov_b32_e32 v144, v34
	v_mov_b32_e32 v145, v34
	v_mov_b32_e32 v146, v34
	v_mov_b32_e32 v147, v34
	v_mov_b32_e32 v148, v34
	v_mov_b32_e32 v149, v34
	v_mov_b32_e32 v150, v34
	v_mov_b32_e32 v151, v34
	v_mov_b32_e32 v152, v34
	v_mov_b32_e32 v153, v34
	v_mov_b32_e32 v154, v34
	v_mov_b32_e32 v155, v34
	v_mov_b32_e32 v156, v34
	v_mov_b32_e32 v157, v34
	v_mov_b32_e32 v158, v34
	v_mov_b32_e32 v159, v34
	v_mov_b32_e32 v160, v34
	v_mov_b32_e32 v161, v34
	v_lshl_add_u64 v[162:163], v[162:163], 1, v[174:175]
	v_lshl_add_u64 v[164:165], v[164:165], 1, v[174:175]
.LBB0_72:
	s_mul_i32 s42, s1, 0x6000
	s_add_i32 s43, s42, 0xffffa000
	s_cmp_gt_i32 s1, 0
	s_waitcnt vmcnt(6)
	s_cselect_b32 s43, s43, 0xc000
	s_waitcnt lgkmcnt(0)
	s_barrier
	s_setprio 2
	v_add3_u32 v0, s42, v177, v176
	v_add_u32_e32 v0, s14, v0
	v_add3_u32 v212, s42, v178, v176
	ds_read_b128 v[196:199], v212 offset:8192
	ds_read_b128 v[180:183], v0
	ds_read_b128 v[184:187], v0 offset:1024
	ds_read_b128 v[188:191], v0 offset:2048
	ds_read_b128 v[192:195], v0 offset:3072
	ds_read_b128 v[200:203], v212 offset:9216
	ds_read_b128 v[204:207], v212 offset:10240
	ds_read_b128 v[208:211], v212 offset:11264
	ds_read_b128 v[216:219], v212 offset:12288
	ds_read_b128 v[226:229], v212 offset:13312
	ds_read_b128 v[230:233], v212 offset:14336
	ds_read_b128 v[234:237], v212 offset:15360
	s_add_i32 s44, s43, s41
	s_mov_b32 m0, s44
	s_nop 0
	global_load_lds_dwordx4 v[162:163], off
	s_add_i32 s44, s43, s15
	s_mov_b32 m0, s44
	s_nop 0
	global_load_lds_dwordx4 v[164:165], off
	s_add_i32 s43, s40, s43
	s_mov_b32 m0, s43
	s_nop 0
	global_load_lds_dwordx4 v[172:173], off
	s_add_i32 s44, s43, 0x400
	s_mov_b32 m0, s44
	s_nop 0
	global_load_lds_dwordx4 v[170:171], off
	s_add_i32 s44, s43, 0x800
	s_mov_b32 m0, s44
	s_nop 0
	global_load_lds_dwordx4 v[168:169], off
	s_addk_i32 s43, 0xc00
	s_mov_b32 m0, s43
	s_nop 0
	global_load_lds_dwordx4 v[166:167], off
	s_setprio 0
	s_waitcnt lgkmcnt(10)
	v_mfma_f32_16x16x32_bf16 v[34:37], v[196:199], v[180:183], v[34:37]
	s_waitcnt lgkmcnt(9)
	v_mfma_f32_16x16x32_bf16 v[38:41], v[196:199], v[184:187], v[38:41]
	s_waitcnt lgkmcnt(8)
	v_mfma_f32_16x16x32_bf16 v[42:45], v[196:199], v[188:191], v[42:45]
	s_waitcnt lgkmcnt(7)
	v_mfma_f32_16x16x32_bf16 v[46:49], v[196:199], v[192:195], v[46:49]
	s_waitcnt lgkmcnt(6)
	v_mfma_f32_16x16x32_bf16 v[50:53], v[200:203], v[180:183], v[50:53]
	v_mfma_f32_16x16x32_bf16 v[54:57], v[200:203], v[184:187], v[54:57]
	v_lshl_add_u64 v[162:163], v[162:163], 0, 64
	v_mfma_f32_16x16x32_bf16 v[58:61], v[200:203], v[188:191], v[58:61]
	v_mfma_f32_16x16x32_bf16 v[62:65], v[200:203], v[192:195], v[62:65]
	s_waitcnt lgkmcnt(5)
	v_mfma_f32_16x16x32_bf16 v[66:69], v[204:207], v[180:183], v[66:69]
	v_mfma_f32_16x16x32_bf16 v[70:73], v[204:207], v[184:187], v[70:73]
	v_lshl_add_u64 v[164:165], v[164:165], 0, 64
	v_mfma_f32_16x16x32_bf16 v[74:77], v[204:207], v[188:191], v[74:77]
	v_mfma_f32_16x16x32_bf16 v[78:81], v[204:207], v[192:195], v[78:81]
	s_waitcnt lgkmcnt(4)
	v_mfma_f32_16x16x32_bf16 v[82:85], v[208:211], v[180:183], v[82:85]
	v_mfma_f32_16x16x32_bf16 v[86:89], v[208:211], v[184:187], v[86:89]
	v_lshl_add_u64 v[172:173], v[172:173], 0, 64
	v_mfma_f32_16x16x32_bf16 v[90:93], v[208:211], v[188:191], v[90:93]
	v_mfma_f32_16x16x32_bf16 v[94:97], v[208:211], v[192:195], v[94:97]
	s_waitcnt lgkmcnt(3)
	v_mfma_f32_16x16x32_bf16 v[98:101], v[216:219], v[180:183], v[98:101]
	v_mfma_f32_16x16x32_bf16 v[102:105], v[216:219], v[184:187], v[102:105]
	v_lshl_add_u64 v[170:171], v[170:171], 0, 64
	v_mfma_f32_16x16x32_bf16 v[106:109], v[216:219], v[188:191], v[106:109]
	v_mfma_f32_16x16x32_bf16 v[110:113], v[216:219], v[192:195], v[110:113]
	s_waitcnt lgkmcnt(2)
	v_mfma_f32_16x16x32_bf16 v[114:117], v[226:229], v[180:183], v[114:117]
	v_mfma_f32_16x16x32_bf16 v[118:121], v[226:229], v[184:187], v[118:121]
	v_lshl_add_u64 v[168:169], v[168:169], 0, 64
	v_mfma_f32_16x16x32_bf16 v[122:125], v[226:229], v[188:191], v[122:125]
	v_mfma_f32_16x16x32_bf16 v[126:129], v[226:229], v[192:195], v[126:129]
	s_waitcnt lgkmcnt(1)
	v_mfma_f32_16x16x32_bf16 v[130:133], v[230:233], v[180:183], v[130:133]
	v_mfma_f32_16x16x32_bf16 v[134:137], v[230:233], v[184:187], v[134:137]
	v_lshl_add_u64 v[166:167], v[166:167], 0, 64
	v_mfma_f32_16x16x32_bf16 v[138:141], v[230:233], v[188:191], v[138:141]
	v_mfma_f32_16x16x32_bf16 v[142:145], v[230:233], v[192:195], v[142:145]
	s_waitcnt lgkmcnt(0)
	v_mfma_f32_16x16x32_bf16 v[146:149], v[234:237], v[180:183], v[146:149]
	v_mfma_f32_16x16x32_bf16 v[150:153], v[234:237], v[184:187], v[150:153]
	v_mfma_f32_16x16x32_bf16 v[154:157], v[234:237], v[188:191], v[154:157]
	v_mfma_f32_16x16x32_bf16 v[158:161], v[234:237], v[192:195], v[158:161]
	s_add_i32 s42, s1, 1
	s_cmp_lg_u32 s1, 2
	s_cselect_b32 s1, s42, 0
	s_add_u32 s12, s12, 64
	s_addc_u32 s13, s13, 0
	s_cmpk_eq_i32 s12, 0x780
	s_cbranch_scc0 .LBB0_72
	s_waitcnt vmcnt(6)
	v_mov_b32_e32 v162, v31
	v_mov_b32_e32 v163, v32
	v_mov_b32_e32 v31, v33
	v_mov_b32_e32 v164, v15
	v_mov_b32_e32 v165, v16
	v_pk_add_f32 v[30:31], v[162:163], v[30:31]
	v_mov_b32_e32 v15, v17
	v_pk_add_f32 v[14:15], v[164:165], v[14:15]
	v_add_f32_e32 v0, v30, v31
	v_add_f32_e32 v0, v0, v14
	v_add_f32_e32 v0, v0, v15
	s_waitcnt vmcnt(4)
	v_mov_b32_e32 v166, v27
	v_mov_b32_e32 v167, v28
	v_fmamk_f32 v0, v0, 0x3a800000, v250
	s_mov_b32 s1, 0x800000
	v_mov_b32_e32 v27, v29
	v_mov_b32_e32 v168, v11
	v_mov_b32_e32 v169, v12
	s_waitcnt vmcnt(1)
	v_mov_b32_e32 v180, v3
	v_mul_f32_e32 v3, 0x4b800000, v0
	v_cmp_gt_f32_e32 vcc, s1, v0
	v_pk_add_f32 v[14:15], v[166:167], v[26:27]
	v_mov_b32_e32 v11, v13
	v_cndmask_b32_e32 v0, v0, v3, vcc
	v_pk_add_f32 v[10:11], v[168:169], v[10:11]
	v_add_f32_e32 v3, v14, v15
	v_add_f32_e32 v3, v3, v10
	v_add_f32_e32 v3, v3, v11
	v_fmamk_f32 v3, v3, 0x3a800000, v250
	v_mov_b32_e32 v170, v23
	v_mov_b32_e32 v171, v24
	v_mov_b32_e32 v181, v4
	v_mul_f32_e32 v4, 0x4b800000, v3
	v_cmp_gt_f32_e64 s[40:41], s1, v3
	v_mov_b32_e32 v23, v25
	v_mov_b32_e32 v172, v7
	v_mov_b32_e32 v173, v8
	v_cndmask_b32_e64 v3, v3, v4, s[40:41]
	v_pk_add_f32 v[10:11], v[170:171], v[22:23]
	v_mov_b32_e32 v7, v9
	v_rsq_f32_e32 v179, v3
	v_pk_add_f32 v[6:7], v[172:173], v[6:7]
	v_add_f32_e32 v3, v10, v11
	v_add_f32_e32 v3, v3, v6
	v_add_f32_e32 v3, v3, v7
	v_fmamk_f32 v3, v3, 0x3a800000, v250
	v_mul_f32_e32 v4, 0x4b800000, v3
	v_cmp_gt_f32_e64 s[42:43], s1, v3
	s_waitcnt vmcnt(0)
	v_mov_b32_e32 v174, v19
	v_mov_b32_e32 v175, v20
	v_cndmask_b32_e64 v3, v3, v4, s[42:43]
	v_mov_b32_e32 v19, v21
	v_rsq_f32_e32 v182, v3
	v_pk_add_f32 v[6:7], v[174:175], v[18:19]
	v_mov_b32_e32 v3, v5
	v_pk_add_f32 v[2:3], v[180:181], v[2:3]
	v_add_f32_e32 v4, v6, v7
	v_add_f32_e32 v2, v4, v2
	v_add_f32_e32 v2, v2, v3
	v_fmamk_f32 v2, v2, 0x3a800000, v250
	v_mul_f32_e32 v3, 0x4b800000, v2
	v_cmp_gt_f32_e64 s[44:45], s1, v2
	s_waitcnt vmcnt(6)
	v_add_u32_e32 v183, v178, v176
	s_waitcnt lgkmcnt(0)
	s_barrier
	v_cndmask_b32_e64 v2, v2, v3, s[44:45]
	v_rsq_f32_e32 v180, v2
	ds_read_b128 v[2:5], v183 offset:15360
	ds_read_b128 v[6:9], v183 offset:14336
	ds_read_b128 v[10:13], v183 offset:13312
	ds_read_b128 v[14:17], v183 offset:12288
	ds_read_b128 v[18:21], v183 offset:11264
	ds_read_b128 v[22:25], v183 offset:10240
	ds_read_b128 v[26:29], v183 offset:9216
	ds_read_b128 v[30:33], v183 offset:8192
	v_add3_u32 v178, s14, v177, v176
	ds_read_b128 v[162:165], v178 offset:3072
	ds_read_b128 v[166:169], v178 offset:2048
	ds_read_b128 v[170:173], v178 offset:1024
	ds_read_b128 v[174:177], v178
	v_rsq_f32_e32 v0, v0
	v_mul_f32_e32 v184, 0x45800000, v179
	v_mul_f32_e32 v185, 0x45800000, v182
	v_mul_f32_e32 v186, 0x45800000, v180
	v_mul_f32_e32 v181, 0x45800000, v0
	s_waitcnt lgkmcnt(0)
	v_mfma_f32_16x16x32_bf16 v[34:37], v[30:33], v[174:177], v[34:37]
	v_mfma_f32_16x16x32_bf16 v[38:41], v[30:33], v[170:173], v[38:41]
	v_mfma_f32_16x16x32_bf16 v[42:45], v[30:33], v[166:169], v[42:45]
	v_mfma_f32_16x16x32_bf16 v[46:49], v[30:33], v[162:165], v[46:49]
	v_mfma_f32_16x16x32_bf16 v[50:53], v[26:29], v[174:177], v[50:53]
	v_mfma_f32_16x16x32_bf16 v[54:57], v[26:29], v[170:173], v[54:57]
	v_mfma_f32_16x16x32_bf16 v[58:61], v[26:29], v[166:169], v[58:61]
	v_mfma_f32_16x16x32_bf16 v[62:65], v[26:29], v[162:165], v[62:65]
	v_mfma_f32_16x16x32_bf16 v[66:69], v[22:25], v[174:177], v[66:69]
	v_mfma_f32_16x16x32_bf16 v[70:73], v[22:25], v[170:173], v[70:73]
	v_mfma_f32_16x16x32_bf16 v[74:77], v[22:25], v[166:169], v[74:77]
	v_mfma_f32_16x16x32_bf16 v[22:25], v[22:25], v[162:165], v[78:81]
	v_mfma_f32_16x16x32_bf16 v[78:81], v[18:21], v[174:177], v[82:85]
	v_mfma_f32_16x16x32_bf16 v[82:85], v[18:21], v[170:173], v[86:89]
	v_mfma_f32_16x16x32_bf16 v[86:89], v[18:21], v[166:169], v[90:93]
	v_mfma_f32_16x16x32_bf16 v[18:21], v[18:21], v[162:165], v[94:97]
	v_mfma_f32_16x16x32_bf16 v[90:93], v[14:17], v[174:177], v[98:101]
	v_mfma_f32_16x16x32_bf16 v[94:97], v[14:17], v[170:173], v[102:105]
	v_mfma_f32_16x16x32_bf16 v[98:101], v[14:17], v[166:169], v[106:109]
	v_mfma_f32_16x16x32_bf16 v[14:17], v[14:17], v[162:165], v[110:113]
	v_mfma_f32_16x16x32_bf16 v[102:105], v[10:13], v[174:177], v[114:117]
	v_mfma_f32_16x16x32_bf16 v[106:109], v[10:13], v[170:173], v[118:121]
	v_mfma_f32_16x16x32_bf16 v[110:113], v[10:13], v[166:169], v[122:125]
	v_mfma_f32_16x16x32_bf16 v[10:13], v[10:13], v[162:165], v[126:129]
	v_mfma_f32_16x16x32_bf16 v[114:117], v[6:9], v[174:177], v[130:133]
	v_mfma_f32_16x16x32_bf16 v[118:121], v[6:9], v[170:173], v[134:137]
	v_mfma_f32_16x16x32_bf16 v[122:125], v[6:9], v[166:169], v[138:141]
	v_mfma_f32_16x16x32_bf16 v[6:9], v[6:9], v[162:165], v[142:145]
	v_mfma_f32_16x16x32_bf16 v[126:129], v[2:5], v[174:177], v[146:149]
	v_mfma_f32_16x16x32_bf16 v[130:133], v[2:5], v[170:173], v[150:153]
	v_mfma_f32_16x16x32_bf16 v[134:137], v[2:5], v[166:169], v[154:157]
	v_mfma_f32_16x16x32_bf16 v[2:5], v[2:5], v[162:165], v[158:161]
	s_waitcnt vmcnt(0)
	v_cndmask_b32_e32 v30, v0, v181, vcc
	v_cndmask_b32_e64 v28, v179, v184, s[40:41]
	v_cndmask_b32_e64 v26, v182, v185, s[42:43]
	v_cndmask_b32_e64 v0, v180, v186, s[44:45]
	s_waitcnt lgkmcnt(0)
	s_barrier
	ds_read_b128 v[138:141], v178 offset:24576
	ds_read_b128 v[142:145], v178 offset:25600
	ds_read_b128 v[146:149], v178 offset:26624
	ds_read_b128 v[150:153], v178 offset:27648
	ds_read_b128 v[154:157], v183 offset:32768
	ds_read_b128 v[158:161], v183 offset:33792
	ds_read_b128 v[162:165], v183 offset:34816
	ds_read_b128 v[166:169], v183 offset:35840
	ds_read_b128 v[170:173], v183 offset:36864
	ds_read_b128 v[174:177], v183 offset:37888
	ds_read_b128 v[178:181], v183 offset:38912
	ds_read_b128 v[182:185], v183 offset:39936
	s_waitcnt lgkmcnt(7)
	v_mfma_f32_16x16x32_bf16 v[32:35], v[154:157], v[138:141], v[34:37]
	v_mfma_f32_16x16x32_bf16 v[36:39], v[154:157], v[142:145], v[38:41]
	v_mfma_f32_16x16x32_bf16 v[40:43], v[154:157], v[146:149], v[42:45]
	v_mfma_f32_16x16x32_bf16 v[44:47], v[154:157], v[150:153], v[46:49]
	s_waitcnt lgkmcnt(6)
	v_mfma_f32_16x16x32_bf16 v[48:51], v[158:161], v[138:141], v[50:53]
	v_mfma_f32_16x16x32_bf16 v[52:55], v[158:161], v[142:145], v[54:57]
	v_mfma_f32_16x16x32_bf16 v[56:59], v[158:161], v[146:149], v[58:61]
	v_mfma_f32_16x16x32_bf16 v[60:63], v[158:161], v[150:153], v[62:65]
	s_waitcnt lgkmcnt(5)
	v_mfma_f32_16x16x32_bf16 v[64:67], v[162:165], v[138:141], v[66:69]
	v_mfma_f32_16x16x32_bf16 v[68:71], v[162:165], v[142:145], v[70:73]
	v_mfma_f32_16x16x32_bf16 v[72:75], v[162:165], v[146:149], v[74:77]
	v_mfma_f32_16x16x32_bf16 v[154:157], v[162:165], v[150:153], v[22:25]
	s_waitcnt lgkmcnt(4)
	v_mfma_f32_16x16x32_bf16 v[76:79], v[166:169], v[138:141], v[78:81]
	v_mfma_f32_16x16x32_bf16 v[80:83], v[166:169], v[142:145], v[82:85]
	v_mfma_f32_16x16x32_bf16 v[84:87], v[166:169], v[146:149], v[86:89]
	v_mfma_f32_16x16x32_bf16 v[158:161], v[166:169], v[150:153], v[18:21]
	s_waitcnt lgkmcnt(3)
	v_mfma_f32_16x16x32_bf16 v[88:91], v[170:173], v[138:141], v[90:93]
	v_mfma_f32_16x16x32_bf16 v[92:95], v[170:173], v[142:145], v[94:97]
	v_mfma_f32_16x16x32_bf16 v[96:99], v[170:173], v[146:149], v[98:101]
	v_mfma_f32_16x16x32_bf16 v[162:165], v[170:173], v[150:153], v[14:17]
	s_waitcnt lgkmcnt(2)
	v_mfma_f32_16x16x32_bf16 v[100:103], v[174:177], v[138:141], v[102:105]
	v_mfma_f32_16x16x32_bf16 v[104:107], v[174:177], v[142:145], v[106:109]
	v_mfma_f32_16x16x32_bf16 v[108:111], v[174:177], v[146:149], v[110:113]
	v_mfma_f32_16x16x32_bf16 v[166:169], v[174:177], v[150:153], v[10:13]
	s_waitcnt lgkmcnt(1)
	v_mfma_f32_16x16x32_bf16 v[112:115], v[178:181], v[138:141], v[114:117]
	v_mfma_f32_16x16x32_bf16 v[116:119], v[178:181], v[142:145], v[118:121]
	v_mfma_f32_16x16x32_bf16 v[22:25], v[178:181], v[146:149], v[122:125]
	v_mfma_f32_16x16x32_bf16 v[18:21], v[178:181], v[150:153], v[6:9]
	s_waitcnt lgkmcnt(0)
	v_mfma_f32_16x16x32_bf16 v[14:17], v[182:185], v[138:141], v[126:129]
	v_mfma_f32_16x16x32_bf16 v[10:13], v[182:185], v[142:145], v[130:133]
	v_mfma_f32_16x16x32_bf16 v[6:9], v[182:185], v[146:149], v[134:137]
	v_mfma_f32_16x16x32_bf16 v[2:5], v[182:185], v[150:153], v[2:5]
	v_mov_b32_e32 v27, v224
	s_movk_i32 s1, 0x210
	v_lshrrev_b32_e32 v120, 1, v27
	v_and_b32_e32 v31, 0x7fffff80, v27
	v_and_b32_e32 v120, 24, v120
	v_and_b32_e32 v29, 0x4f, v27
	v_lshl_or_b32 v31, v31, 1, v120
	v_pk_mul_f32 v[32:33], v[30:31], v[32:33] op_sel_hi:[0,1]
	v_pk_mul_f32 v[34:35], v[30:31], v[34:35] op_sel_hi:[0,1]
	v_mad_u32_u24 v29, v29, s1, v31
	v_cvt_pk_bf16_f32 v32, v32, v33
	v_cvt_pk_bf16_f32 v33, v34, v35
	v_pk_mul_f32 v[34:35], v[28:29], v[36:37] op_sel_hi:[0,1]
	v_pk_mul_f32 v[36:37], v[28:29], v[38:39] op_sel_hi:[0,1]
	v_cvt_pk_bf16_f32 v34, v34, v35
	v_cvt_pk_bf16_f32 v35, v36, v37
	v_pk_mul_f32 v[36:37], v[26:27], v[40:41] op_sel_hi:[0,1]
	v_pk_mul_f32 v[38:39], v[26:27], v[42:43] op_sel_hi:[0,1]
	v_cvt_pk_bf16_f32 v36, v36, v37
	v_cvt_pk_bf16_f32 v37, v38, v39
	v_pk_mul_f32 v[38:39], v[0:1], v[44:45] op_sel_hi:[0,1]
	v_pk_mul_f32 v[40:41], v[0:1], v[46:47] op_sel_hi:[0,1]
	v_cvt_pk_bf16_f32 v38, v38, v39
	v_cvt_pk_bf16_f32 v39, v40, v41
	v_pk_mul_f32 v[40:41], v[30:31], v[48:49] op_sel_hi:[0,1]
	v_pk_mul_f32 v[42:43], v[30:31], v[50:51] op_sel_hi:[0,1]
	v_cvt_pk_bf16_f32 v40, v40, v41
	v_cvt_pk_bf16_f32 v41, v42, v43
	s_barrier
	ds_write2_b64 v29, v[32:33], v[40:41] offset1:4
	v_pk_mul_f32 v[32:33], v[28:29], v[52:53] op_sel_hi:[0,1]
	v_pk_mul_f32 v[40:41], v[28:29], v[54:55] op_sel_hi:[0,1]
	v_cvt_pk_bf16_f32 v32, v32, v33
	v_cvt_pk_bf16_f32 v33, v40, v41
	v_add_u32_e32 v31, 0x2000, v29
	ds_write2_b64 v31, v[34:35], v[32:33] offset0:32 offset1:36
	v_pk_mul_f32 v[32:33], v[26:27], v[56:57] op_sel_hi:[0,1]
	v_pk_mul_f32 v[34:35], v[26:27], v[58:59] op_sel_hi:[0,1]
	v_cvt_pk_bf16_f32 v32, v32, v33
	v_cvt_pk_bf16_f32 v33, v34, v35
	v_add_u32_e32 v44, 0x4000, v29
	ds_write2_b64 v44, v[36:37], v[32:33] offset0:64 offset1:68
	v_pk_mul_f32 v[32:33], v[0:1], v[60:61] op_sel_hi:[0,1]
	v_pk_mul_f32 v[34:35], v[0:1], v[62:63] op_sel_hi:[0,1]
	v_cvt_pk_bf16_f32 v32, v32, v33
	v_cvt_pk_bf16_f32 v33, v34, v35
	v_add_u32_e32 v45, 0x6000, v29
	ds_write2_b64 v45, v[38:39], v[32:33] offset0:96 offset1:100
	v_pk_mul_f32 v[32:33], v[30:31], v[64:65] op_sel_hi:[0,1]
	v_pk_mul_f32 v[34:35], v[30:31], v[66:67] op_sel_hi:[0,1]
	v_cvt_pk_bf16_f32 v32, v32, v33
	v_cvt_pk_bf16_f32 v33, v34, v35
	v_pk_mul_f32 v[34:35], v[28:29], v[68:69] op_sel_hi:[0,1]
	v_pk_mul_f32 v[36:37], v[28:29], v[70:71] op_sel_hi:[0,1]
	v_cvt_pk_bf16_f32 v34, v34, v35
	v_cvt_pk_bf16_f32 v35, v36, v37
	v_pk_mul_f32 v[36:37], v[26:27], v[72:73] op_sel_hi:[0,1]
	v_pk_mul_f32 v[38:39], v[26:27], v[74:75] op_sel_hi:[0,1]
	v_cvt_pk_bf16_f32 v36, v36, v37
	v_cvt_pk_bf16_f32 v37, v38, v39
	v_pk_mul_f32 v[38:39], v[0:1], v[154:155] op_sel_hi:[0,1]
	v_pk_mul_f32 v[40:41], v[0:1], v[156:157] op_sel_hi:[0,1]
	v_cvt_pk_bf16_f32 v38, v38, v39
	v_cvt_pk_bf16_f32 v39, v40, v41
	v_pk_mul_f32 v[40:41], v[30:31], v[76:77] op_sel_hi:[0,1]
	v_pk_mul_f32 v[42:43], v[30:31], v[78:79] op_sel_hi:[0,1]
	v_cvt_pk_bf16_f32 v40, v40, v41
	v_cvt_pk_bf16_f32 v41, v42, v43
	ds_write2_b64 v29, v[32:33], v[40:41] offset0:8 offset1:12
	v_pk_mul_f32 v[32:33], v[28:29], v[80:81] op_sel_hi:[0,1]
	v_pk_mul_f32 v[40:41], v[28:29], v[82:83] op_sel_hi:[0,1]
	v_cvt_pk_bf16_f32 v32, v32, v33
	v_cvt_pk_bf16_f32 v33, v40, v41
	ds_write2_b64 v31, v[34:35], v[32:33] offset0:40 offset1:44
	v_pk_mul_f32 v[32:33], v[26:27], v[84:85] op_sel_hi:[0,1]
	v_pk_mul_f32 v[34:35], v[26:27], v[86:87] op_sel_hi:[0,1]
	v_cvt_pk_bf16_f32 v32, v32, v33
	v_cvt_pk_bf16_f32 v33, v34, v35
	ds_write2_b64 v44, v[36:37], v[32:33] offset0:72 offset1:76
	v_pk_mul_f32 v[32:33], v[0:1], v[158:159] op_sel_hi:[0,1]
	v_pk_mul_f32 v[34:35], v[0:1], v[160:161] op_sel_hi:[0,1]
	v_cvt_pk_bf16_f32 v32, v32, v33
	v_cvt_pk_bf16_f32 v33, v34, v35
	ds_write2_b64 v45, v[38:39], v[32:33] offset0:104 offset1:108
	v_pk_mul_f32 v[32:33], v[30:31], v[88:89] op_sel_hi:[0,1]
	v_pk_mul_f32 v[34:35], v[30:31], v[90:91] op_sel_hi:[0,1]
	v_cvt_pk_bf16_f32 v32, v32, v33
	v_cvt_pk_bf16_f32 v33, v34, v35
	v_pk_mul_f32 v[34:35], v[28:29], v[92:93] op_sel_hi:[0,1]
	v_pk_mul_f32 v[36:37], v[28:29], v[94:95] op_sel_hi:[0,1]
	v_cvt_pk_bf16_f32 v34, v34, v35
	v_cvt_pk_bf16_f32 v35, v36, v37
	v_pk_mul_f32 v[36:37], v[26:27], v[96:97] op_sel_hi:[0,1]
	v_pk_mul_f32 v[38:39], v[26:27], v[98:99] op_sel_hi:[0,1]
	v_cvt_pk_bf16_f32 v36, v36, v37
	v_cvt_pk_bf16_f32 v37, v38, v39
	v_pk_mul_f32 v[38:39], v[0:1], v[162:163] op_sel_hi:[0,1]
	v_pk_mul_f32 v[40:41], v[0:1], v[164:165] op_sel_hi:[0,1]
	v_cvt_pk_bf16_f32 v38, v38, v39
	v_cvt_pk_bf16_f32 v39, v40, v41
	v_pk_mul_f32 v[40:41], v[30:31], v[100:101] op_sel_hi:[0,1]
	v_pk_mul_f32 v[42:43], v[30:31], v[102:103] op_sel_hi:[0,1]
	v_cvt_pk_bf16_f32 v40, v40, v41
	v_cvt_pk_bf16_f32 v41, v42, v43
	ds_write2_b64 v29, v[32:33], v[40:41] offset0:16 offset1:20
	v_pk_mul_f32 v[32:33], v[28:29], v[104:105] op_sel_hi:[0,1]
	v_pk_mul_f32 v[40:41], v[28:29], v[106:107] op_sel_hi:[0,1]
	v_cvt_pk_bf16_f32 v32, v32, v33
	v_cvt_pk_bf16_f32 v33, v40, v41
	ds_write2_b64 v31, v[34:35], v[32:33] offset0:48 offset1:52
	v_pk_mul_f32 v[32:33], v[26:27], v[108:109] op_sel_hi:[0,1]
	v_pk_mul_f32 v[34:35], v[26:27], v[110:111] op_sel_hi:[0,1]
	v_cvt_pk_bf16_f32 v32, v32, v33
	v_cvt_pk_bf16_f32 v33, v34, v35
	ds_write2_b64 v44, v[36:37], v[32:33] offset0:80 offset1:84
	v_pk_mul_f32 v[32:33], v[0:1], v[166:167] op_sel_hi:[0,1]
	v_pk_mul_f32 v[34:35], v[0:1], v[168:169] op_sel_hi:[0,1]
	v_cvt_pk_bf16_f32 v32, v32, v33
	v_cvt_pk_bf16_f32 v33, v34, v35
	v_pk_mul_f32 v[18:19], v[0:1], v[18:19] op_sel_hi:[0,1]
	v_pk_mul_f32 v[20:21], v[0:1], v[20:21] op_sel_hi:[0,1]
	v_pk_mul_f32 v[2:3], v[0:1], v[2:3] op_sel_hi:[0,1]
	v_pk_mul_f32 v[4:5], v[0:1], v[4:5] op_sel_hi:[0,1]
	v_lshlrev_b32_e32 v0, 3, v27
	ds_write2_b64 v45, v[38:39], v[32:33] offset0:112 offset1:116
	v_pk_mul_f32 v[32:33], v[30:31], v[112:113] op_sel_hi:[0,1]
	v_pk_mul_f32 v[34:35], v[30:31], v[114:115] op_sel_hi:[0,1]
	v_cvt_pk_bf16_f32 v18, v18, v19
	v_cvt_pk_bf16_f32 v19, v20, v21
	v_cvt_pk_bf16_f32 v2, v2, v3
	v_cvt_pk_bf16_f32 v3, v4, v5
	v_and_b32_e32 v0, 0xf8, v0
	v_cvt_pk_bf16_f32 v32, v32, v33
	v_cvt_pk_bf16_f32 v33, v34, v35
	v_pk_mul_f32 v[34:35], v[28:29], v[116:117] op_sel_hi:[0,1]
	v_pk_mul_f32 v[36:37], v[28:29], v[118:119] op_sel_hi:[0,1]
	v_pk_mul_f32 v[22:23], v[26:27], v[22:23] op_sel_hi:[0,1]
	v_pk_mul_f32 v[24:25], v[26:27], v[24:25] op_sel_hi:[0,1]
	v_pk_mul_f32 v[14:15], v[30:31], v[14:15] op_sel_hi:[0,1]
	v_pk_mul_f32 v[16:17], v[30:31], v[16:17] op_sel_hi:[0,1]
	v_pk_mul_f32 v[10:11], v[28:29], v[10:11] op_sel_hi:[0,1]
	v_pk_mul_f32 v[12:13], v[28:29], v[12:13] op_sel_hi:[0,1]
	v_pk_mul_f32 v[6:7], v[26:27], v[6:7] op_sel_hi:[0,1]
	v_pk_mul_f32 v[8:9], v[26:27], v[8:9] op_sel_hi:[0,1]
	ds_write2_b64 v45, v[18:19], v[2:3] offset0:120 offset1:124
	v_or_b32_e32 v2, s0, v0
	s_movk_i32 s1, 0x400
	v_cvt_pk_bf16_f32 v34, v34, v35
	v_cvt_pk_bf16_f32 v35, v36, v37
	v_cvt_pk_bf16_f32 v22, v22, v23
	v_cvt_pk_bf16_f32 v23, v24, v25
	v_cvt_pk_bf16_f32 v14, v14, v15
	v_cvt_pk_bf16_f32 v15, v16, v17
	v_cvt_pk_bf16_f32 v10, v10, v11
	v_cvt_pk_bf16_f32 v11, v12, v13
	v_cvt_pk_bf16_f32 v6, v6, v7
	v_cvt_pk_bf16_f32 v7, v8, v9
	v_cmp_gt_i32_e64 s[44:45], s1, v2
	ds_write2_b64 v29, v[32:33], v[14:15] offset0:24 offset1:28
	ds_write2_b64 v31, v[34:35], v[10:11] offset0:56 offset1:60
	ds_write2_b64 v44, v[22:23], v[6:7] offset0:88 offset1:92
	s_waitcnt lgkmcnt(0)
	s_barrier
	s_mov_b64 s[12:13], 11
	s_mov_b64 s[40:41], s[46:47]
	s_branch .LBB0_78
.LBB0_74:
	s_mov_b64 s[44:45], 0
	s_mov_b64 s[12:13], 11
	s_mov_b64 s[40:41], s[46:47]
	s_cbranch_execz .LBB0_78
	s_waitcnt vmcnt(6)
	v_mov_b32_e32 v58, v224
	s_waitcnt vmcnt(0)
	s_nop 0
	v_readfirstlane_b32 s0, v58
	v_bfe_u32 v59, v58, 4, 2
	s_and_b32 s14, s0, 0xffffffc0
	s_waitcnt vmcnt(4)
	v_bfe_u32 v42, v58, 2, 4
	v_sub_u32_e32 v60, 0, v59
	s_add_i32 s14, s14, s82
	v_xor_b32_e32 v0, v58, v60
	v_or_b32_e32 v6, s14, v42
	v_lshlrev_b32_e32 v0, 4, v0
	v_min_i32_e32 v4, 0x7ff, v6
	v_and_b32_e32 v0, 48, v0
	v_ashrrev_i32_e32 v5, 31, v4
	v_lshl_add_u64 v[2:3], s[56:57], 0, v[0:1]
	v_lshlrev_b64 v[4:5], 11, v[4:5]
	v_lshl_add_u64 v[34:35], v[2:3], 0, v[4:5]
	v_or_b32_e32 v4, 16, v6
	v_min_i32_e32 v4, 0x7ff, v4
	v_ashrrev_i32_e32 v5, 31, v4
	v_lshlrev_b64 v[4:5], 11, v[4:5]
	v_lshl_add_u64 v[36:37], v[2:3], 0, v[4:5]
	v_or_b32_e32 v4, 32, v6
	v_min_i32_e32 v4, 0x7ff, v4
	s_ashr_i32 s1, s0, 6
	v_ashrrev_i32_e32 v5, 31, v4
	s_and_b32 s13, s1, 1
	v_lshlrev_b64 v[4:5], 11, v[4:5]
	v_lshl_add_u64 v[38:39], v[2:3], 0, v[4:5]
	v_or_b32_e32 v4, 48, v6
	s_lshl_b32 s14, s13, 6
	v_min_i32_e32 v4, 0x7ff, v4
	v_and_b32_e32 v61, 15, v58
	s_or_b32 s14, s14, s71
	v_ashrrev_i32_e32 v5, 31, v4
	s_waitcnt vmcnt(1)
	v_or_b32_e32 v14, s14, v61
	v_lshlrev_b64 v[4:5], 11, v[4:5]
	v_ashrrev_i32_e32 v15, 31, v14
	v_lshl_add_u64 v[40:41], v[2:3], 0, v[4:5]
	v_lshlrev_b64 v[2:3], 5, v[14:15]
	v_lshl_add_u64 v[2:3], s[48:49], 0, v[2:3]
	s_barrier
	global_load_dwordx4 v[6:9], v[2:3], off offset:16
	global_load_dwordx4 v[22:25], v[2:3], off
	v_or_b32_e32 v2, 16, v14
	v_ashrrev_i32_e32 v3, 31, v2
	v_lshlrev_b64 v[2:3], 5, v[2:3]
	v_lshl_add_u64 v[10:11], s[48:49], 0, v[2:3]
	global_load_dwordx4 v[2:5], v[10:11], off offset:16
	global_load_dwordx4 v[18:21], v[10:11], off
	v_or_b32_e32 v10, 32, v14
	v_or_b32_e32 v14, 48, v14
	v_ashrrev_i32_e32 v11, 31, v10
	v_ashrrev_i32_e32 v15, 31, v14
	v_lshlrev_b64 v[10:11], 5, v[10:11]
	v_lshlrev_b64 v[14:15], 5, v[14:15]
	v_lshl_add_u64 v[16:17], s[48:49], 0, v[10:11]
	v_lshl_add_u64 v[30:31], s[48:49], 0, v[14:15]
	global_load_dwordx4 v[10:13], v[16:17], off offset:16
	global_load_dwordx4 v[26:29], v[16:17], off
	s_nop 0
	global_load_dwordx4 v[14:17], v[30:31], off offset:16
	s_nop 0
	global_load_dwordx4 v[30:33], v[30:31], off
	s_lshl_b32 s14, s1, 1
	s_waitcnt vmcnt(8)
	v_or_b32_e32 v46, s71, v42
	v_lshl_add_u32 v44, s1, 5, v46
	s_lshl_b32 s15, s14, 10
	s_or_b32 s14, s14, 1
	v_ashrrev_i32_e32 v45, 31, v44
	v_lshl_add_u32 v46, s14, 4, v46
	v_lshl_add_u64 v[42:43], s[4:5], 0, v[0:1]
	v_lshlrev_b64 v[162:163], 10, v[44:45]
	v_lshlrev_b64 v[44:45], 11, v[44:45]
	v_ashrrev_i32_e32 v47, 31, v46
	v_lshl_add_u64 v[44:45], v[42:43], 0, v[44:45]
	v_lshlrev_b64 v[164:165], 10, v[46:47]
	v_lshlrev_b64 v[46:47], 11, v[46:47]
	s_mov_b32 s42, m0
	s_mov_b32 m0, s15
	s_nop 0
	global_load_lds_dwordx4 v[44:45], off
	s_mov_b32 m0, s42
	v_lshl_add_u64 v[42:43], v[42:43], 0, v[46:47]
	s_lshl_b32 s40, s1, 12
	s_add_i32 s41, s15, 0x6000
	s_lshl_b32 s14, s14, 10
	s_mov_b32 s15, m0
	s_mov_b32 m0, s14
	s_nop 0
	global_load_lds_dwordx4 v[42:43], off
	s_mov_b32 m0, s15
	s_add_i32 s15, s40, 0x2000
	s_mov_b32 s42, m0
	s_mov_b32 m0, s15
	s_nop 0
	global_load_lds_dwordx4 v[34:35], off
	s_mov_b32 m0, s42
	s_add_i32 s42, s40, 0x2400
	s_mov_b32 s43, m0
	s_mov_b32 m0, s42
	s_nop 0
	global_load_lds_dwordx4 v[36:37], off
	s_mov_b32 m0, s43
	s_add_i32 s42, s40, 0x2800
	s_mov_b32 s43, m0
	s_mov_b32 m0, s42
	s_nop 0
	global_load_lds_dwordx4 v[38:39], off
	s_mov_b32 m0, s43
	s_add_i32 s42, s40, 0x2c00
	s_mov_b32 s43, m0
	s_mov_b32 m0, s42
	s_nop 0
	global_load_lds_dwordx4 v[40:41], off
	s_mov_b32 m0, s43
	v_lshl_add_u64 v[46:47], v[44:45], 0, 64
	s_mov_b32 s42, m0
	s_mov_b32 m0, s41
	s_nop 0
	global_load_lds_dwordx4 v[46:47], off
	s_mov_b32 m0, s42
	v_lshl_add_u64 v[48:49], v[42:43], 0, 64
	s_add_i32 s41, s14, 0x6000
	s_mov_b32 s42, m0
	s_mov_b32 m0, s41
	s_nop 0
	global_load_lds_dwordx4 v[48:49], off
	s_mov_b32 m0, s42
	v_lshrrev_b32_e32 v0, 2, v58
	s_waitcnt vmcnt(25)
	v_lshl_add_u64 v[50:51], v[34:35], 0, 64
	s_add_i32 s41, s40, 0x8000
	s_mov_b32 s42, m0
	s_mov_b32 m0, s41
	s_nop 0
	global_load_lds_dwordx4 v[50:51], off
	s_mov_b32 m0, s42
	v_sub_u32_e32 v0, 0, v0
	v_lshl_add_u64 v[52:53], v[36:37], 0, 64
	s_add_i32 s41, s40, 0x8400
	s_mov_b32 s42, m0
	s_mov_b32 m0, s41
	s_nop 0
	global_load_lds_dwordx4 v[52:53], off
	s_mov_b32 m0, s42
	v_bitop3_b32 v0, v59, v0, 3 bitop3:0x78
	s_and_b32 s0, s0, 0x3ffff80
	v_lshl_add_u64 v[54:55], v[38:39], 0, 64
	s_add_i32 s41, s40, 0x8800
	s_mov_b32 s42, m0
	s_mov_b32 m0, s41
	s_nop 0
	global_load_lds_dwordx4 v[54:55], off
	s_mov_b32 m0, s42
	v_lshlrev_b32_e32 v176, 4, v0
	v_or_b32_e32 v0, s0, v61
	v_lshl_add_u64 v[56:57], v[40:41], 0, 64
	s_add_i32 s40, s40, 0x8c00
	s_mov_b32 s41, m0
	s_mov_b32 m0, s40
	s_nop 0
	global_load_lds_dwordx4 v[56:57], off
	s_mov_b32 m0, s41
	v_lshlrev_b32_e32 v178, 6, v0
	v_bitop3_b32 v0, v58, 3, v60 bitop3:0x48
	v_lshl_add_u64 v[172:173], v[34:35], 0, s[6:7]
	v_lshlrev_b32_e32 v0, 4, v0
	v_mov_b32_e32 v34, 0
	s_mov_b32 s12, 0
	s_lshl_b32 s13, s13, 12
	v_lshlrev_b32_e32 v177, 6, v61
	s_lshl_b32 s40, s1, 11
	v_lshl_add_u64 v[166:167], v[40:41], 0, s[6:7]
	v_lshl_add_u64 v[168:169], v[38:39], 0, s[6:7]
	v_lshl_add_u64 v[170:171], v[36:37], 0, s[6:7]
	v_lshl_add_u64 v[174:175], s[74:75], 0, v[0:1]
	s_mov_b64 s[0:1], 0
	v_mov_b32_e32 v35, v34
	v_mov_b32_e32 v36, v34
	v_mov_b32_e32 v37, v34
	v_mov_b32_e32 v38, v34
	v_mov_b32_e32 v39, v34
	v_mov_b32_e32 v40, v34
	v_mov_b32_e32 v41, v34
	v_mov_b32_e32 v42, v34
	v_mov_b32_e32 v43, v34
	v_mov_b32_e32 v44, v34
	v_mov_b32_e32 v45, v34
	v_mov_b32_e32 v46, v34
	v_mov_b32_e32 v47, v34
	v_mov_b32_e32 v48, v34
	v_mov_b32_e32 v49, v34
	v_mov_b32_e32 v50, v34
	v_mov_b32_e32 v51, v34
	v_mov_b32_e32 v52, v34
	v_mov_b32_e32 v53, v34
	v_mov_b32_e32 v54, v34
	v_mov_b32_e32 v55, v34
	v_mov_b32_e32 v56, v34
	v_mov_b32_e32 v57, v34
	v_mov_b32_e32 v58, v34
	v_mov_b32_e32 v59, v34
	v_mov_b32_e32 v60, v34
	v_mov_b32_e32 v61, v34
	s_waitcnt vmcnt(24)
	v_mov_b32_e32 v62, v34
	v_mov_b32_e32 v63, v34
	v_mov_b32_e32 v64, v34
	v_mov_b32_e32 v65, v34
	v_mov_b32_e32 v66, v34
	v_mov_b32_e32 v67, v34
	v_mov_b32_e32 v68, v34
	v_mov_b32_e32 v69, v34
	v_mov_b32_e32 v70, v34
	v_mov_b32_e32 v71, v34
	v_mov_b32_e32 v72, v34
	v_mov_b32_e32 v73, v34
	v_mov_b32_e32 v74, v34
	v_mov_b32_e32 v75, v34
	v_mov_b32_e32 v76, v34
	v_mov_b32_e32 v77, v34
	v_mov_b32_e32 v78, v34
	v_mov_b32_e32 v79, v34
	v_mov_b32_e32 v80, v34
	v_mov_b32_e32 v81, v34
	v_mov_b32_e32 v82, v34
	v_mov_b32_e32 v83, v34
	v_mov_b32_e32 v84, v34
	v_mov_b32_e32 v85, v34
	v_mov_b32_e32 v86, v34
	v_mov_b32_e32 v87, v34
	v_mov_b32_e32 v88, v34
	v_mov_b32_e32 v89, v34
	v_mov_b32_e32 v90, v34
	v_mov_b32_e32 v91, v34
	v_mov_b32_e32 v92, v34
	v_mov_b32_e32 v93, v34
	v_mov_b32_e32 v94, v34
	v_mov_b32_e32 v95, v34
	v_mov_b32_e32 v96, v34
	v_mov_b32_e32 v97, v34
	v_mov_b32_e32 v98, v34
	v_mov_b32_e32 v99, v34
	v_mov_b32_e32 v100, v34
	v_mov_b32_e32 v101, v34
	v_mov_b32_e32 v102, v34
	v_mov_b32_e32 v103, v34
	v_mov_b32_e32 v104, v34
	v_mov_b32_e32 v105, v34
	v_mov_b32_e32 v106, v34
	v_mov_b32_e32 v107, v34
	v_mov_b32_e32 v108, v34
	v_mov_b32_e32 v109, v34
	v_mov_b32_e32 v110, v34
	v_mov_b32_e32 v111, v34
	v_mov_b32_e32 v112, v34
	v_mov_b32_e32 v113, v34
	v_mov_b32_e32 v114, v34
	v_mov_b32_e32 v115, v34
	v_mov_b32_e32 v116, v34
	v_mov_b32_e32 v117, v34
	v_mov_b32_e32 v118, v34
	v_mov_b32_e32 v119, v34
	v_mov_b32_e32 v120, v34
	v_mov_b32_e32 v121, v34
	v_mov_b32_e32 v122, v34
	v_mov_b32_e32 v123, v34
	v_mov_b32_e32 v124, v34
	v_mov_b32_e32 v125, v34
	v_mov_b32_e32 v126, v34
	v_mov_b32_e32 v127, v34
	v_mov_b32_e32 v128, v34
	v_mov_b32_e32 v129, v34
	v_mov_b32_e32 v130, v34
	v_mov_b32_e32 v131, v34
	v_mov_b32_e32 v132, v34
	v_mov_b32_e32 v133, v34
	v_mov_b32_e32 v134, v34
	v_mov_b32_e32 v135, v34
	v_mov_b32_e32 v136, v34
	v_mov_b32_e32 v137, v34
	v_mov_b32_e32 v138, v34
	v_mov_b32_e32 v139, v34
	v_mov_b32_e32 v140, v34
	v_mov_b32_e32 v141, v34
	v_mov_b32_e32 v142, v34
	v_mov_b32_e32 v143, v34
	v_mov_b32_e32 v144, v34
	v_mov_b32_e32 v145, v34
	v_mov_b32_e32 v146, v34
	v_mov_b32_e32 v147, v34
	v_mov_b32_e32 v148, v34
	v_mov_b32_e32 v149, v34
	v_mov_b32_e32 v150, v34
	v_mov_b32_e32 v151, v34
	v_mov_b32_e32 v152, v34
	v_mov_b32_e32 v153, v34
	v_mov_b32_e32 v154, v34
	v_mov_b32_e32 v155, v34
	v_mov_b32_e32 v156, v34
	v_mov_b32_e32 v157, v34
	v_mov_b32_e32 v158, v34
	v_mov_b32_e32 v159, v34
	v_mov_b32_e32 v160, v34
	v_mov_b32_e32 v161, v34
	v_lshl_add_u64 v[162:163], v[162:163], 1, v[174:175]
	v_lshl_add_u64 v[164:165], v[164:165], 1, v[174:175]
.LBB0_76:
	s_mul_i32 s41, s12, 0x6000
	s_add_i32 s42, s41, 0xffffa000
	s_cmp_gt_i32 s12, 0
	s_waitcnt vmcnt(6)
	s_cselect_b32 s42, s42, 0xc000
	s_waitcnt lgkmcnt(0)
	s_barrier
	s_setprio 2
	v_add3_u32 v0, s41, v177, v176
	v_add_u32_e32 v0, s13, v0
	v_add3_u32 v212, s41, v178, v176
	ds_read_b128 v[196:199], v212 offset:8192
	ds_read_b128 v[180:183], v0
	ds_read_b128 v[184:187], v0 offset:1024
	ds_read_b128 v[188:191], v0 offset:2048
	ds_read_b128 v[192:195], v0 offset:3072
	ds_read_b128 v[200:203], v212 offset:9216
	ds_read_b128 v[204:207], v212 offset:10240
	ds_read_b128 v[208:211], v212 offset:11264
	ds_read_b128 v[216:219], v212 offset:12288
	ds_read_b128 v[226:229], v212 offset:13312
	ds_read_b128 v[230:233], v212 offset:14336
	ds_read_b128 v[234:237], v212 offset:15360
	s_add_i32 s43, s42, s40
	s_mov_b32 m0, s43
	s_nop 0
	global_load_lds_dwordx4 v[162:163], off
	s_add_i32 s43, s42, s14
	s_mov_b32 m0, s43
	s_nop 0
	global_load_lds_dwordx4 v[164:165], off
	s_add_i32 s42, s15, s42
	s_mov_b32 m0, s42
	s_nop 0
	global_load_lds_dwordx4 v[172:173], off
	s_add_i32 s43, s42, 0x400
	s_mov_b32 m0, s43
	s_nop 0
	global_load_lds_dwordx4 v[170:171], off
	s_add_i32 s43, s42, 0x800
	s_mov_b32 m0, s43
	s_nop 0
	global_load_lds_dwordx4 v[168:169], off
	s_addk_i32 s42, 0xc00
	s_mov_b32 m0, s42
	s_nop 0
	global_load_lds_dwordx4 v[166:167], off
	s_setprio 0
	s_waitcnt lgkmcnt(10)
	v_mfma_f32_16x16x32_bf16 v[34:37], v[196:199], v[180:183], v[34:37]
	s_waitcnt lgkmcnt(9)
	v_mfma_f32_16x16x32_bf16 v[38:41], v[196:199], v[184:187], v[38:41]
	s_waitcnt lgkmcnt(8)
	v_mfma_f32_16x16x32_bf16 v[42:45], v[196:199], v[188:191], v[42:45]
	s_waitcnt lgkmcnt(7)
	v_mfma_f32_16x16x32_bf16 v[46:49], v[196:199], v[192:195], v[46:49]
	s_waitcnt lgkmcnt(6)
	v_mfma_f32_16x16x32_bf16 v[50:53], v[200:203], v[180:183], v[50:53]
	v_mfma_f32_16x16x32_bf16 v[54:57], v[200:203], v[184:187], v[54:57]
	v_lshl_add_u64 v[162:163], v[162:163], 0, 64
	v_mfma_f32_16x16x32_bf16 v[58:61], v[200:203], v[188:191], v[58:61]
	v_mfma_f32_16x16x32_bf16 v[62:65], v[200:203], v[192:195], v[62:65]
	s_waitcnt lgkmcnt(5)
	v_mfma_f32_16x16x32_bf16 v[66:69], v[204:207], v[180:183], v[66:69]
	v_mfma_f32_16x16x32_bf16 v[70:73], v[204:207], v[184:187], v[70:73]
	v_lshl_add_u64 v[164:165], v[164:165], 0, 64
	v_mfma_f32_16x16x32_bf16 v[74:77], v[204:207], v[188:191], v[74:77]
	v_mfma_f32_16x16x32_bf16 v[78:81], v[204:207], v[192:195], v[78:81]
	s_waitcnt lgkmcnt(4)
	v_mfma_f32_16x16x32_bf16 v[82:85], v[208:211], v[180:183], v[82:85]
	v_mfma_f32_16x16x32_bf16 v[86:89], v[208:211], v[184:187], v[86:89]
	v_lshl_add_u64 v[172:173], v[172:173], 0, 64
	v_mfma_f32_16x16x32_bf16 v[90:93], v[208:211], v[188:191], v[90:93]
	v_mfma_f32_16x16x32_bf16 v[94:97], v[208:211], v[192:195], v[94:97]
	s_waitcnt lgkmcnt(3)
	v_mfma_f32_16x16x32_bf16 v[98:101], v[216:219], v[180:183], v[98:101]
	v_mfma_f32_16x16x32_bf16 v[102:105], v[216:219], v[184:187], v[102:105]
	v_lshl_add_u64 v[170:171], v[170:171], 0, 64
	v_mfma_f32_16x16x32_bf16 v[106:109], v[216:219], v[188:191], v[106:109]
	v_mfma_f32_16x16x32_bf16 v[110:113], v[216:219], v[192:195], v[110:113]
	s_waitcnt lgkmcnt(2)
	v_mfma_f32_16x16x32_bf16 v[114:117], v[226:229], v[180:183], v[114:117]
	v_mfma_f32_16x16x32_bf16 v[118:121], v[226:229], v[184:187], v[118:121]
	v_lshl_add_u64 v[168:169], v[168:169], 0, 64
	v_mfma_f32_16x16x32_bf16 v[122:125], v[226:229], v[188:191], v[122:125]
	v_mfma_f32_16x16x32_bf16 v[126:129], v[226:229], v[192:195], v[126:129]
	s_waitcnt lgkmcnt(1)
	v_mfma_f32_16x16x32_bf16 v[130:133], v[230:233], v[180:183], v[130:133]
	v_mfma_f32_16x16x32_bf16 v[134:137], v[230:233], v[184:187], v[134:137]
	v_lshl_add_u64 v[166:167], v[166:167], 0, 64
	v_mfma_f32_16x16x32_bf16 v[138:141], v[230:233], v[188:191], v[138:141]
	v_mfma_f32_16x16x32_bf16 v[142:145], v[230:233], v[192:195], v[142:145]
	s_waitcnt lgkmcnt(0)
	v_mfma_f32_16x16x32_bf16 v[146:149], v[234:237], v[180:183], v[146:149]
	v_mfma_f32_16x16x32_bf16 v[150:153], v[234:237], v[184:187], v[150:153]
	v_mfma_f32_16x16x32_bf16 v[154:157], v[234:237], v[188:191], v[154:157]
	v_mfma_f32_16x16x32_bf16 v[158:161], v[234:237], v[192:195], v[158:161]
	s_add_i32 s41, s12, 1
	s_cmp_lg_u32 s12, 2
	s_cselect_b32 s12, s41, 0
	s_add_u32 s0, s0, 64
	s_addc_u32 s1, s1, 0
	s_cmpk_eq_i32 s0, 0x780
	s_cbranch_scc0 .LBB0_76
	s_waitcnt vmcnt(6)
	v_mov_b32_e32 v162, v23
	v_mov_b32_e32 v163, v24
	v_mov_b32_e32 v23, v25
	v_mov_b32_e32 v164, v7
	v_mov_b32_e32 v165, v8
	v_pk_add_f32 v[22:23], v[162:163], v[22:23]
	v_mov_b32_e32 v7, v9
	v_pk_add_f32 v[6:7], v[164:165], v[6:7]
	v_add_f32_e32 v0, v22, v23
	v_add_f32_e32 v0, v0, v6
	v_add_f32_e32 v0, v0, v7
	v_fmamk_f32 v0, v0, 0x3a800000, v250
	s_mov_b32 s0, 0x800000
	s_waitcnt vmcnt(4)
	v_mov_b32_e32 v166, v19
	v_mov_b32_e32 v167, v20
	v_mov_b32_e32 v168, v3
	v_mul_f32_e32 v3, 0x4b800000, v0
	v_cmp_gt_f32_e32 vcc, s0, v0
	v_mov_b32_e32 v19, v21
	v_mov_b32_e32 v169, v4
	v_cndmask_b32_e32 v0, v0, v3, vcc
	v_pk_add_f32 v[6:7], v[166:167], v[18:19]
	v_mov_b32_e32 v3, v5
	v_pk_add_f32 v[2:3], v[168:169], v[2:3]
	v_add_f32_e32 v4, v6, v7
	v_add_f32_e32 v2, v4, v2
	v_add_f32_e32 v2, v2, v3
	v_fmamk_f32 v2, v2, 0x3a800000, v250
	v_mul_f32_e32 v3, 0x4b800000, v2
	v_cmp_gt_f32_e64 s[40:41], s0, v2
	s_waitcnt vmcnt(2)
	v_mov_b32_e32 v170, v27
	v_mov_b32_e32 v171, v28
	v_cndmask_b32_e64 v2, v2, v3, s[40:41]
	v_mov_b32_e32 v27, v29
	v_mov_b32_e32 v172, v11
	v_mov_b32_e32 v173, v12
	v_rsq_f32_e32 v179, v2
	v_pk_add_f32 v[2:3], v[170:171], v[26:27]
	v_mov_b32_e32 v11, v13
	v_pk_add_f32 v[4:5], v[172:173], v[10:11]
	v_add_f32_e32 v2, v2, v3
	v_add_f32_e32 v2, v2, v4
	v_add_f32_e32 v2, v2, v5
	v_fmamk_f32 v2, v2, 0x3a800000, v250
	v_mul_f32_e32 v3, 0x4b800000, v2
	v_cmp_gt_f32_e64 s[42:43], s0, v2
	s_waitcnt vmcnt(0)
	v_mov_b32_e32 v174, v31
	v_mov_b32_e32 v175, v32
	v_cndmask_b32_e64 v2, v2, v3, s[42:43]
	v_mov_b32_e32 v31, v33
	v_mov_b32_e32 v180, v15
	v_mov_b32_e32 v181, v16
	v_rsq_f32_e32 v182, v2
	v_pk_add_f32 v[2:3], v[174:175], v[30:31]
	v_mov_b32_e32 v15, v17
	v_pk_add_f32 v[4:5], v[180:181], v[14:15]
	v_add_f32_e32 v2, v2, v3
	v_add_f32_e32 v2, v2, v4
	v_add_f32_e32 v2, v2, v5
	v_fmamk_f32 v2, v2, 0x3a800000, v250
	v_mul_f32_e32 v3, 0x4b800000, v2
	v_cmp_gt_f32_e64 s[44:45], s0, v2
	s_waitcnt vmcnt(6)
	v_add_u32_e32 v183, v178, v176
	s_waitcnt lgkmcnt(0)
	s_barrier
	v_cndmask_b32_e64 v2, v2, v3, s[44:45]
	v_rsq_f32_e32 v180, v2
	ds_read_b128 v[2:5], v183 offset:15360
	ds_read_b128 v[6:9], v183 offset:14336
	ds_read_b128 v[10:13], v183 offset:13312
	ds_read_b128 v[14:17], v183 offset:12288
	ds_read_b128 v[18:21], v183 offset:11264
	ds_read_b128 v[22:25], v183 offset:10240
	ds_read_b128 v[26:29], v183 offset:9216
	ds_read_b128 v[30:33], v183 offset:8192
	v_add3_u32 v178, s13, v177, v176
	ds_read_b128 v[162:165], v178 offset:3072
	ds_read_b128 v[166:169], v178 offset:2048
	ds_read_b128 v[170:173], v178 offset:1024
	ds_read_b128 v[174:177], v178
	v_rsq_f32_e32 v0, v0
	v_mul_f32_e32 v184, 0x45800000, v179
	v_mul_f32_e32 v185, 0x45800000, v182
	v_mul_f32_e32 v186, 0x45800000, v180
	v_mul_f32_e32 v181, 0x45800000, v0
	s_waitcnt lgkmcnt(0)
	v_mfma_f32_16x16x32_bf16 v[34:37], v[30:33], v[174:177], v[34:37]
	v_mfma_f32_16x16x32_bf16 v[38:41], v[30:33], v[170:173], v[38:41]
	v_mfma_f32_16x16x32_bf16 v[42:45], v[30:33], v[166:169], v[42:45]
	v_mfma_f32_16x16x32_bf16 v[46:49], v[30:33], v[162:165], v[46:49]
	v_mfma_f32_16x16x32_bf16 v[50:53], v[26:29], v[174:177], v[50:53]
	v_mfma_f32_16x16x32_bf16 v[54:57], v[26:29], v[170:173], v[54:57]
	v_mfma_f32_16x16x32_bf16 v[58:61], v[26:29], v[166:169], v[58:61]
	v_mfma_f32_16x16x32_bf16 v[62:65], v[26:29], v[162:165], v[62:65]
	v_mfma_f32_16x16x32_bf16 v[66:69], v[22:25], v[174:177], v[66:69]
	v_mfma_f32_16x16x32_bf16 v[70:73], v[22:25], v[170:173], v[70:73]
	v_mfma_f32_16x16x32_bf16 v[74:77], v[22:25], v[166:169], v[74:77]
	v_mfma_f32_16x16x32_bf16 v[22:25], v[22:25], v[162:165], v[78:81]
	v_mfma_f32_16x16x32_bf16 v[78:81], v[18:21], v[174:177], v[82:85]
	v_mfma_f32_16x16x32_bf16 v[82:85], v[18:21], v[170:173], v[86:89]
	v_mfma_f32_16x16x32_bf16 v[86:89], v[18:21], v[166:169], v[90:93]
	v_mfma_f32_16x16x32_bf16 v[18:21], v[18:21], v[162:165], v[94:97]
	v_mfma_f32_16x16x32_bf16 v[90:93], v[14:17], v[174:177], v[98:101]
	v_mfma_f32_16x16x32_bf16 v[94:97], v[14:17], v[170:173], v[102:105]
	v_mfma_f32_16x16x32_bf16 v[98:101], v[14:17], v[166:169], v[106:109]
	v_mfma_f32_16x16x32_bf16 v[14:17], v[14:17], v[162:165], v[110:113]
	v_mfma_f32_16x16x32_bf16 v[102:105], v[10:13], v[174:177], v[114:117]
	v_mfma_f32_16x16x32_bf16 v[106:109], v[10:13], v[170:173], v[118:121]
	v_mfma_f32_16x16x32_bf16 v[110:113], v[10:13], v[166:169], v[122:125]
	v_mfma_f32_16x16x32_bf16 v[10:13], v[10:13], v[162:165], v[126:129]
	v_mfma_f32_16x16x32_bf16 v[114:117], v[6:9], v[174:177], v[130:133]
	v_mfma_f32_16x16x32_bf16 v[118:121], v[6:9], v[170:173], v[134:137]
	v_mfma_f32_16x16x32_bf16 v[122:125], v[6:9], v[166:169], v[138:141]
	v_mfma_f32_16x16x32_bf16 v[6:9], v[6:9], v[162:165], v[142:145]
	v_mfma_f32_16x16x32_bf16 v[126:129], v[2:5], v[174:177], v[146:149]
	v_mfma_f32_16x16x32_bf16 v[130:133], v[2:5], v[170:173], v[150:153]
	v_mfma_f32_16x16x32_bf16 v[134:137], v[2:5], v[166:169], v[154:157]
	v_mfma_f32_16x16x32_bf16 v[2:5], v[2:5], v[162:165], v[158:161]
	s_waitcnt vmcnt(0)
	v_cndmask_b32_e32 v30, v0, v181, vcc
	v_cndmask_b32_e64 v28, v179, v184, s[40:41]
	v_cndmask_b32_e64 v26, v182, v185, s[42:43]
	v_cndmask_b32_e64 v0, v180, v186, s[44:45]
	s_waitcnt lgkmcnt(0)
	s_barrier
	ds_read_b128 v[138:141], v178 offset:24576
	ds_read_b128 v[142:145], v178 offset:25600
	ds_read_b128 v[146:149], v178 offset:26624
	ds_read_b128 v[150:153], v178 offset:27648
	ds_read_b128 v[154:157], v183 offset:32768
	ds_read_b128 v[158:161], v183 offset:33792
	ds_read_b128 v[162:165], v183 offset:34816
	ds_read_b128 v[166:169], v183 offset:35840
	ds_read_b128 v[170:173], v183 offset:36864
	ds_read_b128 v[174:177], v183 offset:37888
	ds_read_b128 v[178:181], v183 offset:38912
	ds_read_b128 v[182:185], v183 offset:39936
	s_waitcnt lgkmcnt(7)
	v_mfma_f32_16x16x32_bf16 v[32:35], v[154:157], v[138:141], v[34:37]
	v_mfma_f32_16x16x32_bf16 v[36:39], v[154:157], v[142:145], v[38:41]
	v_mfma_f32_16x16x32_bf16 v[40:43], v[154:157], v[146:149], v[42:45]
	v_mfma_f32_16x16x32_bf16 v[44:47], v[154:157], v[150:153], v[46:49]
	s_waitcnt lgkmcnt(6)
	v_mfma_f32_16x16x32_bf16 v[48:51], v[158:161], v[138:141], v[50:53]
	v_mfma_f32_16x16x32_bf16 v[52:55], v[158:161], v[142:145], v[54:57]
	v_mfma_f32_16x16x32_bf16 v[56:59], v[158:161], v[146:149], v[58:61]
	v_mfma_f32_16x16x32_bf16 v[60:63], v[158:161], v[150:153], v[62:65]
	s_waitcnt lgkmcnt(5)
	v_mfma_f32_16x16x32_bf16 v[64:67], v[162:165], v[138:141], v[66:69]
	v_mfma_f32_16x16x32_bf16 v[68:71], v[162:165], v[142:145], v[70:73]
	v_mfma_f32_16x16x32_bf16 v[72:75], v[162:165], v[146:149], v[74:77]
	v_mfma_f32_16x16x32_bf16 v[154:157], v[162:165], v[150:153], v[22:25]
	s_waitcnt lgkmcnt(4)
	v_mfma_f32_16x16x32_bf16 v[76:79], v[166:169], v[138:141], v[78:81]
	v_mfma_f32_16x16x32_bf16 v[80:83], v[166:169], v[142:145], v[82:85]
	v_mfma_f32_16x16x32_bf16 v[84:87], v[166:169], v[146:149], v[86:89]
	v_mfma_f32_16x16x32_bf16 v[158:161], v[166:169], v[150:153], v[18:21]
	s_waitcnt lgkmcnt(3)
	v_mfma_f32_16x16x32_bf16 v[88:91], v[170:173], v[138:141], v[90:93]
	v_mfma_f32_16x16x32_bf16 v[92:95], v[170:173], v[142:145], v[94:97]
	v_mfma_f32_16x16x32_bf16 v[96:99], v[170:173], v[146:149], v[98:101]
	v_mfma_f32_16x16x32_bf16 v[162:165], v[170:173], v[150:153], v[14:17]
	s_waitcnt lgkmcnt(2)
	v_mfma_f32_16x16x32_bf16 v[100:103], v[174:177], v[138:141], v[102:105]
	v_mfma_f32_16x16x32_bf16 v[104:107], v[174:177], v[142:145], v[106:109]
	v_mfma_f32_16x16x32_bf16 v[108:111], v[174:177], v[146:149], v[110:113]
	v_mfma_f32_16x16x32_bf16 v[166:169], v[174:177], v[150:153], v[10:13]
	s_waitcnt lgkmcnt(1)
	v_mfma_f32_16x16x32_bf16 v[112:115], v[178:181], v[138:141], v[114:117]
	v_mfma_f32_16x16x32_bf16 v[116:119], v[178:181], v[142:145], v[118:121]
	v_mfma_f32_16x16x32_bf16 v[22:25], v[178:181], v[146:149], v[122:125]
	v_mfma_f32_16x16x32_bf16 v[18:21], v[178:181], v[150:153], v[6:9]
	s_waitcnt lgkmcnt(0)
	v_mfma_f32_16x16x32_bf16 v[14:17], v[182:185], v[138:141], v[126:129]
	v_mfma_f32_16x16x32_bf16 v[10:13], v[182:185], v[142:145], v[130:133]
	v_mfma_f32_16x16x32_bf16 v[6:9], v[182:185], v[146:149], v[134:137]
	v_mfma_f32_16x16x32_bf16 v[2:5], v[182:185], v[150:153], v[2:5]
	v_mov_b32_e32 v27, v224
	s_movk_i32 s0, 0x210
	v_lshrrev_b32_e32 v120, 1, v27
	v_and_b32_e32 v31, 0x7fffff80, v27
	v_and_b32_e32 v120, 24, v120
	v_and_b32_e32 v29, 0x4f, v27
	v_lshl_or_b32 v31, v31, 1, v120
	v_pk_mul_f32 v[32:33], v[30:31], v[32:33] op_sel_hi:[0,1]
	v_pk_mul_f32 v[34:35], v[30:31], v[34:35] op_sel_hi:[0,1]
	v_mad_u32_u24 v29, v29, s0, v31
	v_cvt_pk_bf16_f32 v32, v32, v33
	v_cvt_pk_bf16_f32 v33, v34, v35
	v_pk_mul_f32 v[34:35], v[28:29], v[36:37] op_sel_hi:[0,1]
	v_pk_mul_f32 v[36:37], v[28:29], v[38:39] op_sel_hi:[0,1]
	v_cvt_pk_bf16_f32 v34, v34, v35
	v_cvt_pk_bf16_f32 v35, v36, v37
	v_pk_mul_f32 v[36:37], v[26:27], v[40:41] op_sel_hi:[0,1]
	v_pk_mul_f32 v[38:39], v[26:27], v[42:43] op_sel_hi:[0,1]
	v_cvt_pk_bf16_f32 v36, v36, v37
	v_cvt_pk_bf16_f32 v37, v38, v39
	v_pk_mul_f32 v[38:39], v[0:1], v[44:45] op_sel_hi:[0,1]
	v_pk_mul_f32 v[40:41], v[0:1], v[46:47] op_sel_hi:[0,1]
	v_cvt_pk_bf16_f32 v38, v38, v39
	v_cvt_pk_bf16_f32 v39, v40, v41
	v_pk_mul_f32 v[40:41], v[30:31], v[48:49] op_sel_hi:[0,1]
	v_pk_mul_f32 v[42:43], v[30:31], v[50:51] op_sel_hi:[0,1]
	v_cvt_pk_bf16_f32 v40, v40, v41
	v_cvt_pk_bf16_f32 v41, v42, v43
	s_barrier
	ds_write2_b64 v29, v[32:33], v[40:41] offset1:4
	v_pk_mul_f32 v[32:33], v[28:29], v[52:53] op_sel_hi:[0,1]
	v_pk_mul_f32 v[40:41], v[28:29], v[54:55] op_sel_hi:[0,1]
	v_cvt_pk_bf16_f32 v32, v32, v33
	v_cvt_pk_bf16_f32 v33, v40, v41
	v_add_u32_e32 v31, 0x2000, v29
	ds_write2_b64 v31, v[34:35], v[32:33] offset0:32 offset1:36
	v_pk_mul_f32 v[32:33], v[26:27], v[56:57] op_sel_hi:[0,1]
	v_pk_mul_f32 v[34:35], v[26:27], v[58:59] op_sel_hi:[0,1]
	v_cvt_pk_bf16_f32 v32, v32, v33
	v_cvt_pk_bf16_f32 v33, v34, v35
	v_add_u32_e32 v44, 0x4000, v29
	ds_write2_b64 v44, v[36:37], v[32:33] offset0:64 offset1:68
	v_pk_mul_f32 v[32:33], v[0:1], v[60:61] op_sel_hi:[0,1]
	v_pk_mul_f32 v[34:35], v[0:1], v[62:63] op_sel_hi:[0,1]
	v_cvt_pk_bf16_f32 v32, v32, v33
	v_cvt_pk_bf16_f32 v33, v34, v35
	v_add_u32_e32 v45, 0x6000, v29
	ds_write2_b64 v45, v[38:39], v[32:33] offset0:96 offset1:100
	v_pk_mul_f32 v[32:33], v[30:31], v[64:65] op_sel_hi:[0,1]
	v_pk_mul_f32 v[34:35], v[30:31], v[66:67] op_sel_hi:[0,1]
	v_cvt_pk_bf16_f32 v32, v32, v33
	v_cvt_pk_bf16_f32 v33, v34, v35
	v_pk_mul_f32 v[34:35], v[28:29], v[68:69] op_sel_hi:[0,1]
	v_pk_mul_f32 v[36:37], v[28:29], v[70:71] op_sel_hi:[0,1]
	v_cvt_pk_bf16_f32 v34, v34, v35
	v_cvt_pk_bf16_f32 v35, v36, v37
	v_pk_mul_f32 v[36:37], v[26:27], v[72:73] op_sel_hi:[0,1]
	v_pk_mul_f32 v[38:39], v[26:27], v[74:75] op_sel_hi:[0,1]
	v_cvt_pk_bf16_f32 v36, v36, v37
	v_cvt_pk_bf16_f32 v37, v38, v39
	v_pk_mul_f32 v[38:39], v[0:1], v[154:155] op_sel_hi:[0,1]
	v_pk_mul_f32 v[40:41], v[0:1], v[156:157] op_sel_hi:[0,1]
	v_cvt_pk_bf16_f32 v38, v38, v39
	v_cvt_pk_bf16_f32 v39, v40, v41
	v_pk_mul_f32 v[40:41], v[30:31], v[76:77] op_sel_hi:[0,1]
	v_pk_mul_f32 v[42:43], v[30:31], v[78:79] op_sel_hi:[0,1]
	v_cvt_pk_bf16_f32 v40, v40, v41
	v_cvt_pk_bf16_f32 v41, v42, v43
	ds_write2_b64 v29, v[32:33], v[40:41] offset0:8 offset1:12
	v_pk_mul_f32 v[32:33], v[28:29], v[80:81] op_sel_hi:[0,1]
	v_pk_mul_f32 v[40:41], v[28:29], v[82:83] op_sel_hi:[0,1]
	v_cvt_pk_bf16_f32 v32, v32, v33
	v_cvt_pk_bf16_f32 v33, v40, v41
	ds_write2_b64 v31, v[34:35], v[32:33] offset0:40 offset1:44
	v_pk_mul_f32 v[32:33], v[26:27], v[84:85] op_sel_hi:[0,1]
	v_pk_mul_f32 v[34:35], v[26:27], v[86:87] op_sel_hi:[0,1]
	v_cvt_pk_bf16_f32 v32, v32, v33
	v_cvt_pk_bf16_f32 v33, v34, v35
	ds_write2_b64 v44, v[36:37], v[32:33] offset0:72 offset1:76
	v_pk_mul_f32 v[32:33], v[0:1], v[158:159] op_sel_hi:[0,1]
	v_pk_mul_f32 v[34:35], v[0:1], v[160:161] op_sel_hi:[0,1]
	v_cvt_pk_bf16_f32 v32, v32, v33
	v_cvt_pk_bf16_f32 v33, v34, v35
	ds_write2_b64 v45, v[38:39], v[32:33] offset0:104 offset1:108
	v_pk_mul_f32 v[32:33], v[30:31], v[88:89] op_sel_hi:[0,1]
	v_pk_mul_f32 v[34:35], v[30:31], v[90:91] op_sel_hi:[0,1]
	v_cvt_pk_bf16_f32 v32, v32, v33
	v_cvt_pk_bf16_f32 v33, v34, v35
	v_pk_mul_f32 v[34:35], v[28:29], v[92:93] op_sel_hi:[0,1]
	v_pk_mul_f32 v[36:37], v[28:29], v[94:95] op_sel_hi:[0,1]
	v_cvt_pk_bf16_f32 v34, v34, v35
	v_cvt_pk_bf16_f32 v35, v36, v37
	v_pk_mul_f32 v[36:37], v[26:27], v[96:97] op_sel_hi:[0,1]
	v_pk_mul_f32 v[38:39], v[26:27], v[98:99] op_sel_hi:[0,1]
	v_cvt_pk_bf16_f32 v36, v36, v37
	v_cvt_pk_bf16_f32 v37, v38, v39
	v_pk_mul_f32 v[38:39], v[0:1], v[162:163] op_sel_hi:[0,1]
	v_pk_mul_f32 v[40:41], v[0:1], v[164:165] op_sel_hi:[0,1]
	v_cvt_pk_bf16_f32 v38, v38, v39
	v_cvt_pk_bf16_f32 v39, v40, v41
	v_pk_mul_f32 v[40:41], v[30:31], v[100:101] op_sel_hi:[0,1]
	v_pk_mul_f32 v[42:43], v[30:31], v[102:103] op_sel_hi:[0,1]
	v_cvt_pk_bf16_f32 v40, v40, v41
	v_cvt_pk_bf16_f32 v41, v42, v43
	ds_write2_b64 v29, v[32:33], v[40:41] offset0:16 offset1:20
	v_pk_mul_f32 v[32:33], v[28:29], v[104:105] op_sel_hi:[0,1]
	v_pk_mul_f32 v[40:41], v[28:29], v[106:107] op_sel_hi:[0,1]
	v_cvt_pk_bf16_f32 v32, v32, v33
	v_cvt_pk_bf16_f32 v33, v40, v41
	ds_write2_b64 v31, v[34:35], v[32:33] offset0:48 offset1:52
	v_pk_mul_f32 v[32:33], v[26:27], v[108:109] op_sel_hi:[0,1]
	v_pk_mul_f32 v[34:35], v[26:27], v[110:111] op_sel_hi:[0,1]
	v_cvt_pk_bf16_f32 v32, v32, v33
	v_cvt_pk_bf16_f32 v33, v34, v35
	ds_write2_b64 v44, v[36:37], v[32:33] offset0:80 offset1:84
	v_pk_mul_f32 v[32:33], v[0:1], v[166:167] op_sel_hi:[0,1]
	v_pk_mul_f32 v[34:35], v[0:1], v[168:169] op_sel_hi:[0,1]
	v_cvt_pk_bf16_f32 v32, v32, v33
	v_cvt_pk_bf16_f32 v33, v34, v35
	v_pk_mul_f32 v[18:19], v[0:1], v[18:19] op_sel_hi:[0,1]
	v_pk_mul_f32 v[20:21], v[0:1], v[20:21] op_sel_hi:[0,1]
	v_pk_mul_f32 v[2:3], v[0:1], v[2:3] op_sel_hi:[0,1]
	v_pk_mul_f32 v[4:5], v[0:1], v[4:5] op_sel_hi:[0,1]
	v_lshlrev_b32_e32 v0, 3, v27
	ds_write2_b64 v45, v[38:39], v[32:33] offset0:112 offset1:116
	v_pk_mul_f32 v[32:33], v[30:31], v[112:113] op_sel_hi:[0,1]
	v_pk_mul_f32 v[34:35], v[30:31], v[114:115] op_sel_hi:[0,1]
	v_cvt_pk_bf16_f32 v18, v18, v19
	v_cvt_pk_bf16_f32 v19, v20, v21
	v_cvt_pk_bf16_f32 v2, v2, v3
	v_cvt_pk_bf16_f32 v3, v4, v5
	v_and_b32_e32 v0, 0xf8, v0
	v_cvt_pk_bf16_f32 v32, v32, v33
	v_cvt_pk_bf16_f32 v33, v34, v35
	v_pk_mul_f32 v[34:35], v[28:29], v[116:117] op_sel_hi:[0,1]
	v_pk_mul_f32 v[36:37], v[28:29], v[118:119] op_sel_hi:[0,1]
	v_pk_mul_f32 v[22:23], v[26:27], v[22:23] op_sel_hi:[0,1]
	v_pk_mul_f32 v[24:25], v[26:27], v[24:25] op_sel_hi:[0,1]
	v_pk_mul_f32 v[14:15], v[30:31], v[14:15] op_sel_hi:[0,1]
	v_pk_mul_f32 v[16:17], v[30:31], v[16:17] op_sel_hi:[0,1]
	v_pk_mul_f32 v[10:11], v[28:29], v[10:11] op_sel_hi:[0,1]
	v_pk_mul_f32 v[12:13], v[28:29], v[12:13] op_sel_hi:[0,1]
	v_pk_mul_f32 v[6:7], v[26:27], v[6:7] op_sel_hi:[0,1]
	v_pk_mul_f32 v[8:9], v[26:27], v[8:9] op_sel_hi:[0,1]
	ds_write2_b64 v45, v[18:19], v[2:3] offset0:120 offset1:124
	v_or_b32_e32 v2, s82, v0
	s_movk_i32 s0, 0x800
	v_cvt_pk_bf16_f32 v34, v34, v35
	v_cvt_pk_bf16_f32 v35, v36, v37
	v_cvt_pk_bf16_f32 v22, v22, v23
	v_cvt_pk_bf16_f32 v23, v24, v25
	v_cvt_pk_bf16_f32 v14, v14, v15
	v_cvt_pk_bf16_f32 v15, v16, v17
	v_cvt_pk_bf16_f32 v10, v10, v11
	v_cvt_pk_bf16_f32 v11, v12, v13
	v_cvt_pk_bf16_f32 v6, v6, v7
	v_cvt_pk_bf16_f32 v7, v8, v9
	v_cmp_gt_i32_e64 s[44:45], s0, v2
	s_mov_b64 s[12:13], 12
	s_mov_b64 s[40:41], s[54:55]
	s_mov_b32 s0, s82
	ds_write2_b64 v29, v[32:33], v[14:15] offset0:24 offset1:28
	ds_write2_b64 v31, v[34:35], v[10:11] offset0:56 offset1:60
	ds_write2_b64 v44, v[22:23], v[6:7] offset0:88 offset1:92
	s_waitcnt lgkmcnt(0)
	s_barrier

.LBB0_118:
	s_or_b64 exec, exec, s[0:1]
	s_waitcnt vmcnt(1)
	v_mov_b32_e32 v14, v224
	s_lshl_b32 s0, s87, 8
	v_readfirstlane_b32 s42, v14
	v_bfe_u32 v15, v14, 4, 2
	v_sub_u32_e32 v16, 0, v15
	s_and_b32 s13, s42, 0xffffffc0
	v_bfe_u32 v10, v14, 2, 4
	v_xor_b32_e32 v0, v14, v16
	s_add_i32 s13, s13, s0
	v_or_b32_e32 v11, s13, v10
	v_lshlrev_b32_e32 v0, 4, v0
	s_lshl_b32 s12, s88, 7
	s_ashr_i32 s43, s42, 6
	v_and_b32_e32 v0, 48, v0
	v_min_i32_e32 v4, 0x3ff, v11
	v_or_b32_e32 v6, 16, v11
	v_or_b32_e32 v8, 32, v11
	v_or_b32_e32 v11, 48, v11
	v_lshl_add_u64 v[2:3], s[46:47], 0, v[0:1]
	v_min_i32_e32 v6, 0x3ff, v6
	v_min_i32_e32 v8, 0x3ff, v8
	v_min_i32_e32 v11, 0x3ff, v11
	s_lshl_b32 s13, s43, 1
	v_or_b32_e32 v17, s12, v10
	v_mad_i64_i32 v[4:5], s[14:15], v4, s19, v[2:3]
	v_mad_i64_i32 v[6:7], s[14:15], v6, s19, v[2:3]
	v_mad_i64_i32 v[8:9], s[14:15], v8, s19, v[2:3]
	v_mad_i64_i32 v[2:3], s[14:15], v11, s19, v[2:3]
	v_lshl_add_u64 v[10:11], s[4:5], 0, v[0:1]
	v_lshl_add_u32 v0, s43, 5, v17
	s_movk_i32 s69, 0xac0
	s_lshl_b32 s68, s13, 10
	s_or_b32 s13, s13, 1
	v_mad_i64_i32 v[130:131], s[14:15], v0, s69, 0
	v_lshl_add_u32 v0, s13, 4, v17
	s_waitcnt vmcnt(0)
	s_barrier
	v_lshl_add_u64 v[12:13], v[130:131], 1, v[10:11]
	s_mov_b32 s14, m0
	s_mov_b32 m0, s68
	s_nop 0
	global_load_lds_dwordx4 v[12:13], off
	s_mov_b32 m0, s14
	s_lshl_b32 s13, s13, 10
	v_mad_i64_i32 v[132:133], s[14:15], v0, s69, 0
	v_lshl_add_u64 v[10:11], v[132:133], 1, v[10:11]
	s_mov_b32 s14, m0
	s_mov_b32 m0, s13
	s_nop 0
	global_load_lds_dwordx4 v[10:11], off
	s_mov_b32 m0, s14
	s_lshl_b32 s15, s43, 12
	s_add_i32 s14, s15, 0x2000
	s_mov_b32 s69, m0
	s_mov_b32 m0, s14
	s_nop 0
	global_load_lds_dwordx4 v[4:5], off
	s_mov_b32 m0, s69
	s_add_i32 s69, s15, 0x2400
	s_mov_b32 s70, m0
	s_mov_b32 m0, s69
	s_nop 0
	global_load_lds_dwordx4 v[6:7], off
	s_mov_b32 m0, s70
	s_add_i32 s69, s15, 0x2800
	s_mov_b32 s70, m0
	s_mov_b32 m0, s69
	s_nop 0
	global_load_lds_dwordx4 v[8:9], off
	s_mov_b32 m0, s70
	s_add_i32 s69, s15, 0x2c00
	s_mov_b32 s70, m0
	s_mov_b32 m0, s69
	s_nop 0
	global_load_lds_dwordx4 v[2:3], off
	s_mov_b32 m0, s70
	v_lshl_add_u64 v[12:13], v[12:13], 0, 64
	s_addk_i32 s68, 0x6000
	s_mov_b32 s69, m0
	s_mov_b32 m0, s68
	s_nop 0
	global_load_lds_dwordx4 v[12:13], off
	s_mov_b32 m0, s69
	v_lshl_add_u64 v[10:11], v[10:11], 0, 64
	s_add_i32 s68, s13, 0x6000
	s_mov_b32 s69, m0
	s_mov_b32 m0, s68
	s_nop 0
	global_load_lds_dwordx4 v[10:11], off
	s_mov_b32 m0, s69
	v_lshl_add_u64 v[10:11], v[4:5], 0, 64
	s_add_i32 s68, s15, 0x8000
	s_mov_b32 s69, m0
	s_mov_b32 m0, s68
	s_nop 0
	global_load_lds_dwordx4 v[10:11], off
	s_mov_b32 m0, s69
	v_lshrrev_b32_e32 v0, 2, v14
	v_lshl_add_u64 v[10:11], v[6:7], 0, 64
	s_add_i32 s68, s15, 0x8400
	s_mov_b32 s69, m0
	s_mov_b32 m0, s68
	s_nop 0
	global_load_lds_dwordx4 v[10:11], off
	s_mov_b32 m0, s69
	v_sub_u32_e32 v0, 0, v0
	v_lshl_add_u64 v[10:11], v[8:9], 0, 64
	s_add_i32 s68, s15, 0x8800
	s_mov_b32 s69, m0
	s_mov_b32 m0, s68
	s_nop 0
	global_load_lds_dwordx4 v[10:11], off
	s_mov_b32 m0, s69
	s_add_i32 s15, s15, 0x8c00
	v_bitop3_b32 v0, v15, v0, 3 bitop3:0x78
	v_lshl_add_u64 v[10:11], v[2:3], 0, 64
	s_mov_b32 s68, m0
	s_mov_b32 m0, s15
	s_nop 0
	global_load_lds_dwordx4 v[10:11], off
	s_mov_b32 m0, s68
	v_lshlrev_b32_e32 v144, 4, v0
	v_and_b32_e32 v0, 15, v14
	s_and_b32 s15, s42, 0x3ffff80
	v_and_or_b32 v10, s42, 64, v0
	v_or_b32_e32 v0, s15, v0
	v_lshlrev_b32_e32 v145, 6, v0
	v_bitop3_b32 v0, v14, 3, v16 bitop3:0x48
	v_lshl_add_u64 v[134:135], v[2:3], 0, s[6:7]
	v_lshlrev_b32_e32 v0, 4, v0
	v_mov_b32_e32 v2, 0
	s_mov_b32 s1, 0
	v_lshlrev_b32_e32 v146, 6, v10
	s_lshl_b32 s15, s43, 11
	v_lshl_add_u64 v[136:137], v[8:9], 0, s[6:7]
	v_lshl_add_u64 v[138:139], v[6:7], 0, s[6:7]
	v_lshl_add_u64 v[140:141], v[4:5], 0, s[6:7]
	v_lshl_add_u64 v[142:143], s[56:57], 0, v[0:1]
	s_mov_b64 s[42:43], 0
	v_mov_b32_e32 v3, v2
	v_mov_b32_e32 v4, v2
	v_mov_b32_e32 v5, v2
	v_mov_b32_e32 v6, v2
	v_mov_b32_e32 v7, v2
	v_mov_b32_e32 v8, v2
	v_mov_b32_e32 v9, v2
	v_mov_b32_e32 v10, v2
	v_mov_b32_e32 v11, v2
	v_mov_b32_e32 v12, v2
	v_mov_b32_e32 v13, v2
	v_mov_b32_e32 v14, v2
	v_mov_b32_e32 v15, v2
	v_mov_b32_e32 v16, v2
	v_mov_b32_e32 v17, v2
	s_waitcnt vmcnt(21)
	v_mov_b32_e32 v18, v2
	v_mov_b32_e32 v19, v2
	v_mov_b32_e32 v20, v2
	v_mov_b32_e32 v21, v2
	s_waitcnt vmcnt(20)
	v_mov_b32_e32 v22, v2
	v_mov_b32_e32 v23, v2
	v_mov_b32_e32 v24, v2
	v_mov_b32_e32 v25, v2
	v_mov_b32_e32 v26, v2
	v_mov_b32_e32 v27, v2
	v_mov_b32_e32 v28, v2
	v_mov_b32_e32 v29, v2
	s_waitcnt vmcnt(19)
	v_mov_b32_e32 v30, v2
	v_mov_b32_e32 v31, v2
	v_mov_b32_e32 v32, v2
	v_mov_b32_e32 v33, v2
	v_mov_b32_e32 v34, v2
	v_mov_b32_e32 v35, v2
	v_mov_b32_e32 v36, v2
	v_mov_b32_e32 v37, v2
	v_mov_b32_e32 v38, v2
	v_mov_b32_e32 v39, v2
	v_mov_b32_e32 v40, v2
	v_mov_b32_e32 v41, v2
	s_waitcnt vmcnt(18)
	v_mov_b32_e32 v42, v2
	v_mov_b32_e32 v43, v2
	v_mov_b32_e32 v44, v2
	v_mov_b32_e32 v45, v2
	s_waitcnt vmcnt(0)
	v_mov_b32_e32 v46, v2
	v_mov_b32_e32 v47, v2
	v_mov_b32_e32 v48, v2
	v_mov_b32_e32 v49, v2
	s_waitcnt vmcnt(17)
	v_mov_b32_e32 v50, v2
	v_mov_b32_e32 v51, v2
	v_mov_b32_e32 v52, v2
	v_mov_b32_e32 v53, v2
	v_mov_b32_e32 v54, v2
	v_mov_b32_e32 v55, v2
	v_mov_b32_e32 v56, v2
	v_mov_b32_e32 v57, v2
	v_mov_b32_e32 v58, v2
	v_mov_b32_e32 v59, v2
	v_mov_b32_e32 v60, v2
	v_mov_b32_e32 v61, v2
	s_waitcnt vmcnt(16)
	v_mov_b32_e32 v62, v2
	v_mov_b32_e32 v63, v2
	v_mov_b32_e32 v64, v2
	v_mov_b32_e32 v65, v2
	v_mov_b32_e32 v66, v2
	v_mov_b32_e32 v67, v2
	v_mov_b32_e32 v68, v2
	v_mov_b32_e32 v69, v2
	v_mov_b32_e32 v70, v2
	v_mov_b32_e32 v71, v2
	v_mov_b32_e32 v72, v2
	v_mov_b32_e32 v73, v2
	v_mov_b32_e32 v74, v2
	v_mov_b32_e32 v75, v2
	v_mov_b32_e32 v76, v2
	v_mov_b32_e32 v77, v2
	v_mov_b32_e32 v78, v2
	v_mov_b32_e32 v79, v2
	v_mov_b32_e32 v80, v2
	v_mov_b32_e32 v81, v2
	v_mov_b32_e32 v82, v2
	v_mov_b32_e32 v83, v2
	v_mov_b32_e32 v84, v2
	v_mov_b32_e32 v85, v2
	v_mov_b32_e32 v86, v2
	v_mov_b32_e32 v87, v2
	v_mov_b32_e32 v88, v2
	v_mov_b32_e32 v89, v2
	v_mov_b32_e32 v90, v2
	v_mov_b32_e32 v91, v2
	v_mov_b32_e32 v92, v2
	v_mov_b32_e32 v93, v2
	v_mov_b32_e32 v94, v2
	v_mov_b32_e32 v95, v2
	v_mov_b32_e32 v96, v2
	v_mov_b32_e32 v97, v2
	v_mov_b32_e32 v98, v2
	v_mov_b32_e32 v99, v2
	v_mov_b32_e32 v100, v2
	v_mov_b32_e32 v101, v2
	v_mov_b32_e32 v102, v2
	v_mov_b32_e32 v103, v2
	v_mov_b32_e32 v104, v2
	v_mov_b32_e32 v105, v2
	v_mov_b32_e32 v106, v2
	v_mov_b32_e32 v107, v2
	v_mov_b32_e32 v108, v2
	v_mov_b32_e32 v109, v2
	v_mov_b32_e32 v110, v2
	v_mov_b32_e32 v111, v2
	v_mov_b32_e32 v112, v2
	v_mov_b32_e32 v113, v2
	v_mov_b32_e32 v114, v2
	v_mov_b32_e32 v115, v2
	v_mov_b32_e32 v116, v2
	v_mov_b32_e32 v117, v2
	v_mov_b32_e32 v118, v2
	v_mov_b32_e32 v119, v2
	v_mov_b32_e32 v120, v2
	v_mov_b32_e32 v121, v2
	v_mov_b32_e32 v122, v2
	v_mov_b32_e32 v123, v2
	v_mov_b32_e32 v124, v2
	v_mov_b32_e32 v125, v2
	v_mov_b32_e32 v126, v2
	v_mov_b32_e32 v127, v2
	v_mov_b32_e32 v128, v2
	v_mov_b32_e32 v129, v2
	v_lshl_add_u64 v[130:131], v[130:131], 1, v[142:143]
	v_lshl_add_u64 v[132:133], v[132:133], 1, v[142:143]
.LBB0_119:
	s_mul_i32 s68, s1, 0x6000
	s_add_i32 s69, s68, 0xffffa000
	s_cmp_gt_i32 s1, 0
	s_waitcnt vmcnt(6)
	s_cselect_b32 s69, s69, 0xc000
	s_waitcnt lgkmcnt(0)
	s_barrier
	s_setprio 2
	v_or_b32_e32 v0, s68, v146
	v_add_u32_e32 v0, v0, v144
	v_add3_u32 v212, s68, v145, v144
	ds_read_b128 v[164:167], v212 offset:8192
	ds_read_b128 v[148:151], v0
	ds_read_b128 v[152:155], v0 offset:1024
	ds_read_b128 v[156:159], v0 offset:2048
	ds_read_b128 v[160:163], v0 offset:3072
	ds_read_b128 v[168:171], v212 offset:9216
	ds_read_b128 v[172:175], v212 offset:10240
	ds_read_b128 v[176:179], v212 offset:11264
	ds_read_b128 v[180:183], v212 offset:12288
	ds_read_b128 v[184:187], v212 offset:13312
	ds_read_b128 v[188:191], v212 offset:14336
	ds_read_b128 v[192:195], v212 offset:15360
	s_add_i32 s70, s69, s15
	s_mov_b32 m0, s70
	s_nop 0
	global_load_lds_dwordx4 v[130:131], off
	s_add_i32 s70, s69, s13
	s_mov_b32 m0, s70
	s_nop 0
	global_load_lds_dwordx4 v[132:133], off
	s_add_i32 s69, s14, s69
	s_mov_b32 m0, s69
	s_nop 0
	global_load_lds_dwordx4 v[140:141], off
	s_add_i32 s70, s69, 0x400
	s_mov_b32 m0, s70
	s_nop 0
	global_load_lds_dwordx4 v[138:139], off
	s_add_i32 s70, s69, 0x800
	s_mov_b32 m0, s70
	s_nop 0
	global_load_lds_dwordx4 v[136:137], off
	s_addk_i32 s69, 0xc00
	s_mov_b32 m0, s69
	s_nop 0
	global_load_lds_dwordx4 v[134:135], off
	s_setprio 0
	s_waitcnt lgkmcnt(10)
	v_mfma_f32_16x16x32_bf16 v[126:129], v[164:167], v[148:151], v[126:129]
	s_waitcnt lgkmcnt(9)
	v_mfma_f32_16x16x32_bf16 v[122:125], v[164:167], v[152:155], v[122:125]
	s_waitcnt lgkmcnt(8)
	v_mfma_f32_16x16x32_bf16 v[118:121], v[164:167], v[156:159], v[118:121]
	s_waitcnt lgkmcnt(7)
	v_mfma_f32_16x16x32_bf16 v[114:117], v[164:167], v[160:163], v[114:117]
	s_waitcnt lgkmcnt(6)
	v_mfma_f32_16x16x32_bf16 v[110:113], v[168:171], v[148:151], v[110:113]
	v_mfma_f32_16x16x32_bf16 v[106:109], v[168:171], v[152:155], v[106:109]
	v_lshl_add_u64 v[130:131], v[130:131], 0, 64
	v_mfma_f32_16x16x32_bf16 v[102:105], v[168:171], v[156:159], v[102:105]
	v_mfma_f32_16x16x32_bf16 v[98:101], v[168:171], v[160:163], v[98:101]
	s_waitcnt lgkmcnt(5)
	v_mfma_f32_16x16x32_bf16 v[94:97], v[172:175], v[148:151], v[94:97]
	v_mfma_f32_16x16x32_bf16 v[90:93], v[172:175], v[152:155], v[90:93]
	v_lshl_add_u64 v[132:133], v[132:133], 0, 64
	v_mfma_f32_16x16x32_bf16 v[86:89], v[172:175], v[156:159], v[86:89]
	v_mfma_f32_16x16x32_bf16 v[82:85], v[172:175], v[160:163], v[82:85]
	s_waitcnt lgkmcnt(4)
	v_mfma_f32_16x16x32_bf16 v[78:81], v[176:179], v[148:151], v[78:81]
	v_mfma_f32_16x16x32_bf16 v[74:77], v[176:179], v[152:155], v[74:77]
	v_lshl_add_u64 v[140:141], v[140:141], 0, 64
	v_mfma_f32_16x16x32_bf16 v[70:73], v[176:179], v[156:159], v[70:73]
	v_mfma_f32_16x16x32_bf16 v[66:69], v[176:179], v[160:163], v[66:69]
	s_waitcnt lgkmcnt(3)
	v_mfma_f32_16x16x32_bf16 v[62:65], v[180:183], v[148:151], v[62:65]
	v_mfma_f32_16x16x32_bf16 v[58:61], v[180:183], v[152:155], v[58:61]
	v_lshl_add_u64 v[138:139], v[138:139], 0, 64
	v_mfma_f32_16x16x32_bf16 v[54:57], v[180:183], v[156:159], v[54:57]
	v_mfma_f32_16x16x32_bf16 v[50:53], v[180:183], v[160:163], v[50:53]
	s_waitcnt lgkmcnt(2)
	v_mfma_f32_16x16x32_bf16 v[46:49], v[184:187], v[148:151], v[46:49]
	v_mfma_f32_16x16x32_bf16 v[42:45], v[184:187], v[152:155], v[42:45]
	v_lshl_add_u64 v[136:137], v[136:137], 0, 64
	v_mfma_f32_16x16x32_bf16 v[38:41], v[184:187], v[156:159], v[38:41]
	v_mfma_f32_16x16x32_bf16 v[34:37], v[184:187], v[160:163], v[34:37]
	s_waitcnt lgkmcnt(1)
	v_mfma_f32_16x16x32_bf16 v[30:33], v[188:191], v[148:151], v[30:33]
	v_mfma_f32_16x16x32_bf16 v[26:29], v[188:191], v[152:155], v[26:29]
	v_lshl_add_u64 v[134:135], v[134:135], 0, 64
	v_mfma_f32_16x16x32_bf16 v[22:25], v[188:191], v[156:159], v[22:25]
	v_mfma_f32_16x16x32_bf16 v[18:21], v[188:191], v[160:163], v[18:21]
	s_waitcnt lgkmcnt(0)
	v_mfma_f32_16x16x32_bf16 v[14:17], v[192:195], v[148:151], v[14:17]
	v_mfma_f32_16x16x32_bf16 v[10:13], v[192:195], v[152:155], v[10:13]
	v_mfma_f32_16x16x32_bf16 v[6:9], v[192:195], v[156:159], v[6:9]
	v_mfma_f32_16x16x32_bf16 v[2:5], v[192:195], v[160:163], v[2:5]
	s_add_i32 s68, s1, 1
	s_cmp_lg_u32 s1, 2
	s_cselect_b32 s1, s68, 0
	s_add_u32 s42, s42, 64
	s_addc_u32 s43, s43, 0
	s_cmpk_eq_i32 s42, 0x1500
	s_cbranch_scc0 .LBB0_119
	s_waitcnt vmcnt(6)
	v_add_u32_e32 v0, v146, v144
	v_add_u32_e32 v221, v145, v144
	s_waitcnt lgkmcnt(0)
	s_barrier
	ds_read_b128 v[130:133], v0
	ds_read_b128 v[134:137], v0 offset:1024
	ds_read_b128 v[138:141], v0 offset:2048
	ds_read_b128 v[146:149], v0 offset:3072
	ds_read_b128 v[142:145], v221 offset:8192
	ds_read_b128 v[150:153], v221 offset:9216
	ds_read_b128 v[154:157], v221 offset:10240
	ds_read_b128 v[158:161], v221 offset:11264
	ds_read_b128 v[162:165], v221 offset:12288
	ds_read_b128 v[166:169], v221 offset:13312
	ds_read_b128 v[170:173], v221 offset:14336
	ds_read_b128 v[174:177], v221 offset:15360
	s_waitcnt lgkmcnt(7)
	v_mfma_f32_16x16x32_bf16 v[126:129], v[142:145], v[130:133], v[126:129]
	v_mfma_f32_16x16x32_bf16 v[122:125], v[142:145], v[134:137], v[122:125]
	v_mfma_f32_16x16x32_bf16 v[118:121], v[142:145], v[138:141], v[118:121]
	v_mfma_f32_16x16x32_bf16 v[114:117], v[142:145], v[146:149], v[114:117]
	s_waitcnt lgkmcnt(6)
	v_mfma_f32_16x16x32_bf16 v[110:113], v[150:153], v[130:133], v[110:113]
	v_mfma_f32_16x16x32_bf16 v[106:109], v[150:153], v[134:137], v[106:109]
	v_mfma_f32_16x16x32_bf16 v[102:105], v[150:153], v[138:141], v[102:105]
	v_mfma_f32_16x16x32_bf16 v[98:101], v[150:153], v[146:149], v[98:101]
	s_waitcnt lgkmcnt(5)
	v_mfma_f32_16x16x32_bf16 v[94:97], v[154:157], v[130:133], v[94:97]
	v_mfma_f32_16x16x32_bf16 v[90:93], v[154:157], v[134:137], v[90:93]
	v_mfma_f32_16x16x32_bf16 v[86:89], v[154:157], v[138:141], v[86:89]
	v_mfma_f32_16x16x32_bf16 v[82:85], v[154:157], v[146:149], v[82:85]
	s_waitcnt lgkmcnt(4)
	v_mfma_f32_16x16x32_bf16 v[78:81], v[158:161], v[130:133], v[78:81]
	v_mfma_f32_16x16x32_bf16 v[74:77], v[158:161], v[134:137], v[74:77]
	v_mfma_f32_16x16x32_bf16 v[70:73], v[158:161], v[138:141], v[70:73]
	v_mfma_f32_16x16x32_bf16 v[66:69], v[158:161], v[146:149], v[66:69]
	s_waitcnt lgkmcnt(3)
	v_mfma_f32_16x16x32_bf16 v[142:145], v[162:165], v[130:133], v[62:65]
	v_mfma_f32_16x16x32_bf16 v[150:153], v[162:165], v[134:137], v[58:61]
	v_mfma_f32_16x16x32_bf16 v[154:157], v[162:165], v[138:141], v[54:57]
	v_mfma_f32_16x16x32_bf16 v[158:161], v[162:165], v[146:149], v[50:53]
	s_waitcnt lgkmcnt(2)
	v_mfma_f32_16x16x32_bf16 v[162:165], v[166:169], v[130:133], v[46:49]
	v_mfma_f32_16x16x32_bf16 v[178:181], v[166:169], v[134:137], v[42:45]
	v_mfma_f32_16x16x32_bf16 v[182:185], v[166:169], v[138:141], v[38:41]
	v_mfma_f32_16x16x32_bf16 v[166:169], v[166:169], v[146:149], v[34:37]
	s_waitcnt lgkmcnt(1)
	v_mfma_f32_16x16x32_bf16 v[186:189], v[170:173], v[130:133], v[30:33]
	v_mfma_f32_16x16x32_bf16 v[190:193], v[170:173], v[134:137], v[26:29]
	v_mfma_f32_16x16x32_bf16 v[194:197], v[170:173], v[138:141], v[22:25]
	v_mfma_f32_16x16x32_bf16 v[170:173], v[170:173], v[146:149], v[18:21]
	s_waitcnt lgkmcnt(0)
	v_mfma_f32_16x16x32_bf16 v[130:133], v[174:177], v[130:133], v[14:17]
	v_mfma_f32_16x16x32_bf16 v[134:137], v[174:177], v[134:137], v[10:13]
	v_mfma_f32_16x16x32_bf16 v[138:141], v[174:177], v[138:141], v[6:9]
	v_mfma_f32_16x16x32_bf16 v[146:149], v[174:177], v[146:149], v[2:5]
	s_waitcnt vmcnt(0)
	s_waitcnt lgkmcnt(0)
	s_barrier
	ds_read_b128 v[174:177], v0 offset:24576
	ds_read_b128 v[198:201], v0 offset:25600
	ds_read_b128 v[202:205], v0 offset:26624
	ds_read_b128 v[206:209], v0 offset:27648
	ds_read_b128 v[14:17], v221 offset:32768
	ds_read_b128 v[30:33], v221 offset:33792
	ds_read_b128 v[46:49], v221 offset:34816
	ds_read_b128 v[62:65], v221 offset:35840
	ds_read_b128 v[210:213], v221 offset:36864
	ds_read_b128 v[216:219], v221 offset:37888
	ds_read_b128 v[226:229], v221 offset:38912
	ds_read_b128 v[230:233], v221 offset:39936
	s_waitcnt lgkmcnt(7)
	v_mfma_f32_16x16x32_bf16 v[2:5], v[14:17], v[174:177], v[126:129]
	v_mfma_f32_16x16x32_bf16 v[6:9], v[14:17], v[198:201], v[122:125]
	v_mfma_f32_16x16x32_bf16 v[10:13], v[14:17], v[202:205], v[118:121]
	v_mfma_f32_16x16x32_bf16 v[14:17], v[14:17], v[206:209], v[114:117]
	s_waitcnt lgkmcnt(6)
	v_mfma_f32_16x16x32_bf16 v[18:21], v[30:33], v[174:177], v[110:113]
	v_mfma_f32_16x16x32_bf16 v[22:25], v[30:33], v[198:201], v[106:109]
	v_mfma_f32_16x16x32_bf16 v[26:29], v[30:33], v[202:205], v[102:105]
	v_mfma_f32_16x16x32_bf16 v[30:33], v[30:33], v[206:209], v[98:101]
	s_waitcnt lgkmcnt(5)
	v_mfma_f32_16x16x32_bf16 v[34:37], v[46:49], v[174:177], v[94:97]
	v_mfma_f32_16x16x32_bf16 v[38:41], v[46:49], v[198:201], v[90:93]
	v_mfma_f32_16x16x32_bf16 v[42:45], v[46:49], v[202:205], v[86:89]
	v_mfma_f32_16x16x32_bf16 v[46:49], v[46:49], v[206:209], v[82:85]
	s_waitcnt lgkmcnt(4)
	v_mfma_f32_16x16x32_bf16 v[50:53], v[62:65], v[174:177], v[78:81]
	v_mfma_f32_16x16x32_bf16 v[54:57], v[62:65], v[198:201], v[74:77]
	v_mfma_f32_16x16x32_bf16 v[58:61], v[62:65], v[202:205], v[70:73]
	v_mfma_f32_16x16x32_bf16 v[62:65], v[62:65], v[206:209], v[66:69]
	s_waitcnt lgkmcnt(3)
	v_mfma_f32_16x16x32_bf16 v[66:69], v[210:213], v[174:177], v[142:145]
	v_mfma_f32_16x16x32_bf16 v[70:73], v[210:213], v[198:201], v[150:153]
	v_mfma_f32_16x16x32_bf16 v[74:77], v[210:213], v[202:205], v[154:157]
	v_mfma_f32_16x16x32_bf16 v[78:81], v[210:213], v[206:209], v[158:161]
	s_waitcnt lgkmcnt(2)
	v_mfma_f32_16x16x32_bf16 v[82:85], v[216:219], v[174:177], v[162:165]
	v_mfma_f32_16x16x32_bf16 v[86:89], v[216:219], v[198:201], v[178:181]
	v_mfma_f32_16x16x32_bf16 v[90:93], v[216:219], v[202:205], v[182:185]
	v_mfma_f32_16x16x32_bf16 v[94:97], v[216:219], v[206:209], v[166:169]
	s_waitcnt lgkmcnt(1)
	v_mfma_f32_16x16x32_bf16 v[98:101], v[226:229], v[174:177], v[186:189]
	v_mfma_f32_16x16x32_bf16 v[102:105], v[226:229], v[198:201], v[190:193]
	v_mfma_f32_16x16x32_bf16 v[106:109], v[226:229], v[202:205], v[194:197]
	v_mfma_f32_16x16x32_bf16 v[110:113], v[226:229], v[206:209], v[170:173]
	s_waitcnt lgkmcnt(0)
	v_mfma_f32_16x16x32_bf16 v[114:117], v[230:233], v[174:177], v[130:133]
	v_mfma_f32_16x16x32_bf16 v[118:121], v[230:233], v[198:201], v[134:137]
	v_mfma_f32_16x16x32_bf16 v[122:125], v[230:233], v[202:205], v[138:141]
	v_mfma_f32_16x16x32_bf16 v[126:129], v[230:233], v[206:209], v[146:149]
	v_mov_b32_e32 v130, v224
	s_ashr_i32 s13, s12, 31
	v_and_b32_e32 v131, 31, v130
	v_ashrrev_i32_e32 v197, 7, v130
	v_ashrrev_i32_e32 v132, 5, v130
	v_lshlrev_b32_e32 v0, 2, v131
	s_lshl_b64 s[68:69], s[12:13], 11
	v_lshlrev_b32_e32 v164, 4, v131
	v_cmp_eq_u32_e64 s[42:43], 0, v131
	v_and_b32_e32 v131, 0x4f, v130
	v_and_b32_e32 v130, 48, v130
	s_movk_i32 s13, 0x210
	v_cmp_lt_i32_e32 vcc, v247, v214
	v_mad_u32_u24 v202, v131, s13, v130
	s_ashr_i32 s1, s0, 31
	v_cndmask_b32_e32 v130, v225, v247, vcc
	v_cmp_lt_i32_e32 vcc, v248, v214
	v_lshlrev_b32_e32 v203, 2, v130
	s_lshl_b32 s70, s87, 1
	v_cndmask_b32_e32 v130, v225, v248, vcc
	v_cmp_lt_i32_e32 vcc, v249, v214
	v_lshlrev_b32_e32 v204, 2, v130
	v_lshl_or_b32 v0, v132, 10, v0
	v_cndmask_b32_e32 v130, v225, v249, vcc
	v_cmp_lt_i32_e32 vcc, v223, v214
	v_lshlrev_b32_e32 v205, 2, v130
	v_mul_lo_u32 v165, v132, s13
	v_cndmask_b32_e32 v130, v225, v223, vcc
	v_cmp_lt_i32_e32 vcc, v252, v214
	v_lshlrev_b32_e32 v206, 2, v130
	s_mov_b32 s14, 0
	v_cndmask_b32_e32 v130, v225, v252, vcc
	v_lshlrev_b32_e32 v207, 2, v130
	v_add_u32_e32 v130, s12, v132
	v_ashrrev_i32_e32 v131, 31, v130
	s_add_u32 s12, s74, s68
	v_lshlrev_b64 v[132:133], 5, v[130:131]
	v_add_u32_e32 v134, 8, v130
	v_add_u32_e32 v136, 16, v130
	v_add_u32_e32 v138, 24, v130
	v_add_u32_e32 v140, 32, v130
	v_add_u32_e32 v142, 40, v130
	v_add_u32_e32 v144, 48, v130
	v_add_u32_e32 v146, 56, v130
	v_add_u32_e32 v148, 64, v130
	v_add_u32_e32 v150, 0x48, v130
	v_add_u32_e32 v152, 0x50, v130
	v_add_u32_e32 v154, 0x58, v130
	v_add_u32_e32 v156, 0x60, v130
	v_add_u32_e32 v158, 0x68, v130
	v_add_u32_e32 v160, 0x70, v130
	v_add_u32_e32 v130, 0x78, v130
	s_addc_u32 s13, s75, s69
	s_lshl_b64 s[0:1], s[0:1], 1
	v_ashrrev_i32_e32 v135, 31, v134
	v_ashrrev_i32_e32 v137, 31, v136
	v_ashrrev_i32_e32 v139, 31, v138
	v_ashrrev_i32_e32 v141, 31, v140
	v_ashrrev_i32_e32 v143, 31, v142
	v_ashrrev_i32_e32 v145, 31, v144
	v_ashrrev_i32_e32 v147, 31, v146
	v_ashrrev_i32_e32 v149, 31, v148
	v_ashrrev_i32_e32 v151, 31, v150
	v_ashrrev_i32_e32 v153, 31, v152
	v_ashrrev_i32_e32 v155, 31, v154
	v_ashrrev_i32_e32 v157, 31, v156
	v_ashrrev_i32_e32 v159, 31, v158
	v_ashrrev_i32_e32 v161, 31, v160
	v_ashrrev_i32_e32 v131, 31, v130
	s_add_u32 s0, s12, s0
	v_lshlrev_b64 v[134:135], 5, v[134:135]
	v_lshlrev_b64 v[136:137], 5, v[136:137]
	v_lshlrev_b64 v[138:139], 5, v[138:139]
	v_lshlrev_b64 v[140:141], 5, v[140:141]
	v_lshlrev_b64 v[142:143], 5, v[142:143]
	v_lshlrev_b64 v[144:145], 5, v[144:145]
	v_lshlrev_b64 v[146:147], 5, v[146:147]
	v_lshlrev_b64 v[148:149], 5, v[148:149]
	v_lshlrev_b64 v[150:151], 5, v[150:151]
	v_lshlrev_b64 v[152:153], 5, v[152:153]
	v_lshlrev_b64 v[154:155], 5, v[154:155]
	v_lshlrev_b64 v[156:157], 5, v[156:157]
	v_lshlrev_b64 v[158:159], 5, v[158:159]
	v_lshlrev_b64 v[160:161], 5, v[160:161]
	v_lshlrev_b64 v[162:163], 5, v[130:131]
	s_addc_u32 s1, s13, s1
	v_lshl_add_u64 v[130:131], v[0:1], 1, s[0:1]
	v_lshl_add_u64 v[132:133], s[44:45], 0, v[132:133]
	v_lshl_add_u64 v[134:135], s[44:45], 0, v[134:135]
	v_lshl_add_u64 v[136:137], s[44:45], 0, v[136:137]
	v_lshl_add_u64 v[138:139], s[44:45], 0, v[138:139]
	v_lshl_add_u64 v[140:141], s[44:45], 0, v[140:141]
	v_lshl_add_u64 v[142:143], s[44:45], 0, v[142:143]
	v_lshl_add_u64 v[144:145], s[44:45], 0, v[144:145]
	v_lshl_add_u64 v[146:147], s[44:45], 0, v[146:147]
	v_lshl_add_u64 v[148:149], s[44:45], 0, v[148:149]
	v_lshl_add_u64 v[150:151], s[44:45], 0, v[150:151]
	v_lshl_add_u64 v[152:153], s[44:45], 0, v[152:153]
	v_lshl_add_u64 v[154:155], s[44:45], 0, v[154:155]
	v_lshl_add_u64 v[156:157], s[44:45], 0, v[156:157]
	v_lshl_add_u64 v[158:159], s[44:45], 0, v[158:159]
	v_lshl_add_u64 v[160:161], s[44:45], 0, v[160:161]
	v_lshl_add_u64 v[162:163], s[44:45], 0, v[162:163]
	s_mov_b64 s[0:1], -1
	v_add_u32_e32 v0, v164, v165
	s_branch .LBB0_122

.LBB0_166:
	s_ashr_i32 s5, s4, 31
	s_lshr_b32 s5, s5, 28
	s_add_i32 s5, s4, s5
	s_ashr_i32 s14, s5, 4
	s_and_b32 s5, s5, -16
	s_sub_i32 s46, s4, s5
	v_readlane_b32 s4, v254, 52
	s_waitcnt vmcnt(6)
	v_mov_b32_e32 v58, v224
	s_add_i32 s46, s46, s4
	s_lshl_b32 s97, s14, 8
	v_readfirstlane_b32 s4, v58
	v_bfe_u32 v59, v58, 4, 2
	s_and_b32 s13, s4, 0xffffffc0
	s_waitcnt vmcnt(4)
	v_bfe_u32 v42, v58, 2, 4
	v_sub_u32_e32 v60, 0, v59
	s_add_i32 s13, s13, s97
	v_xor_b32_e32 v0, v58, v60
	v_or_b32_e32 v6, s13, v42
	v_lshlrev_b32_e32 v0, 4, v0
	v_min_i32_e32 v4, 0x157f, v6
	v_and_b32_e32 v0, 48, v0
	v_ashrrev_i32_e32 v5, 31, v4
	v_lshl_add_u64 v[2:3], s[74:75], 0, v[0:1]
	v_lshlrev_b64 v[4:5], 11, v[4:5]
	v_lshl_add_u64 v[34:35], v[2:3], 0, v[4:5]
	v_or_b32_e32 v4, 16, v6
	v_min_i32_e32 v4, 0x157f, v4
	v_ashrrev_i32_e32 v5, 31, v4
	v_lshlrev_b64 v[4:5], 11, v[4:5]
	v_lshl_add_u64 v[36:37], v[2:3], 0, v[4:5]
	v_or_b32_e32 v4, 32, v6
	v_min_i32_e32 v4, 0x157f, v4
	s_ashr_i32 s5, s4, 6
	v_ashrrev_i32_e32 v5, 31, v4
	s_and_b32 s12, s5, 1
	v_lshlrev_b64 v[4:5], 11, v[4:5]
	s_lshl_b32 s15, s46, 7
	v_lshl_add_u64 v[38:39], v[2:3], 0, v[4:5]
	v_or_b32_e32 v4, 48, v6
	s_lshl_b32 s13, s12, 6
	v_min_i32_e32 v4, 0x157f, v4
	v_and_b32_e32 v61, 15, v58
	s_or_b32 s13, s13, s15
	v_ashrrev_i32_e32 v5, 31, v4
	s_waitcnt vmcnt(1)
	v_or_b32_e32 v14, s13, v61
	v_lshlrev_b64 v[4:5], 11, v[4:5]
	v_ashrrev_i32_e32 v15, 31, v14
	v_lshl_add_u64 v[40:41], v[2:3], 0, v[4:5]
	v_lshlrev_b64 v[2:3], 5, v[14:15]
	v_lshl_add_u64 v[2:3], s[70:71], 0, v[2:3]
	s_waitcnt vmcnt(0)
	s_waitcnt lgkmcnt(0)
	s_barrier
	global_load_dwordx4 v[6:9], v[2:3], off offset:16
	global_load_dwordx4 v[22:25], v[2:3], off
	v_or_b32_e32 v2, 16, v14
	v_ashrrev_i32_e32 v3, 31, v2
	v_lshlrev_b64 v[2:3], 5, v[2:3]
	v_lshl_add_u64 v[10:11], s[70:71], 0, v[2:3]
	global_load_dwordx4 v[2:5], v[10:11], off offset:16
	global_load_dwordx4 v[18:21], v[10:11], off
	v_or_b32_e32 v10, 32, v14
	v_or_b32_e32 v14, 48, v14
	v_ashrrev_i32_e32 v11, 31, v10
	v_ashrrev_i32_e32 v15, 31, v14
	v_lshlrev_b64 v[10:11], 5, v[10:11]
	v_lshlrev_b64 v[14:15], 5, v[14:15]
	v_lshl_add_u64 v[16:17], s[70:71], 0, v[10:11]
	v_lshl_add_u64 v[30:31], s[70:71], 0, v[14:15]
	global_load_dwordx4 v[10:13], v[16:17], off offset:16
	global_load_dwordx4 v[26:29], v[16:17], off
	s_nop 0
	global_load_dwordx4 v[14:17], v[30:31], off offset:16
	s_nop 0
	global_load_dwordx4 v[30:33], v[30:31], off
	s_lshl_b32 s13, s5, 1
	s_waitcnt vmcnt(8)
	v_or_b32_e32 v46, s15, v42
	v_lshl_add_u32 v44, s5, 5, v46
	s_lshl_b32 s40, s13, 10
	s_or_b32 s13, s13, 1
	v_ashrrev_i32_e32 v45, 31, v44
	v_lshl_add_u32 v46, s13, 4, v46
	v_lshl_add_u64 v[42:43], s[2:3], 0, v[0:1]
	v_lshlrev_b64 v[162:163], 10, v[44:45]
	v_lshlrev_b64 v[44:45], 11, v[44:45]
	v_ashrrev_i32_e32 v47, 31, v46
	v_lshl_add_u64 v[44:45], v[42:43], 0, v[44:45]
	v_lshlrev_b64 v[164:165], 10, v[46:47]
	v_lshlrev_b64 v[46:47], 11, v[46:47]
	s_mov_b32 s41, m0
	s_mov_b32 m0, s40
	s_nop 0
	global_load_lds_dwordx4 v[44:45], off
	s_mov_b32 m0, s41
	v_lshl_add_u64 v[42:43], v[42:43], 0, v[46:47]
	s_lshl_b32 s42, s5, 12
	s_add_i32 s43, s40, 0x6000
	s_lshl_b32 s40, s13, 10
	s_mov_b32 s13, m0
	s_mov_b32 m0, s40
	s_nop 0
	global_load_lds_dwordx4 v[42:43], off
	s_mov_b32 m0, s13
	s_add_i32 s41, s42, 0x2000
	s_mov_b32 s13, m0
	s_mov_b32 m0, s41
	s_nop 0
	global_load_lds_dwordx4 v[34:35], off
	s_mov_b32 m0, s13
	s_add_i32 s13, s42, 0x2400
	s_mov_b32 s44, m0
	s_mov_b32 m0, s13
	s_nop 0
	global_load_lds_dwordx4 v[36:37], off
	s_mov_b32 m0, s44
	s_add_i32 s13, s42, 0x2800
	s_mov_b32 s44, m0
	s_mov_b32 m0, s13
	s_nop 0
	global_load_lds_dwordx4 v[38:39], off
	s_mov_b32 m0, s44
	s_add_i32 s13, s42, 0x2c00
	s_mov_b32 s44, m0
	s_mov_b32 m0, s13
	s_nop 0
	global_load_lds_dwordx4 v[40:41], off
	s_mov_b32 m0, s44
	v_lshl_add_u64 v[46:47], v[44:45], 0, 64
	s_mov_b32 s13, m0
	s_mov_b32 m0, s43
	s_nop 0
	global_load_lds_dwordx4 v[46:47], off
	s_mov_b32 m0, s13
	v_lshl_add_u64 v[48:49], v[42:43], 0, 64
	s_add_i32 s13, s40, 0x6000
	s_mov_b32 s43, m0
	s_mov_b32 m0, s13
	s_nop 0
	global_load_lds_dwordx4 v[48:49], off
	s_mov_b32 m0, s43
	v_lshrrev_b32_e32 v0, 2, v58
	s_waitcnt vmcnt(25)
	v_lshl_add_u64 v[50:51], v[34:35], 0, 64
	s_add_i32 s13, s42, 0x8000
	s_mov_b32 s43, m0
	s_mov_b32 m0, s13
	s_nop 0
	global_load_lds_dwordx4 v[50:51], off
	s_mov_b32 m0, s43
	v_sub_u32_e32 v0, 0, v0
	v_lshl_add_u64 v[52:53], v[36:37], 0, 64
	s_add_i32 s13, s42, 0x8400
	s_mov_b32 s43, m0
	s_mov_b32 m0, s13
	s_nop 0
	global_load_lds_dwordx4 v[52:53], off
	s_mov_b32 m0, s43
	v_bitop3_b32 v0, v59, v0, 3 bitop3:0x78
	s_and_b32 s4, s4, 0x3ffff80
	v_lshl_add_u64 v[54:55], v[38:39], 0, 64
	s_add_i32 s13, s42, 0x8800
	s_mov_b32 s43, m0
	s_mov_b32 m0, s13
	s_nop 0
	global_load_lds_dwordx4 v[54:55], off
	s_mov_b32 m0, s43
	v_lshlrev_b32_e32 v176, 4, v0
	v_or_b32_e32 v0, s4, v61
	v_lshl_add_u64 v[56:57], v[40:41], 0, 64
	s_add_i32 s42, s42, 0x8c00
	s_mov_b32 s13, m0
	s_mov_b32 m0, s42
	s_nop 0
	global_load_lds_dwordx4 v[56:57], off
	s_mov_b32 m0, s13
	v_lshlrev_b32_e32 v178, 6, v0
	v_bitop3_b32 v0, v58, 3, v60 bitop3:0x48
	v_lshl_add_u64 v[172:173], v[34:35], 0, s[6:7]
	v_lshlrev_b32_e32 v0, 4, v0
	v_mov_b32_e32 v34, 0
	v_mov_b32_e32 v221, 0x7f800000
	s_lshl_b32 s47, s12, 12
	v_lshlrev_b32_e32 v177, 6, v61
	s_lshl_b32 s42, s5, 11
	v_lshl_add_u64 v[166:167], v[40:41], 0, s[6:7]
	v_lshl_add_u64 v[168:169], v[38:39], 0, s[6:7]
	v_lshl_add_u64 v[170:171], v[36:37], 0, s[6:7]
	v_lshl_add_u64 v[174:175], s[0:1], 0, v[0:1]
	s_mov_b64 s[12:13], 0
	s_mov_b32 s43, 0
	v_mov_b32_e32 v35, v34
	v_mov_b32_e32 v36, v34
	v_mov_b32_e32 v37, v34
	v_mov_b32_e32 v38, v34
	v_mov_b32_e32 v39, v34
	v_mov_b32_e32 v40, v34
	v_mov_b32_e32 v41, v34
	v_mov_b32_e32 v42, v34
	v_mov_b32_e32 v43, v34
	v_mov_b32_e32 v44, v34
	v_mov_b32_e32 v45, v34
	v_mov_b32_e32 v46, v34
	v_mov_b32_e32 v47, v34
	v_mov_b32_e32 v48, v34
	v_mov_b32_e32 v49, v34
	v_mov_b32_e32 v50, v34
	v_mov_b32_e32 v51, v34
	v_mov_b32_e32 v52, v34
	v_mov_b32_e32 v53, v34
	v_mov_b32_e32 v54, v34
	v_mov_b32_e32 v55, v34
	v_mov_b32_e32 v56, v34
	v_mov_b32_e32 v57, v34
	v_mov_b32_e32 v58, v34
	v_mov_b32_e32 v59, v34
	v_mov_b32_e32 v60, v34
	v_mov_b32_e32 v61, v34
	s_waitcnt vmcnt(24)
	v_mov_b32_e32 v62, v34
	v_mov_b32_e32 v63, v34
	v_mov_b32_e32 v64, v34
	v_mov_b32_e32 v65, v34
	v_mov_b32_e32 v66, v34
	v_mov_b32_e32 v67, v34
	v_mov_b32_e32 v68, v34
	v_mov_b32_e32 v69, v34
	v_mov_b32_e32 v70, v34
	v_mov_b32_e32 v71, v34
	v_mov_b32_e32 v72, v34
	v_mov_b32_e32 v73, v34
	v_mov_b32_e32 v74, v34
	v_mov_b32_e32 v75, v34
	v_mov_b32_e32 v76, v34
	v_mov_b32_e32 v77, v34
	v_mov_b32_e32 v78, v34
	v_mov_b32_e32 v79, v34
	v_mov_b32_e32 v80, v34
	v_mov_b32_e32 v81, v34
	v_mov_b32_e32 v82, v34
	v_mov_b32_e32 v83, v34
	v_mov_b32_e32 v84, v34
	v_mov_b32_e32 v85, v34
	v_mov_b32_e32 v86, v34
	v_mov_b32_e32 v87, v34
	v_mov_b32_e32 v88, v34
	v_mov_b32_e32 v89, v34
	v_mov_b32_e32 v90, v34
	v_mov_b32_e32 v91, v34
	v_mov_b32_e32 v92, v34
	v_mov_b32_e32 v93, v34
	v_mov_b32_e32 v94, v34
	v_mov_b32_e32 v95, v34
	v_mov_b32_e32 v96, v34
	v_mov_b32_e32 v97, v34
	v_mov_b32_e32 v98, v34
	v_mov_b32_e32 v99, v34
	v_mov_b32_e32 v100, v34
	v_mov_b32_e32 v101, v34
	v_mov_b32_e32 v102, v34
	v_mov_b32_e32 v103, v34
	v_mov_b32_e32 v104, v34
	v_mov_b32_e32 v105, v34
	v_mov_b32_e32 v106, v34
	v_mov_b32_e32 v107, v34
	v_mov_b32_e32 v108, v34
	v_mov_b32_e32 v109, v34
	v_mov_b32_e32 v110, v34
	v_mov_b32_e32 v111, v34
	v_mov_b32_e32 v112, v34
	v_mov_b32_e32 v113, v34
	v_mov_b32_e32 v114, v34
	v_mov_b32_e32 v115, v34
	v_mov_b32_e32 v116, v34
	v_mov_b32_e32 v117, v34
	v_mov_b32_e32 v118, v34
	v_mov_b32_e32 v119, v34
	v_mov_b32_e32 v120, v34
	v_mov_b32_e32 v121, v34
	v_mov_b32_e32 v122, v34
	v_mov_b32_e32 v123, v34
	v_mov_b32_e32 v124, v34
	v_mov_b32_e32 v125, v34
	v_mov_b32_e32 v126, v34
	v_mov_b32_e32 v127, v34
	v_mov_b32_e32 v128, v34
	v_mov_b32_e32 v129, v34
	v_mov_b32_e32 v130, v34
	v_mov_b32_e32 v131, v34
	v_mov_b32_e32 v132, v34
	v_mov_b32_e32 v133, v34
	v_mov_b32_e32 v134, v34
	v_mov_b32_e32 v135, v34
	v_mov_b32_e32 v136, v34
	v_mov_b32_e32 v137, v34
	v_mov_b32_e32 v138, v34
	v_mov_b32_e32 v139, v34
	v_mov_b32_e32 v140, v34
	v_mov_b32_e32 v141, v34
	v_mov_b32_e32 v142, v34
	v_mov_b32_e32 v143, v34
	v_mov_b32_e32 v144, v34
	v_mov_b32_e32 v145, v34
	v_mov_b32_e32 v146, v34
	v_mov_b32_e32 v147, v34
	v_mov_b32_e32 v148, v34
	v_mov_b32_e32 v149, v34
	v_mov_b32_e32 v150, v34
	v_mov_b32_e32 v151, v34
	v_mov_b32_e32 v152, v34
	v_mov_b32_e32 v153, v34
	v_mov_b32_e32 v154, v34
	v_mov_b32_e32 v155, v34
	v_mov_b32_e32 v156, v34
	v_mov_b32_e32 v157, v34
	v_mov_b32_e32 v158, v34
	v_mov_b32_e32 v159, v34
	v_mov_b32_e32 v160, v34
	v_mov_b32_e32 v161, v34
	v_lshl_add_u64 v[162:163], v[162:163], 1, v[174:175]
	v_lshl_add_u64 v[164:165], v[164:165], 1, v[174:175]
.LBB0_167:
	s_mul_i32 s4, s43, 0x6000
	s_add_i32 s5, s4, 0xffffa000
	s_cmp_gt_i32 s43, 0
	s_waitcnt vmcnt(6)
	s_cselect_b32 s5, s5, 0xc000
	s_waitcnt lgkmcnt(0)
	s_barrier
	s_setprio 2
	v_add3_u32 v0, s4, v177, v176
	v_add_u32_e32 v0, s47, v0
	v_add3_u32 v212, s4, v178, v176
	ds_read_b128 v[196:199], v212 offset:8192
	ds_read_b128 v[180:183], v0
	ds_read_b128 v[184:187], v0 offset:1024
	ds_read_b128 v[188:191], v0 offset:2048
	ds_read_b128 v[192:195], v0 offset:3072
	ds_read_b128 v[200:203], v212 offset:9216
	ds_read_b128 v[204:207], v212 offset:10240
	ds_read_b128 v[208:211], v212 offset:11264
	ds_read_b128 v[216:219], v212 offset:12288
	ds_read_b128 v[226:229], v212 offset:13312
	ds_read_b128 v[230:233], v212 offset:14336
	ds_read_b128 v[234:237], v212 offset:15360
	s_add_i32 s44, s5, s42
	s_mov_b32 m0, s44
	s_nop 0
	global_load_lds_dwordx4 v[162:163], off
	s_add_i32 s44, s5, s40
	s_mov_b32 m0, s44
	s_nop 0
	global_load_lds_dwordx4 v[164:165], off
	s_add_i32 s5, s41, s5
	s_mov_b32 m0, s5
	s_nop 0
	global_load_lds_dwordx4 v[172:173], off
	s_add_i32 s44, s5, 0x400
	s_mov_b32 m0, s44
	s_nop 0
	global_load_lds_dwordx4 v[170:171], off
	s_add_i32 s44, s5, 0x800
	s_mov_b32 m0, s44
	s_nop 0
	global_load_lds_dwordx4 v[168:169], off
	s_addk_i32 s5, 0xc00
	s_mov_b32 m0, s5
	s_nop 0
	global_load_lds_dwordx4 v[166:167], off
	s_setprio 0
	s_waitcnt lgkmcnt(10)
	v_mfma_f32_16x16x32_bf16 v[34:37], v[196:199], v[180:183], v[34:37]
	s_waitcnt lgkmcnt(9)
	v_mfma_f32_16x16x32_bf16 v[38:41], v[196:199], v[184:187], v[38:41]
	s_waitcnt lgkmcnt(8)
	v_mfma_f32_16x16x32_bf16 v[42:45], v[196:199], v[188:191], v[42:45]
	s_waitcnt lgkmcnt(7)
	v_mfma_f32_16x16x32_bf16 v[46:49], v[196:199], v[192:195], v[46:49]
	s_waitcnt lgkmcnt(6)
	v_mfma_f32_16x16x32_bf16 v[50:53], v[200:203], v[180:183], v[50:53]
	v_mfma_f32_16x16x32_bf16 v[54:57], v[200:203], v[184:187], v[54:57]
	v_lshl_add_u64 v[162:163], v[162:163], 0, 64
	v_mfma_f32_16x16x32_bf16 v[58:61], v[200:203], v[188:191], v[58:61]
	v_mfma_f32_16x16x32_bf16 v[62:65], v[200:203], v[192:195], v[62:65]
	s_waitcnt lgkmcnt(5)
	v_mfma_f32_16x16x32_bf16 v[66:69], v[204:207], v[180:183], v[66:69]
	v_mfma_f32_16x16x32_bf16 v[70:73], v[204:207], v[184:187], v[70:73]
	v_lshl_add_u64 v[164:165], v[164:165], 0, 64
	v_mfma_f32_16x16x32_bf16 v[74:77], v[204:207], v[188:191], v[74:77]
	v_mfma_f32_16x16x32_bf16 v[78:81], v[204:207], v[192:195], v[78:81]
	s_waitcnt lgkmcnt(4)
	v_mfma_f32_16x16x32_bf16 v[82:85], v[208:211], v[180:183], v[82:85]
	v_mfma_f32_16x16x32_bf16 v[86:89], v[208:211], v[184:187], v[86:89]
	v_lshl_add_u64 v[172:173], v[172:173], 0, 64
	v_mfma_f32_16x16x32_bf16 v[90:93], v[208:211], v[188:191], v[90:93]
	v_mfma_f32_16x16x32_bf16 v[94:97], v[208:211], v[192:195], v[94:97]
	s_waitcnt lgkmcnt(3)
	v_mfma_f32_16x16x32_bf16 v[98:101], v[216:219], v[180:183], v[98:101]
	v_mfma_f32_16x16x32_bf16 v[102:105], v[216:219], v[184:187], v[102:105]
	v_lshl_add_u64 v[170:171], v[170:171], 0, 64
	v_mfma_f32_16x16x32_bf16 v[106:109], v[216:219], v[188:191], v[106:109]
	v_mfma_f32_16x16x32_bf16 v[110:113], v[216:219], v[192:195], v[110:113]
	s_waitcnt lgkmcnt(2)
	v_mfma_f32_16x16x32_bf16 v[114:117], v[226:229], v[180:183], v[114:117]
	v_mfma_f32_16x16x32_bf16 v[118:121], v[226:229], v[184:187], v[118:121]
	v_lshl_add_u64 v[168:169], v[168:169], 0, 64
	v_mfma_f32_16x16x32_bf16 v[122:125], v[226:229], v[188:191], v[122:125]
	v_mfma_f32_16x16x32_bf16 v[126:129], v[226:229], v[192:195], v[126:129]
	s_waitcnt lgkmcnt(1)
	v_mfma_f32_16x16x32_bf16 v[130:133], v[230:233], v[180:183], v[130:133]
	v_mfma_f32_16x16x32_bf16 v[134:137], v[230:233], v[184:187], v[134:137]
	v_lshl_add_u64 v[166:167], v[166:167], 0, 64
	v_mfma_f32_16x16x32_bf16 v[138:141], v[230:233], v[188:191], v[138:141]
	v_mfma_f32_16x16x32_bf16 v[142:145], v[230:233], v[192:195], v[142:145]
	s_waitcnt lgkmcnt(0)
	v_mfma_f32_16x16x32_bf16 v[146:149], v[234:237], v[180:183], v[146:149]
	v_mfma_f32_16x16x32_bf16 v[150:153], v[234:237], v[184:187], v[150:153]
	v_mfma_f32_16x16x32_bf16 v[154:157], v[234:237], v[188:191], v[154:157]
	v_mfma_f32_16x16x32_bf16 v[158:161], v[234:237], v[192:195], v[158:161]
	s_add_i32 s4, s43, 1
	s_cmp_lg_u32 s43, 2
	s_cselect_b32 s43, s4, 0
	s_add_u32 s12, s12, 64
	s_addc_u32 s13, s13, 0
	s_cmpk_eq_i32 s12, 0x780
	s_cbranch_scc0 .LBB0_167
	s_waitcnt vmcnt(6)
	v_mov_b32_e32 v162, v23
	v_mov_b32_e32 v163, v24
	v_mov_b32_e32 v23, v25
	v_mov_b32_e32 v164, v7
	v_mov_b32_e32 v165, v8
	v_pk_add_f32 v[22:23], v[162:163], v[22:23]
	v_mov_b32_e32 v7, v9
	v_pk_add_f32 v[6:7], v[164:165], v[6:7]
	v_add_f32_e32 v0, v22, v23
	v_add_f32_e32 v0, v0, v6
	v_add_f32_e32 v0, v0, v7
	v_fmamk_f32 v0, v0, 0x3a800000, v250
	s_mov_b32 s4, 0x800000
	s_waitcnt vmcnt(4)
	v_mov_b32_e32 v166, v19
	v_mov_b32_e32 v167, v20
	v_mov_b32_e32 v168, v3
	v_mul_f32_e32 v3, 0x4b800000, v0
	v_cmp_gt_f32_e32 vcc, s4, v0
	v_mov_b32_e32 v19, v21
	v_mov_b32_e32 v169, v4
	v_cndmask_b32_e32 v0, v0, v3, vcc
	v_pk_add_f32 v[6:7], v[166:167], v[18:19]
	v_mov_b32_e32 v3, v5
	v_pk_add_f32 v[2:3], v[168:169], v[2:3]
	v_add_f32_e32 v4, v6, v7
	v_add_f32_e32 v2, v4, v2
	v_add_f32_e32 v2, v2, v3
	v_fmamk_f32 v2, v2, 0x3a800000, v250
	v_mul_f32_e32 v3, 0x4b800000, v2
	v_cmp_gt_f32_e64 s[40:41], s4, v2
	s_waitcnt vmcnt(2)
	v_mov_b32_e32 v170, v27
	v_mov_b32_e32 v171, v28
	v_cndmask_b32_e64 v2, v2, v3, s[40:41]
	v_mov_b32_e32 v27, v29
	v_mov_b32_e32 v172, v11
	v_mov_b32_e32 v173, v12
	v_rsq_f32_e32 v182, v2
	v_pk_add_f32 v[2:3], v[170:171], v[26:27]
	v_mov_b32_e32 v11, v13
	v_pk_add_f32 v[4:5], v[172:173], v[10:11]
	v_add_f32_e32 v2, v2, v3
	v_add_f32_e32 v2, v2, v4
	v_add_f32_e32 v2, v2, v5
	v_fmamk_f32 v2, v2, 0x3a800000, v250
	v_mul_f32_e32 v3, 0x4b800000, v2
	v_cmp_gt_f32_e64 s[42:43], s4, v2
	s_waitcnt vmcnt(0)
	v_mov_b32_e32 v174, v31
	v_mov_b32_e32 v175, v32
	v_cndmask_b32_e64 v2, v2, v3, s[42:43]
	v_mov_b32_e32 v31, v33
	v_mov_b32_e32 v180, v15
	v_mov_b32_e32 v181, v16
	v_rsq_f32_e32 v183, v2
	v_pk_add_f32 v[2:3], v[174:175], v[30:31]
	v_mov_b32_e32 v15, v17
	v_pk_add_f32 v[4:5], v[180:181], v[14:15]
	v_add_f32_e32 v2, v2, v3
	v_add_f32_e32 v2, v2, v4
	v_add_f32_e32 v2, v2, v5
	v_fmamk_f32 v2, v2, 0x3a800000, v250
	v_mul_f32_e32 v3, 0x4b800000, v2
	v_cmp_gt_f32_e64 s[44:45], s4, v2
	s_waitcnt vmcnt(6)
	v_add_u32_e32 v185, v178, v176
	s_waitcnt lgkmcnt(0)
	s_barrier
	v_cndmask_b32_e64 v2, v2, v3, s[44:45]
	v_rsq_f32_e32 v184, v2
	ds_read_b128 v[2:5], v185 offset:15360
	ds_read_b128 v[6:9], v185 offset:14336
	ds_read_b128 v[10:13], v185 offset:13312
	ds_read_b128 v[14:17], v185 offset:12288
	ds_read_b128 v[18:21], v185 offset:11264
	ds_read_b128 v[22:25], v185 offset:10240
	ds_read_b128 v[26:29], v185 offset:9216
	ds_read_b128 v[30:33], v185 offset:8192
	v_add3_u32 v186, s47, v177, v176
	ds_read_b128 v[162:165], v186 offset:3072
	ds_read_b128 v[166:169], v186 offset:2048
	ds_read_b128 v[170:173], v186 offset:1024
	ds_read_b128 v[174:177], v186
	v_rsq_f32_e32 v0, v0
	v_mul_f32_e32 v188, 0x45800000, v182
	v_mul_f32_e32 v189, 0x45800000, v183
	v_mul_f32_e32 v190, 0x45800000, v184
	v_mul_f32_e32 v187, 0x45800000, v0
	s_waitcnt lgkmcnt(0)
	v_mfma_f32_16x16x32_bf16 v[34:37], v[30:33], v[174:177], v[34:37]
	v_mfma_f32_16x16x32_bf16 v[38:41], v[30:33], v[170:173], v[38:41]
	v_mfma_f32_16x16x32_bf16 v[178:181], v[30:33], v[166:169], v[42:45]
	v_mfma_f32_16x16x32_bf16 v[30:33], v[30:33], v[162:165], v[46:49]
	v_mfma_f32_16x16x32_bf16 v[48:51], v[26:29], v[174:177], v[50:53]
	v_mfma_f32_16x16x32_bf16 v[52:55], v[26:29], v[170:173], v[54:57]
	v_mfma_f32_16x16x32_bf16 v[56:59], v[26:29], v[166:169], v[58:61]
	v_mfma_f32_16x16x32_bf16 v[26:29], v[26:29], v[162:165], v[62:65]
	v_mfma_f32_16x16x32_bf16 v[60:63], v[22:25], v[174:177], v[66:69]
	v_mfma_f32_16x16x32_bf16 v[64:67], v[22:25], v[170:173], v[70:73]
	v_mfma_f32_16x16x32_bf16 v[68:71], v[22:25], v[166:169], v[74:77]
	v_mfma_f32_16x16x32_bf16 v[22:25], v[22:25], v[162:165], v[78:81]
	v_mfma_f32_16x16x32_bf16 v[72:75], v[18:21], v[174:177], v[82:85]
	v_mfma_f32_16x16x32_bf16 v[76:79], v[18:21], v[170:173], v[86:89]
	v_mfma_f32_16x16x32_bf16 v[80:83], v[18:21], v[166:169], v[90:93]
	v_mfma_f32_16x16x32_bf16 v[18:21], v[18:21], v[162:165], v[94:97]
	v_mfma_f32_16x16x32_bf16 v[84:87], v[14:17], v[174:177], v[98:101]
	v_mfma_f32_16x16x32_bf16 v[88:91], v[14:17], v[170:173], v[102:105]
	v_mfma_f32_16x16x32_bf16 v[92:95], v[14:17], v[166:169], v[106:109]
	v_mfma_f32_16x16x32_bf16 v[14:17], v[14:17], v[162:165], v[110:113]
	v_mfma_f32_16x16x32_bf16 v[96:99], v[10:13], v[174:177], v[114:117]
	v_mfma_f32_16x16x32_bf16 v[100:103], v[10:13], v[170:173], v[118:121]
	v_mfma_f32_16x16x32_bf16 v[104:107], v[10:13], v[166:169], v[122:125]
	v_mfma_f32_16x16x32_bf16 v[10:13], v[10:13], v[162:165], v[126:129]
	v_mfma_f32_16x16x32_bf16 v[108:111], v[6:9], v[174:177], v[130:133]
	v_mfma_f32_16x16x32_bf16 v[112:115], v[6:9], v[170:173], v[134:137]
	v_mfma_f32_16x16x32_bf16 v[116:119], v[6:9], v[166:169], v[138:141]
	v_mfma_f32_16x16x32_bf16 v[120:123], v[2:5], v[174:177], v[146:149]
	v_mfma_f32_16x16x32_bf16 v[124:127], v[2:5], v[170:173], v[150:153]
	v_mfma_f32_16x16x32_bf16 v[128:131], v[2:5], v[166:169], v[154:157]
	v_mfma_f32_16x16x32_bf16 v[6:9], v[6:9], v[162:165], v[142:145]
	v_mfma_f32_16x16x32_bf16 v[2:5], v[2:5], v[162:165], v[158:161]
	s_waitcnt vmcnt(0)
	v_cndmask_b32_e32 v46, v0, v187, vcc
	v_cndmask_b32_e64 v44, v182, v188, s[40:41]
	v_cndmask_b32_e64 v42, v183, v189, s[42:43]
	v_cndmask_b32_e64 v0, v184, v190, s[44:45]
	s_waitcnt lgkmcnt(0)
	s_barrier
	ds_read_b128 v[132:135], v186 offset:24576
	ds_read_b128 v[136:139], v186 offset:25600
	ds_read_b128 v[140:143], v186 offset:26624
	ds_read_b128 v[144:147], v186 offset:27648
	ds_read_b128 v[148:151], v185 offset:32768
	ds_read_b128 v[152:155], v185 offset:33792
	ds_read_b128 v[156:159], v185 offset:34816
	ds_read_b128 v[160:163], v185 offset:35840
	ds_read_b128 v[164:167], v185 offset:36864
	ds_read_b128 v[168:171], v185 offset:37888
	ds_read_b128 v[172:175], v185 offset:38912
	ds_read_b128 v[182:185], v185 offset:39936
	s_waitcnt lgkmcnt(4)
	v_mfma_f32_16x16x32_bf16 v[242:245], v[160:163], v[140:143], v[80:83]
	v_mfma_f32_16x16x32_bf16 v[246:249], v[160:163], v[144:147], v[18:21]
	s_waitcnt lgkmcnt(3)
	v_mfma_f32_16x16x32_bf16 v[210:213], v[164:167], v[132:135], v[84:87]
	v_mfma_f32_16x16x32_bf16 v[194:197], v[164:167], v[136:139], v[88:91]
	v_mfma_f32_16x16x32_bf16 v[206:209], v[164:167], v[140:143], v[92:95]
	v_mfma_f32_16x16x32_bf16 v[164:167], v[164:167], v[144:147], v[14:17]
	v_mfma_f32_16x16x32_bf16 v[186:189], v[148:151], v[132:135], v[34:37]
	v_mfma_f32_16x16x32_bf16 v[190:193], v[148:151], v[136:139], v[38:41]
	v_mfma_f32_16x16x32_bf16 v[176:179], v[148:151], v[140:143], v[178:181]
	v_mfma_f32_16x16x32_bf16 v[198:201], v[148:151], v[144:147], v[30:33]
	v_mfma_f32_16x16x32_bf16 v[48:51], v[152:155], v[132:135], v[48:51]
	v_mfma_f32_16x16x32_bf16 v[52:55], v[152:155], v[136:139], v[52:55]
	v_mfma_f32_16x16x32_bf16 v[56:59], v[152:155], v[140:143], v[56:59]
	v_mfma_f32_16x16x32_bf16 v[202:205], v[152:155], v[144:147], v[26:29]
	v_mfma_f32_16x16x32_bf16 v[60:63], v[156:159], v[132:135], v[60:63]
	v_mfma_f32_16x16x32_bf16 v[216:219], v[156:159], v[136:139], v[64:67]
	v_mfma_f32_16x16x32_bf16 v[226:229], v[156:159], v[140:143], v[68:71]
	v_mfma_f32_16x16x32_bf16 v[230:233], v[156:159], v[144:147], v[22:25]
	v_mfma_f32_16x16x32_bf16 v[234:237], v[160:163], v[132:135], v[72:75]
	v_mfma_f32_16x16x32_bf16 v[238:241], v[160:163], v[136:139], v[76:79]
	s_waitcnt lgkmcnt(2)
	v_mfma_f32_16x16x32_bf16 v[150:153], v[168:171], v[132:135], v[96:99]
	v_mfma_f32_16x16x32_bf16 v[160:163], v[168:171], v[136:139], v[100:103]
	v_mfma_f32_16x16x32_bf16 v[38:41], v[168:171], v[140:143], v[104:107]
	v_mfma_f32_16x16x32_bf16 v[34:37], v[168:171], v[144:147], v[10:13]
	s_waitcnt lgkmcnt(1)
	v_mfma_f32_16x16x32_bf16 v[30:33], v[172:175], v[132:135], v[108:111]
	v_mfma_f32_16x16x32_bf16 v[26:29], v[172:175], v[136:139], v[112:115]
	v_mfma_f32_16x16x32_bf16 v[22:25], v[172:175], v[140:143], v[116:119]
	v_mfma_f32_16x16x32_bf16 v[18:21], v[172:175], v[144:147], v[6:9]
	s_waitcnt lgkmcnt(0)
	v_mfma_f32_16x16x32_bf16 v[14:17], v[182:185], v[132:135], v[120:123]
	v_mfma_f32_16x16x32_bf16 v[10:13], v[182:185], v[136:139], v[124:127]
	v_mfma_f32_16x16x32_bf16 v[6:9], v[182:185], v[140:143], v[128:131]
	v_mfma_f32_16x16x32_bf16 v[2:5], v[182:185], v[144:147], v[2:5]
	v_mov_b32_e32 v43, v224
	s_lshl_b32 s4, s46, 3
	v_lshrrev_b32_e32 v65, 1, v43
	v_lshlrev_b32_e32 v45, 3, v43
	v_and_b32_e32 v140, 24, v65
	v_ashrrev_i32_e32 v65, 4, v43
	v_and_b32_e32 v47, 56, v45
	v_add_u32_e32 v66, 0x7c, v65
	v_cmp_gt_i32_e32 vcc, 2, v65
	v_ashrrev_i32_e32 v142, 7, v43
	v_and_b32_e32 v64, 0x4f, v43
	v_cmp_gt_i32_e64 s[40:41], 64, v43
	v_cndmask_b32_e32 v66, v66, v65, vcc
	v_and_b32_e32 v67, 0x78, v45
	v_bfe_u32 v45, v45, 6, 1
	v_lshl_add_u32 v65, v65, 1, s4
	v_ashrrev_i32_e32 v43, 3, v43
	s_movk_i32 s4, 0xffe1
	v_pk_mul_f32 v[48:49], v[46:47], v[48:49] op_sel_hi:[0,1]
	v_or_b32_e32 v45, v65, v45
	v_cmp_lt_i32_e64 s[44:45], s4, v43
	s_movk_i32 s4, 0xffc1
	v_cvt_pk_bf16_f32 v74, v48, v49
	v_pk_mul_f32 v[48:49], v[46:47], v[50:51] op_sel_hi:[0,1]
	s_movk_i32 s5, 0x110
	v_add_u32_e32 v132, s15, v43
	v_cmp_lt_i32_e64 s[46:47], s4, v43
	s_movk_i32 s4, 0xffa1
	v_cvt_pk_bf16_f32 v75, v48, v49
	v_pk_mul_f32 v[48:49], v[44:45], v[52:53] op_sel_hi:[0,1]
	v_mul_u32_u24_e32 v141, 0x110, v64
	v_cmp_lt_i32_e64 s[42:43], 1, v43
	v_mul_lo_u32 v64, v43, s5
	v_cmp_lt_i32_e64 s[48:49], s4, v43
	v_add_u32_e32 v43, 0x60, v132
	v_cvt_pk_bf16_f32 v76, v48, v49
	v_pk_mul_f32 v[48:49], v[44:45], v[54:55] op_sel_hi:[0,1]
	v_cvt_pk_bf16_f32 v77, v48, v49
	v_pk_mul_f32 v[48:49], v[42:43], v[56:57] op_sel_hi:[0,1]
	v_cvt_pk_bf16_f32 v78, v48, v49
	v_pk_mul_f32 v[48:49], v[42:43], v[58:59] op_sel_hi:[0,1]
	v_cvt_pk_bf16_f32 v79, v48, v49
	v_pk_mul_f32 v[48:49], v[0:1], v[202:203] op_sel_hi:[0,1]
	v_cvt_pk_bf16_f32 v80, v48, v49
	v_pk_mul_f32 v[48:49], v[0:1], v[204:205] op_sel_hi:[0,1]
	v_cvt_pk_bf16_f32 v81, v48, v49
	v_pk_mul_f32 v[48:49], v[46:47], v[60:61] op_sel_hi:[0,1]
	v_cvt_pk_bf16_f32 v82, v48, v49
	v_pk_mul_f32 v[48:49], v[46:47], v[62:63] op_sel_hi:[0,1]
	v_cvt_pk_bf16_f32 v83, v48, v49
	v_pk_mul_f32 v[48:49], v[44:45], v[216:217] op_sel_hi:[0,1]
	v_cvt_pk_bf16_f32 v84, v48, v49
	v_pk_mul_f32 v[48:49], v[44:45], v[218:219] op_sel_hi:[0,1]
	v_cvt_pk_bf16_f32 v85, v48, v49
	v_pk_mul_f32 v[48:49], v[42:43], v[226:227] op_sel_hi:[0,1]
	v_cvt_pk_bf16_f32 v86, v48, v49
	v_pk_mul_f32 v[48:49], v[42:43], v[228:229] op_sel_hi:[0,1]
	v_cvt_pk_bf16_f32 v87, v48, v49
	v_pk_mul_f32 v[48:49], v[0:1], v[230:231] op_sel_hi:[0,1]
	v_cvt_pk_bf16_f32 v88, v48, v49
	v_pk_mul_f32 v[48:49], v[0:1], v[232:233] op_sel_hi:[0,1]
	v_cvt_pk_bf16_f32 v89, v48, v49
	v_pk_mul_f32 v[48:49], v[46:47], v[234:235] op_sel_hi:[0,1]
	v_cvt_pk_bf16_f32 v90, v48, v49
	v_pk_mul_f32 v[48:49], v[46:47], v[236:237] op_sel_hi:[0,1]
	v_cvt_pk_bf16_f32 v91, v48, v49
	v_pk_mul_f32 v[48:49], v[44:45], v[238:239] op_sel_hi:[0,1]
	v_cvt_pk_bf16_f32 v92, v48, v49
	v_pk_mul_f32 v[48:49], v[44:45], v[240:241] op_sel_hi:[0,1]
	v_cvt_pk_bf16_f32 v93, v48, v49
	v_pk_mul_f32 v[48:49], v[42:43], v[242:243] op_sel_hi:[0,1]
	v_cvt_pk_bf16_f32 v94, v48, v49
	v_pk_mul_f32 v[48:49], v[42:43], v[244:245] op_sel_hi:[0,1]
	v_cvt_pk_bf16_f32 v95, v48, v49
	v_pk_mul_f32 v[48:49], v[0:1], v[246:247] op_sel_hi:[0,1]
	v_cvt_pk_bf16_f32 v96, v48, v49
	v_pk_mul_f32 v[48:49], v[0:1], v[248:249] op_sel_hi:[0,1]
	v_cvt_pk_bf16_f32 v97, v48, v49
	v_pk_mul_f32 v[48:49], v[46:47], v[210:211] op_sel_hi:[0,1]
	v_cvt_pk_bf16_f32 v98, v48, v49
	v_pk_mul_f32 v[48:49], v[46:47], v[212:213] op_sel_hi:[0,1]
	v_cvt_pk_bf16_f32 v99, v48, v49
	v_pk_mul_f32 v[48:49], v[44:45], v[194:195] op_sel_hi:[0,1]
	v_cvt_pk_bf16_f32 v100, v48, v49
	v_pk_mul_f32 v[48:49], v[44:45], v[196:197] op_sel_hi:[0,1]
	v_mul_lo_u32 v66, v66, s5
	v_lshl_add_u32 v144, v47, 1, v64
	v_pk_mul_f32 v[64:65], v[46:47], v[186:187] op_sel_hi:[0,1]
	v_cvt_pk_bf16_f32 v101, v48, v49
	v_pk_mul_f32 v[48:49], v[42:43], v[206:207] op_sel_hi:[0,1]
	v_lshl_add_u32 v143, v67, 1, v66
	v_cvt_pk_bf16_f32 v66, v64, v65
	v_pk_mul_f32 v[64:65], v[46:47], v[188:189] op_sel_hi:[0,1]
	v_cvt_pk_bf16_f32 v102, v48, v49
	v_pk_mul_f32 v[48:49], v[42:43], v[208:209] op_sel_hi:[0,1]
	v_cvt_pk_bf16_f32 v67, v64, v65
	v_pk_mul_f32 v[64:65], v[44:45], v[190:191] op_sel_hi:[0,1]
	v_cvt_pk_bf16_f32 v103, v48, v49
	v_pk_mul_f32 v[48:49], v[0:1], v[164:165] op_sel_hi:[0,1]
	v_cvt_pk_bf16_f32 v68, v64, v65
	v_pk_mul_f32 v[64:65], v[44:45], v[192:193] op_sel_hi:[0,1]
	v_cvt_pk_bf16_f32 v104, v48, v49
	v_pk_mul_f32 v[48:49], v[0:1], v[166:167] op_sel_hi:[0,1]
	v_pk_mul_f32 v[2:3], v[0:1], v[2:3] op_sel_hi:[0,1]
	v_cvt_pk_bf16_f32 v69, v64, v65
	v_pk_mul_f32 v[64:65], v[42:43], v[176:177] op_sel_hi:[0,1]
	v_cvt_pk_bf16_f32 v105, v48, v49
	v_pk_mul_f32 v[48:49], v[46:47], v[150:151] op_sel_hi:[0,1]
	v_cvt_pk_bf16_f32 v128, v2, v3
	v_pk_mul_f32 v[2:3], v[0:1], v[4:5] op_sel_hi:[0,1]
	v_cvt_pk_bf16_f32 v70, v64, v65
	v_pk_mul_f32 v[64:65], v[42:43], v[178:179] op_sel_hi:[0,1]
	v_cvt_pk_bf16_f32 v106, v48, v49
	v_pk_mul_f32 v[48:49], v[46:47], v[152:153] op_sel_hi:[0,1]
	v_cvt_pk_bf16_f32 v129, v2, v3
	v_mov_b64_e32 v[2:3], s[54:55]
	v_add_u32_e32 v134, 32, v132
	v_add_u32_e32 v136, 64, v132
	v_cvt_pk_bf16_f32 v71, v64, v65
	v_pk_mul_f32 v[64:65], v[0:1], v[198:199] op_sel_hi:[0,1]
	v_cvt_pk_bf16_f32 v107, v48, v49
	v_pk_mul_f32 v[48:49], v[44:45], v[160:161] op_sel_hi:[0,1]
	v_pk_mul_f32 v[38:39], v[42:43], v[38:39] op_sel_hi:[0,1]
	v_pk_mul_f32 v[34:35], v[0:1], v[34:35] op_sel_hi:[0,1]
	v_pk_mul_f32 v[30:31], v[46:47], v[30:31] op_sel_hi:[0,1]
	v_pk_mul_f32 v[26:27], v[44:45], v[26:27] op_sel_hi:[0,1]
	v_pk_mul_f32 v[22:23], v[42:43], v[22:23] op_sel_hi:[0,1]
	v_pk_mul_f32 v[18:19], v[0:1], v[18:19] op_sel_hi:[0,1]
	v_pk_mul_f32 v[14:15], v[46:47], v[14:15] op_sel_hi:[0,1]
	v_pk_mul_f32 v[10:11], v[44:45], v[10:11] op_sel_hi:[0,1]
	v_pk_mul_f32 v[6:7], v[42:43], v[6:7] op_sel_hi:[0,1]
	v_mad_i64_i32 v[130:131], s[4:5], v45, s19, v[2:3]
	v_mov_b64_e32 v[2:3], s[52:53]
	v_cvt_pk_bf16_f32 v72, v64, v65
	v_pk_mul_f32 v[64:65], v[0:1], v[200:201] op_sel_hi:[0,1]
	v_cvt_pk_bf16_f32 v108, v48, v49
	v_pk_mul_f32 v[48:49], v[44:45], v[162:163] op_sel_hi:[0,1]
	v_cvt_pk_bf16_f32 v110, v38, v39
	v_pk_mul_f32 v[38:39], v[42:43], v[40:41] op_sel_hi:[0,1]
	v_cvt_pk_bf16_f32 v112, v34, v35
	v_pk_mul_f32 v[34:35], v[0:1], v[36:37] op_sel_hi:[0,1]
	v_cvt_pk_bf16_f32 v114, v30, v31
	v_pk_mul_f32 v[30:31], v[46:47], v[32:33] op_sel_hi:[0,1]
	v_cvt_pk_bf16_f32 v116, v26, v27
	v_pk_mul_f32 v[26:27], v[44:45], v[28:29] op_sel_hi:[0,1]
	v_cvt_pk_bf16_f32 v118, v22, v23
	v_pk_mul_f32 v[22:23], v[42:43], v[24:25] op_sel_hi:[0,1]
	v_cvt_pk_bf16_f32 v120, v18, v19
	v_pk_mul_f32 v[18:19], v[0:1], v[20:21] op_sel_hi:[0,1]
	v_cvt_pk_bf16_f32 v122, v14, v15
	v_pk_mul_f32 v[14:15], v[46:47], v[16:17] op_sel_hi:[0,1]
	v_cvt_pk_bf16_f32 v124, v10, v11
	v_pk_mul_f32 v[10:11], v[44:45], v[12:13] op_sel_hi:[0,1]
	v_cvt_pk_bf16_f32 v126, v6, v7
	v_pk_mul_f32 v[6:7], v[42:43], v[8:9] op_sel_hi:[0,1]
	v_mad_i64_i32 v[132:133], s[4:5], v132, s19, v[2:3]
	v_mad_i64_i32 v[134:135], s[4:5], v134, s19, v[2:3]
	v_mad_i64_i32 v[136:137], s[4:5], v136, s19, v[2:3]
	v_mad_i64_i32 v[138:139], s[4:5], v43, s19, v[2:3]
	v_add_u32_e32 v145, 0xfffffef0, v144
	v_add_u32_e32 v146, 0xffffff70, v144
	v_add_u32_e32 v147, 0xfffffde0, v144
	v_add_u32_e32 v148, 0xfffffe60, v144
	v_add_u32_e32 v149, 0x2200, v144
	v_add_u32_e32 v168, 0x20f0, v144
	v_add_u32_e32 v169, 0x2170, v144
	v_add_u32_e32 v170, 0x1fe0, v144
	v_add_u32_e32 v171, 0x2060, v144
	v_add_u32_e32 v154, 0x4400, v144
	v_add_u32_e32 v155, 0x42f0, v144
	v_add_u32_e32 v156, 0x4370, v144
	v_add_u32_e32 v157, 0x41e0, v144
	v_add_u32_e32 v158, 0x4260, v144
	v_add_u32_e32 v159, 0x6600, v144
	v_add_u32_e32 v172, 0x64f0, v144
	v_add_u32_e32 v173, 0x6570, v144
	v_add_u32_e32 v174, 0x63e0, v144
	v_add_u32_e32 v175, 0x6460, v144
	v_cvt_pk_bf16_f32 v73, v64, v65
	v_cvt_pk_bf16_f32 v109, v48, v49
	v_cvt_pk_bf16_f32 v111, v38, v39
	v_cvt_pk_bf16_f32 v113, v34, v35
	v_cvt_pk_bf16_f32 v115, v30, v31
	v_cvt_pk_bf16_f32 v117, v26, v27
	v_cvt_pk_bf16_f32 v119, v22, v23
	v_cvt_pk_bf16_f32 v121, v18, v19
	v_cvt_pk_bf16_f32 v123, v14, v15
	v_cvt_pk_bf16_f32 v125, v10, v11
	v_cvt_pk_bf16_f32 v127, v6, v7
	v_lshl_or_b32 v0, s14, 7, v47
	s_mov_b32 s4, 0
	s_mov_b64 s[12:13], -1
	v_add_u32_e32 v164, v140, v141
	v_xor_b32_e32 v246, 32, v225
	v_xor_b32_e32 v247, 16, v225
	v_xor_b32_e32 v248, 8, v225
	v_xor_b32_e32 v249, 4, v225
	v_mov_b32_e32 v243, v221
	s_branch .LBB0_171

.LBB0_193:
	s_waitcnt vmcnt(1)
	v_mov_b32_e32 v16, v224
	s_lshl_b32 s46, s57, 8
	v_readfirstlane_b32 s40, v16
	s_and_b32 s14, s40, 0xffffffc0
	v_bfe_u32 v17, v16, 4, 2
	v_bfe_u32 v12, v16, 2, 4
	s_add_i32 s14, s14, s46
	v_sub_u32_e32 v18, 0, v17
	v_or_b32_e32 v10, s14, v12
	s_lshl_b32 s12, s68, 7
	s_ashr_i32 s41, s40, 6
	v_xor_b32_e32 v0, v16, v18
	v_min_i32_e32 v4, 0x3ff, v10
	v_or_b32_e32 v6, 16, v10
	v_or_b32_e32 v8, 32, v10
	v_or_b32_e32 v10, 48, v10
	v_lshlrev_b32_e32 v0, 4, v0
	v_min_i32_e32 v6, 0x3ff, v6
	v_min_i32_e32 v8, 0x3ff, v8
	v_min_i32_e32 v10, 0x3ff, v10
	s_lshl_b32 s14, s41, 1
	v_or_b32_e32 v14, s12, v12
	v_and_b32_e32 v0, 48, v0
	v_ashrrev_i32_e32 v5, 31, v4
	v_ashrrev_i32_e32 v7, 31, v6
	v_ashrrev_i32_e32 v9, 31, v8
	v_ashrrev_i32_e32 v11, 31, v10
	v_lshl_add_u32 v12, s41, 5, v14
	s_lshl_b32 s47, s14, 10
	s_or_b32 s14, s14, 1
	v_lshl_add_u64 v[2:3], s[4:5], 0, v[0:1]
	v_lshlrev_b64 v[4:5], 11, v[4:5]
	v_lshlrev_b64 v[6:7], 11, v[6:7]
	v_lshlrev_b64 v[8:9], 11, v[8:9]
	v_lshlrev_b64 v[10:11], 11, v[10:11]
	v_ashrrev_i32_e32 v13, 31, v12
	v_lshl_add_u32 v14, s14, 4, v14
	v_lshl_add_u64 v[4:5], v[2:3], 0, v[4:5]
	v_lshl_add_u64 v[6:7], v[2:3], 0, v[6:7]
	v_lshl_add_u64 v[8:9], v[2:3], 0, v[8:9]
	v_lshl_add_u64 v[2:3], v[2:3], 0, v[10:11]
	v_lshl_add_u64 v[10:11], s[0:1], 0, v[0:1]
	v_lshlrev_b64 v[130:131], 10, v[12:13]
	v_lshlrev_b64 v[12:13], 11, v[12:13]
	v_ashrrev_i32_e32 v15, 31, v14
	s_waitcnt vmcnt(0)
	s_waitcnt lgkmcnt(0)
	s_barrier
	v_lshl_add_u64 v[12:13], v[10:11], 0, v[12:13]
	s_mov_b32 s15, m0
	s_mov_b32 m0, s47
	s_nop 0
	global_load_lds_dwordx4 v[12:13], off
	s_mov_b32 m0, s15
	v_lshlrev_b64 v[132:133], 10, v[14:15]
	v_lshlrev_b64 v[14:15], 11, v[14:15]
	v_lshl_add_u64 v[10:11], v[10:11], 0, v[14:15]
	s_lshl_b32 s14, s14, 10
	s_mov_b32 s15, m0
	s_mov_b32 m0, s14
	s_nop 0
	global_load_lds_dwordx4 v[10:11], off
	s_mov_b32 m0, s15
	s_lshl_b32 s48, s41, 12
	s_add_i32 s15, s48, 0x2000
	s_mov_b32 s49, m0
	s_mov_b32 m0, s15
	s_nop 0
	global_load_lds_dwordx4 v[4:5], off
	s_mov_b32 m0, s49
	s_add_i32 s49, s48, 0x2400
	s_mov_b32 s69, m0
	s_mov_b32 m0, s49
	s_nop 0
	global_load_lds_dwordx4 v[6:7], off
	s_mov_b32 m0, s69
	s_add_i32 s49, s48, 0x2800
	s_mov_b32 s69, m0
	s_mov_b32 m0, s49
	s_nop 0
	global_load_lds_dwordx4 v[8:9], off
	s_mov_b32 m0, s69
	s_add_i32 s49, s48, 0x2c00
	s_mov_b32 s69, m0
	s_mov_b32 m0, s49
	s_nop 0
	global_load_lds_dwordx4 v[2:3], off
	s_mov_b32 m0, s69
	v_lshl_add_u64 v[12:13], v[12:13], 0, 64
	s_addk_i32 s47, 0x6000
	s_mov_b32 s49, m0
	s_mov_b32 m0, s47
	s_nop 0
	global_load_lds_dwordx4 v[12:13], off
	s_mov_b32 m0, s49
	v_lshl_add_u64 v[10:11], v[10:11], 0, 64
	s_add_i32 s47, s14, 0x6000
	s_mov_b32 s49, m0
	s_mov_b32 m0, s47
	s_nop 0
	global_load_lds_dwordx4 v[10:11], off
	s_mov_b32 m0, s49
	v_lshl_add_u64 v[10:11], v[4:5], 0, 64
	v_lshrrev_b32_e32 v0, 2, v16
	s_add_i32 s47, s48, 0x8000
	s_mov_b32 s49, m0
	s_mov_b32 m0, s47
	s_nop 0
	global_load_lds_dwordx4 v[10:11], off
	s_mov_b32 m0, s49
	v_lshl_add_u64 v[10:11], v[6:7], 0, 64
	v_sub_u32_e32 v0, 0, v0
	s_add_i32 s47, s48, 0x8400
	s_mov_b32 s49, m0
	s_mov_b32 m0, s47
	s_nop 0
	global_load_lds_dwordx4 v[10:11], off
	s_mov_b32 m0, s49
	v_lshl_add_u64 v[10:11], v[8:9], 0, 64
	v_bitop3_b32 v0, v17, v0, 3 bitop3:0x78
	s_add_i32 s47, s48, 0x8800
	s_mov_b32 s49, m0
	s_mov_b32 m0, s47
	s_nop 0
	global_load_lds_dwordx4 v[10:11], off
	s_mov_b32 m0, s49
	v_lshl_add_u64 v[10:11], v[2:3], 0, 64
	v_lshlrev_b32_e32 v144, 4, v0
	v_and_b32_e32 v0, 15, v16
	s_add_i32 s48, s48, 0x8c00
	s_mov_b32 s47, m0
	s_mov_b32 m0, s48
	s_nop 0
	global_load_lds_dwordx4 v[10:11], off
	s_mov_b32 m0, s47
	v_and_or_b32 v10, s40, 64, v0
	s_and_b32 s40, s40, 0x3ffff80
	v_or_b32_e32 v0, s40, v0
	v_lshlrev_b32_e32 v145, 6, v0
	v_bitop3_b32 v0, v16, 3, v18 bitop3:0x48
	v_lshl_add_u64 v[134:135], v[2:3], 0, s[6:7]
	v_lshlrev_b32_e32 v0, 4, v0
	v_mov_b32_e32 v2, 0
	s_mov_b32 s13, 0
	v_lshlrev_b32_e32 v146, 6, v10
	s_lshl_b32 s47, s41, 11
	v_lshl_add_u64 v[136:137], v[8:9], 0, s[6:7]
	v_lshl_add_u64 v[138:139], v[6:7], 0, s[6:7]
	v_lshl_add_u64 v[140:141], v[4:5], 0, s[6:7]
	v_lshl_add_u64 v[142:143], s[44:45], 0, v[0:1]
	s_mov_b64 s[40:41], 0
	v_mov_b32_e32 v3, v2
	v_mov_b32_e32 v4, v2
	v_mov_b32_e32 v5, v2
	v_mov_b32_e32 v6, v2
	v_mov_b32_e32 v7, v2
	v_mov_b32_e32 v8, v2
	v_mov_b32_e32 v9, v2
	v_mov_b32_e32 v10, v2
	v_mov_b32_e32 v11, v2
	v_mov_b32_e32 v12, v2
	v_mov_b32_e32 v13, v2
	v_mov_b32_e32 v14, v2
	v_mov_b32_e32 v15, v2
	v_mov_b32_e32 v16, v2
	v_mov_b32_e32 v17, v2
	v_mov_b32_e32 v18, v2
	v_mov_b32_e32 v19, v2
	v_mov_b32_e32 v20, v2
	v_mov_b32_e32 v21, v2
	v_mov_b32_e32 v22, v2
	v_mov_b32_e32 v23, v2
	v_mov_b32_e32 v24, v2
	v_mov_b32_e32 v25, v2
	v_mov_b32_e32 v26, v2
	v_mov_b32_e32 v27, v2
	v_mov_b32_e32 v28, v2
	v_mov_b32_e32 v29, v2
	v_mov_b32_e32 v30, v2
	v_mov_b32_e32 v31, v2
	v_mov_b32_e32 v32, v2
	v_mov_b32_e32 v33, v2
	v_mov_b32_e32 v34, v2
	v_mov_b32_e32 v35, v2
	v_mov_b32_e32 v36, v2
	v_mov_b32_e32 v37, v2
	v_mov_b32_e32 v38, v2
	v_mov_b32_e32 v39, v2
	v_mov_b32_e32 v40, v2
	v_mov_b32_e32 v41, v2
	v_mov_b32_e32 v42, v2
	v_mov_b32_e32 v43, v2
	v_mov_b32_e32 v44, v2
	v_mov_b32_e32 v45, v2
	s_waitcnt vmcnt(0)
	v_mov_b32_e32 v46, v2
	v_mov_b32_e32 v47, v2
	v_mov_b32_e32 v48, v2
	v_mov_b32_e32 v49, v2
	v_mov_b32_e32 v50, v2
	v_mov_b32_e32 v51, v2
	v_mov_b32_e32 v52, v2
	v_mov_b32_e32 v53, v2
	v_mov_b32_e32 v54, v2
	v_mov_b32_e32 v55, v2
	v_mov_b32_e32 v56, v2
	v_mov_b32_e32 v57, v2
	v_mov_b32_e32 v58, v2
	v_mov_b32_e32 v59, v2
	v_mov_b32_e32 v60, v2
	v_mov_b32_e32 v61, v2
	v_mov_b32_e32 v62, v2
	v_mov_b32_e32 v63, v2
	v_mov_b32_e32 v64, v2
	v_mov_b32_e32 v65, v2
	v_mov_b32_e32 v66, v2
	v_mov_b32_e32 v67, v2
	v_mov_b32_e32 v68, v2
	v_mov_b32_e32 v69, v2
	v_mov_b32_e32 v70, v2
	v_mov_b32_e32 v71, v2
	v_mov_b32_e32 v72, v2
	v_mov_b32_e32 v73, v2
	v_mov_b32_e32 v74, v2
	v_mov_b32_e32 v75, v2
	v_mov_b32_e32 v76, v2
	v_mov_b32_e32 v77, v2
	v_mov_b32_e32 v78, v2
	v_mov_b32_e32 v79, v2
	v_mov_b32_e32 v80, v2
	v_mov_b32_e32 v81, v2
	v_mov_b32_e32 v82, v2
	v_mov_b32_e32 v83, v2
	v_mov_b32_e32 v84, v2
	v_mov_b32_e32 v85, v2
	v_mov_b32_e32 v86, v2
	v_mov_b32_e32 v87, v2
	v_mov_b32_e32 v88, v2
	v_mov_b32_e32 v89, v2
	v_mov_b32_e32 v90, v2
	v_mov_b32_e32 v91, v2
	v_mov_b32_e32 v92, v2
	v_mov_b32_e32 v93, v2
	v_mov_b32_e32 v94, v2
	v_mov_b32_e32 v95, v2
	v_mov_b32_e32 v96, v2
	v_mov_b32_e32 v97, v2
	v_mov_b32_e32 v98, v2
	v_mov_b32_e32 v99, v2
	v_mov_b32_e32 v100, v2
	v_mov_b32_e32 v101, v2
	v_mov_b32_e32 v102, v2
	v_mov_b32_e32 v103, v2
	v_mov_b32_e32 v104, v2
	v_mov_b32_e32 v105, v2
	v_mov_b32_e32 v106, v2
	v_mov_b32_e32 v107, v2
	v_mov_b32_e32 v108, v2
	v_mov_b32_e32 v109, v2
	v_mov_b32_e32 v110, v2
	v_mov_b32_e32 v111, v2
	v_mov_b32_e32 v112, v2
	v_mov_b32_e32 v113, v2
	v_mov_b32_e32 v114, v2
	v_mov_b32_e32 v115, v2
	v_mov_b32_e32 v116, v2
	v_mov_b32_e32 v117, v2
	v_mov_b32_e32 v118, v2
	v_mov_b32_e32 v119, v2
	v_mov_b32_e32 v120, v2
	v_mov_b32_e32 v121, v2
	v_mov_b32_e32 v122, v2
	v_mov_b32_e32 v123, v2
	v_mov_b32_e32 v124, v2
	v_mov_b32_e32 v125, v2
	v_mov_b32_e32 v126, v2
	v_mov_b32_e32 v127, v2
	v_mov_b32_e32 v128, v2
	v_mov_b32_e32 v129, v2
	v_lshl_add_u64 v[130:131], v[130:131], 1, v[142:143]
	v_lshl_add_u64 v[132:133], v[132:133], 1, v[142:143]
.LBB0_194:
	s_mul_i32 s48, s13, 0x6000
	s_add_i32 s49, s48, 0xffffa000
	s_cmp_gt_i32 s13, 0
	s_waitcnt vmcnt(6)
	s_cselect_b32 s49, s49, 0xc000
	s_waitcnt lgkmcnt(0)
	s_barrier
	s_setprio 2
	v_or_b32_e32 v0, s48, v146
	v_add_u32_e32 v0, v0, v144
	v_add3_u32 v212, s48, v145, v144
	ds_read_b128 v[164:167], v212 offset:8192
	ds_read_b128 v[148:151], v0
	ds_read_b128 v[152:155], v0 offset:1024
	ds_read_b128 v[156:159], v0 offset:2048
	ds_read_b128 v[160:163], v0 offset:3072
	ds_read_b128 v[168:171], v212 offset:9216
	ds_read_b128 v[172:175], v212 offset:10240
	ds_read_b128 v[176:179], v212 offset:11264
	ds_read_b128 v[180:183], v212 offset:12288
	ds_read_b128 v[184:187], v212 offset:13312
	ds_read_b128 v[188:191], v212 offset:14336
	ds_read_b128 v[198:201], v212 offset:15360
	s_add_i32 s69, s49, s47
	s_mov_b32 m0, s69
	s_nop 0
	global_load_lds_dwordx4 v[130:131], off
	s_add_i32 s69, s49, s14
	s_mov_b32 m0, s69
	s_nop 0
	global_load_lds_dwordx4 v[132:133], off
	s_add_i32 s49, s15, s49
	s_mov_b32 m0, s49
	s_nop 0
	global_load_lds_dwordx4 v[140:141], off
	s_add_i32 s69, s49, 0x400
	s_mov_b32 m0, s69
	s_nop 0
	global_load_lds_dwordx4 v[138:139], off
	s_add_i32 s69, s49, 0x800
	s_mov_b32 m0, s69
	s_nop 0
	global_load_lds_dwordx4 v[136:137], off
	s_addk_i32 s49, 0xc00
	s_mov_b32 m0, s49
	s_nop 0
	global_load_lds_dwordx4 v[134:135], off
	s_setprio 0
	s_waitcnt lgkmcnt(10)
	v_mfma_f32_16x16x32_bf16 v[126:129], v[164:167], v[148:151], v[126:129]
	s_waitcnt lgkmcnt(9)
	v_mfma_f32_16x16x32_bf16 v[122:125], v[164:167], v[152:155], v[122:125]
	s_waitcnt lgkmcnt(8)
	v_mfma_f32_16x16x32_bf16 v[118:121], v[164:167], v[156:159], v[118:121]
	s_waitcnt lgkmcnt(7)
	v_mfma_f32_16x16x32_bf16 v[114:117], v[164:167], v[160:163], v[114:117]
	s_waitcnt lgkmcnt(6)
	v_mfma_f32_16x16x32_bf16 v[110:113], v[168:171], v[148:151], v[110:113]
	v_mfma_f32_16x16x32_bf16 v[106:109], v[168:171], v[152:155], v[106:109]
	v_lshl_add_u64 v[130:131], v[130:131], 0, 64
	v_mfma_f32_16x16x32_bf16 v[102:105], v[168:171], v[156:159], v[102:105]
	v_mfma_f32_16x16x32_bf16 v[98:101], v[168:171], v[160:163], v[98:101]
	s_waitcnt lgkmcnt(5)
	v_mfma_f32_16x16x32_bf16 v[94:97], v[172:175], v[148:151], v[94:97]
	v_mfma_f32_16x16x32_bf16 v[90:93], v[172:175], v[152:155], v[90:93]
	v_lshl_add_u64 v[132:133], v[132:133], 0, 64
	v_mfma_f32_16x16x32_bf16 v[86:89], v[172:175], v[156:159], v[86:89]
	v_mfma_f32_16x16x32_bf16 v[82:85], v[172:175], v[160:163], v[82:85]
	s_waitcnt lgkmcnt(4)
	v_mfma_f32_16x16x32_bf16 v[78:81], v[176:179], v[148:151], v[78:81]
	v_mfma_f32_16x16x32_bf16 v[74:77], v[176:179], v[152:155], v[74:77]
	v_lshl_add_u64 v[140:141], v[140:141], 0, 64
	v_mfma_f32_16x16x32_bf16 v[70:73], v[176:179], v[156:159], v[70:73]
	v_mfma_f32_16x16x32_bf16 v[66:69], v[176:179], v[160:163], v[66:69]
	s_waitcnt lgkmcnt(3)
	v_mfma_f32_16x16x32_bf16 v[62:65], v[180:183], v[148:151], v[62:65]
	v_mfma_f32_16x16x32_bf16 v[58:61], v[180:183], v[152:155], v[58:61]
	v_lshl_add_u64 v[138:139], v[138:139], 0, 64
	v_mfma_f32_16x16x32_bf16 v[54:57], v[180:183], v[156:159], v[54:57]
	v_mfma_f32_16x16x32_bf16 v[50:53], v[180:183], v[160:163], v[50:53]
	s_waitcnt lgkmcnt(2)
	v_mfma_f32_16x16x32_bf16 v[46:49], v[184:187], v[148:151], v[46:49]
	v_mfma_f32_16x16x32_bf16 v[42:45], v[184:187], v[152:155], v[42:45]
	v_lshl_add_u64 v[136:137], v[136:137], 0, 64
	v_mfma_f32_16x16x32_bf16 v[38:41], v[184:187], v[156:159], v[38:41]
	v_mfma_f32_16x16x32_bf16 v[34:37], v[184:187], v[160:163], v[34:37]
	s_waitcnt lgkmcnt(1)
	v_mfma_f32_16x16x32_bf16 v[30:33], v[188:191], v[148:151], v[30:33]
	v_mfma_f32_16x16x32_bf16 v[26:29], v[188:191], v[152:155], v[26:29]
	v_lshl_add_u64 v[134:135], v[134:135], 0, 64
	v_mfma_f32_16x16x32_bf16 v[22:25], v[188:191], v[156:159], v[22:25]
	v_mfma_f32_16x16x32_bf16 v[18:21], v[188:191], v[160:163], v[18:21]
	s_waitcnt lgkmcnt(0)
	v_mfma_f32_16x16x32_bf16 v[14:17], v[198:201], v[148:151], v[14:17]
	v_mfma_f32_16x16x32_bf16 v[10:13], v[198:201], v[152:155], v[10:13]
	v_mfma_f32_16x16x32_bf16 v[6:9], v[198:201], v[156:159], v[6:9]
	v_mfma_f32_16x16x32_bf16 v[2:5], v[198:201], v[160:163], v[2:5]
	s_add_i32 s48, s13, 1
	s_cmp_lg_u32 s13, 2
	s_cselect_b32 s13, s48, 0
	s_add_u32 s40, s40, 64
	s_addc_u32 s41, s41, 0
	s_cmpk_eq_i32 s40, 0x780
	s_cbranch_scc0 .LBB0_194
	s_waitcnt vmcnt(6)
	v_add_u32_e32 v0, v146, v144
	v_add_u32_e32 v194, v145, v144
	s_waitcnt lgkmcnt(0)
	s_barrier
	ds_read_b128 v[130:133], v0
	ds_read_b128 v[134:137], v0 offset:1024
	ds_read_b128 v[138:141], v0 offset:2048
	ds_read_b128 v[146:149], v0 offset:3072
	ds_read_b128 v[142:145], v194 offset:8192
	ds_read_b128 v[150:153], v194 offset:9216
	ds_read_b128 v[154:157], v194 offset:10240
	ds_read_b128 v[158:161], v194 offset:11264
	ds_read_b128 v[162:165], v194 offset:12288
	ds_read_b128 v[166:169], v194 offset:13312
	ds_read_b128 v[170:173], v194 offset:14336
	ds_read_b128 v[174:177], v194 offset:15360
	s_waitcnt lgkmcnt(7)
	v_mfma_f32_16x16x32_bf16 v[126:129], v[142:145], v[130:133], v[126:129]
	v_mfma_f32_16x16x32_bf16 v[122:125], v[142:145], v[134:137], v[122:125]
	v_mfma_f32_16x16x32_bf16 v[118:121], v[142:145], v[138:141], v[118:121]
	v_mfma_f32_16x16x32_bf16 v[114:117], v[142:145], v[146:149], v[114:117]
	s_waitcnt lgkmcnt(6)
	v_mfma_f32_16x16x32_bf16 v[110:113], v[150:153], v[130:133], v[110:113]
	v_mfma_f32_16x16x32_bf16 v[106:109], v[150:153], v[134:137], v[106:109]
	v_mfma_f32_16x16x32_bf16 v[102:105], v[150:153], v[138:141], v[102:105]
	v_mfma_f32_16x16x32_bf16 v[98:101], v[150:153], v[146:149], v[98:101]
	s_waitcnt lgkmcnt(5)
	v_mfma_f32_16x16x32_bf16 v[94:97], v[154:157], v[130:133], v[94:97]
	v_mfma_f32_16x16x32_bf16 v[90:93], v[154:157], v[134:137], v[90:93]
	v_mfma_f32_16x16x32_bf16 v[86:89], v[154:157], v[138:141], v[86:89]
	v_mfma_f32_16x16x32_bf16 v[82:85], v[154:157], v[146:149], v[82:85]
	s_waitcnt lgkmcnt(4)
	v_mfma_f32_16x16x32_bf16 v[78:81], v[158:161], v[130:133], v[78:81]
	v_mfma_f32_16x16x32_bf16 v[74:77], v[158:161], v[134:137], v[74:77]
	v_mfma_f32_16x16x32_bf16 v[70:73], v[158:161], v[138:141], v[70:73]
	v_mfma_f32_16x16x32_bf16 v[66:69], v[158:161], v[146:149], v[66:69]
	s_waitcnt lgkmcnt(3)
	v_mfma_f32_16x16x32_bf16 v[142:145], v[162:165], v[130:133], v[62:65]
	v_mfma_f32_16x16x32_bf16 v[150:153], v[162:165], v[134:137], v[58:61]
	v_mfma_f32_16x16x32_bf16 v[154:157], v[162:165], v[138:141], v[54:57]
	v_mfma_f32_16x16x32_bf16 v[158:161], v[162:165], v[146:149], v[50:53]
	s_waitcnt lgkmcnt(2)
	v_mfma_f32_16x16x32_bf16 v[162:165], v[166:169], v[130:133], v[46:49]
	v_mfma_f32_16x16x32_bf16 v[178:181], v[166:169], v[134:137], v[42:45]
	v_mfma_f32_16x16x32_bf16 v[182:185], v[166:169], v[138:141], v[38:41]
	v_mfma_f32_16x16x32_bf16 v[166:169], v[166:169], v[146:149], v[34:37]
	s_waitcnt lgkmcnt(1)
	v_mfma_f32_16x16x32_bf16 v[186:189], v[170:173], v[130:133], v[30:33]
	v_mfma_f32_16x16x32_bf16 v[190:193], v[170:173], v[134:137], v[26:29]
	v_mfma_f32_16x16x32_bf16 v[198:201], v[170:173], v[138:141], v[22:25]
	v_mfma_f32_16x16x32_bf16 v[170:173], v[170:173], v[146:149], v[18:21]
	s_waitcnt lgkmcnt(0)
	v_mfma_f32_16x16x32_bf16 v[130:133], v[174:177], v[130:133], v[14:17]
	v_mfma_f32_16x16x32_bf16 v[134:137], v[174:177], v[134:137], v[10:13]
	v_mfma_f32_16x16x32_bf16 v[138:141], v[174:177], v[138:141], v[6:9]
	v_mfma_f32_16x16x32_bf16 v[146:149], v[174:177], v[146:149], v[2:5]
	s_waitcnt vmcnt(0)
	s_waitcnt lgkmcnt(0)
	s_barrier
	ds_read_b128 v[174:177], v0 offset:24576
	ds_read_b128 v[202:205], v0 offset:25600
	ds_read_b128 v[216:219], v0 offset:26624
	ds_read_b128 v[226:229], v0 offset:27648
	ds_read_b128 v[14:17], v194 offset:32768
	ds_read_b128 v[30:33], v194 offset:33792
	ds_read_b128 v[46:49], v194 offset:34816
	ds_read_b128 v[62:65], v194 offset:35840
	ds_read_b128 v[230:233], v194 offset:36864
	ds_read_b128 v[234:237], v194 offset:37888
	ds_read_b128 v[238:241], v194 offset:38912
	ds_read_b128 v[242:245], v194 offset:39936
	s_waitcnt lgkmcnt(7)
	v_mfma_f32_16x16x32_bf16 v[2:5], v[14:17], v[174:177], v[126:129]
	v_mfma_f32_16x16x32_bf16 v[6:9], v[14:17], v[202:205], v[122:125]
	v_mfma_f32_16x16x32_bf16 v[10:13], v[14:17], v[216:219], v[118:121]
	v_mfma_f32_16x16x32_bf16 v[14:17], v[14:17], v[226:229], v[114:117]
	s_waitcnt lgkmcnt(6)
	v_mfma_f32_16x16x32_bf16 v[18:21], v[30:33], v[174:177], v[110:113]
	v_mfma_f32_16x16x32_bf16 v[22:25], v[30:33], v[202:205], v[106:109]
	v_mfma_f32_16x16x32_bf16 v[26:29], v[30:33], v[216:219], v[102:105]
	v_mfma_f32_16x16x32_bf16 v[30:33], v[30:33], v[226:229], v[98:101]
	s_waitcnt lgkmcnt(5)
	v_mfma_f32_16x16x32_bf16 v[34:37], v[46:49], v[174:177], v[94:97]
	v_mfma_f32_16x16x32_bf16 v[38:41], v[46:49], v[202:205], v[90:93]
	v_mfma_f32_16x16x32_bf16 v[42:45], v[46:49], v[216:219], v[86:89]
	v_mfma_f32_16x16x32_bf16 v[46:49], v[46:49], v[226:229], v[82:85]
	s_waitcnt lgkmcnt(4)
	v_mfma_f32_16x16x32_bf16 v[50:53], v[62:65], v[174:177], v[78:81]
	v_mfma_f32_16x16x32_bf16 v[54:57], v[62:65], v[202:205], v[74:77]
	v_mfma_f32_16x16x32_bf16 v[58:61], v[62:65], v[216:219], v[70:73]
	v_mfma_f32_16x16x32_bf16 v[62:65], v[62:65], v[226:229], v[66:69]
	s_waitcnt lgkmcnt(3)
	v_mfma_f32_16x16x32_bf16 v[66:69], v[230:233], v[174:177], v[142:145]
	v_mfma_f32_16x16x32_bf16 v[70:73], v[230:233], v[202:205], v[150:153]
	v_mfma_f32_16x16x32_bf16 v[74:77], v[230:233], v[216:219], v[154:157]
	v_mfma_f32_16x16x32_bf16 v[78:81], v[230:233], v[226:229], v[158:161]
	s_waitcnt lgkmcnt(2)
	v_mfma_f32_16x16x32_bf16 v[82:85], v[234:237], v[174:177], v[162:165]
	v_mfma_f32_16x16x32_bf16 v[86:89], v[234:237], v[202:205], v[178:181]
	v_mfma_f32_16x16x32_bf16 v[90:93], v[234:237], v[216:219], v[182:185]
	v_mfma_f32_16x16x32_bf16 v[94:97], v[234:237], v[226:229], v[166:169]
	s_waitcnt lgkmcnt(1)
	v_mfma_f32_16x16x32_bf16 v[98:101], v[238:241], v[174:177], v[186:189]
	v_mfma_f32_16x16x32_bf16 v[102:105], v[238:241], v[202:205], v[190:193]
	v_mfma_f32_16x16x32_bf16 v[106:109], v[238:241], v[216:219], v[198:201]
	v_mfma_f32_16x16x32_bf16 v[110:113], v[238:241], v[226:229], v[170:173]
	s_waitcnt lgkmcnt(0)
	v_mfma_f32_16x16x32_bf16 v[114:117], v[242:245], v[174:177], v[130:133]
	v_mfma_f32_16x16x32_bf16 v[118:121], v[242:245], v[202:205], v[134:137]
	v_mfma_f32_16x16x32_bf16 v[122:125], v[242:245], v[216:219], v[138:141]
	v_mfma_f32_16x16x32_bf16 v[126:129], v[242:245], v[226:229], v[146:149]
	v_mov_b32_e32 v130, v224
	s_ashr_i32 s13, s12, 31
	v_and_b32_e32 v131, 31, v130
	v_ashrrev_i32_e32 v197, 7, v130
	v_ashrrev_i32_e32 v132, 5, v130
	v_lshlrev_b32_e32 v0, 2, v131
	s_lshl_b64 s[48:49], s[12:13], 11
	v_lshlrev_b32_e32 v164, 4, v131
	v_cmp_eq_u32_e64 s[40:41], 0, v131
	v_and_b32_e32 v131, 0x4f, v130
	v_and_b32_e32 v130, 48, v130
	s_movk_i32 s13, 0x210
	v_cmp_lt_i32_e32 vcc, v247, v214
	v_mad_u32_u24 v202, v131, s13, v130
	s_ashr_i32 s47, s46, 31
	v_cndmask_b32_e32 v130, v225, v247, vcc
	v_cmp_lt_i32_e32 vcc, v248, v214
	v_lshlrev_b32_e32 v203, 2, v130
	s_lshl_b32 s69, s57, 1
	v_cndmask_b32_e32 v130, v225, v248, vcc
	v_cmp_lt_i32_e32 vcc, v249, v214
	v_lshlrev_b32_e32 v204, 2, v130
	s_add_u32 s15, s53, s48
	v_cndmask_b32_e32 v130, v225, v249, vcc
	v_cmp_lt_i32_e32 vcc, v223, v214
	v_lshlrev_b32_e32 v205, 2, v130
	v_lshl_or_b32 v0, v132, 10, v0
	v_cndmask_b32_e32 v130, v225, v223, vcc
	v_cmp_lt_i32_e32 vcc, v252, v214
	v_lshlrev_b32_e32 v206, 2, v130
	v_mul_lo_u32 v165, v132, s13
	v_cndmask_b32_e32 v130, v225, v252, vcc
	v_lshlrev_b32_e32 v207, 2, v130
	v_add_u32_e32 v130, s12, v132
	v_ashrrev_i32_e32 v131, 31, v130
	v_lshlrev_b64 v[132:133], 5, v[130:131]
	v_add_u32_e32 v134, 8, v130
	v_add_u32_e32 v136, 16, v130
	v_add_u32_e32 v138, 24, v130
	v_add_u32_e32 v140, 32, v130
	v_add_u32_e32 v142, 40, v130
	v_add_u32_e32 v144, 48, v130
	v_add_u32_e32 v146, 56, v130
	v_add_u32_e32 v148, 64, v130
	v_add_u32_e32 v150, 0x48, v130
	v_add_u32_e32 v152, 0x50, v130
	v_add_u32_e32 v154, 0x58, v130
	v_add_u32_e32 v156, 0x60, v130
	v_add_u32_e32 v158, 0x68, v130
	v_add_u32_e32 v160, 0x70, v130
	v_add_u32_e32 v130, 0x78, v130
	s_addc_u32 s48, s54, s49
	s_lshl_b64 s[12:13], s[46:47], 1
	v_ashrrev_i32_e32 v135, 31, v134
	v_ashrrev_i32_e32 v137, 31, v136
	v_ashrrev_i32_e32 v139, 31, v138
	v_ashrrev_i32_e32 v141, 31, v140
	v_ashrrev_i32_e32 v143, 31, v142
	v_ashrrev_i32_e32 v145, 31, v144
	v_ashrrev_i32_e32 v147, 31, v146
	v_ashrrev_i32_e32 v149, 31, v148
	v_ashrrev_i32_e32 v151, 31, v150
	v_ashrrev_i32_e32 v153, 31, v152
	v_ashrrev_i32_e32 v155, 31, v154
	v_ashrrev_i32_e32 v157, 31, v156
	v_ashrrev_i32_e32 v159, 31, v158
	v_ashrrev_i32_e32 v161, 31, v160
	v_ashrrev_i32_e32 v131, 31, v130
	s_add_u32 s12, s15, s12
	v_lshlrev_b64 v[134:135], 5, v[134:135]
	v_lshlrev_b64 v[136:137], 5, v[136:137]
	v_lshlrev_b64 v[138:139], 5, v[138:139]
	v_lshlrev_b64 v[140:141], 5, v[140:141]
	v_lshlrev_b64 v[142:143], 5, v[142:143]
	v_lshlrev_b64 v[144:145], 5, v[144:145]
	v_lshlrev_b64 v[146:147], 5, v[146:147]
	v_lshlrev_b64 v[148:149], 5, v[148:149]
	v_lshlrev_b64 v[150:151], 5, v[150:151]
	v_lshlrev_b64 v[152:153], 5, v[152:153]
	v_lshlrev_b64 v[154:155], 5, v[154:155]
	v_lshlrev_b64 v[156:157], 5, v[156:157]
	v_lshlrev_b64 v[158:159], 5, v[158:159]
	v_lshlrev_b64 v[160:161], 5, v[160:161]
	v_lshlrev_b64 v[162:163], 5, v[130:131]
	s_addc_u32 s13, s48, s13
	s_mov_b32 s14, 0
	v_lshl_add_u64 v[130:131], v[0:1], 1, s[12:13]
	v_lshl_add_u64 v[132:133], s[42:43], 0, v[132:133]
	v_lshl_add_u64 v[134:135], s[42:43], 0, v[134:135]
	v_lshl_add_u64 v[136:137], s[42:43], 0, v[136:137]
	v_lshl_add_u64 v[138:139], s[42:43], 0, v[138:139]
	v_lshl_add_u64 v[140:141], s[42:43], 0, v[140:141]
	v_lshl_add_u64 v[142:143], s[42:43], 0, v[142:143]
	v_lshl_add_u64 v[144:145], s[42:43], 0, v[144:145]
	v_lshl_add_u64 v[146:147], s[42:43], 0, v[146:147]
	v_lshl_add_u64 v[148:149], s[42:43], 0, v[148:149]
	v_lshl_add_u64 v[150:151], s[42:43], 0, v[150:151]
	v_lshl_add_u64 v[152:153], s[42:43], 0, v[152:153]
	v_lshl_add_u64 v[154:155], s[42:43], 0, v[154:155]
	v_lshl_add_u64 v[156:157], s[42:43], 0, v[156:157]
	v_lshl_add_u64 v[158:159], s[42:43], 0, v[158:159]
	v_lshl_add_u64 v[160:161], s[42:43], 0, v[160:161]
	v_lshl_add_u64 v[162:163], s[42:43], 0, v[162:163]
	s_mov_b64 s[46:47], -1
	v_add_u32_e32 v0, v164, v165
	v_mov_b32_e32 v243, 0x7f800000
	s_branch .LBB0_197

.LBB0_642:
	s_ashr_i32 s13, s12, 31
	s_lshr_b32 s13, s13, 28
	s_add_i32 s13, s12, s13
	s_and_b32 s40, s13, 0x1fffff0
	s_sub_i32 s12, s12, s40
	s_add_i32 s12, s12, s15
	s_lshl_b32 s57, s12, 7
	s_lshl_b32 s12, s13, 4
	s_waitcnt vmcnt(6)
	v_mov_b32_e32 v58, v224
	s_and_b32 s54, s12, 0xffffff00
	s_waitcnt vmcnt(0)
	s_waitcnt lgkmcnt(0)
	v_readfirstlane_b32 s12, v58
	v_bfe_u32 v59, v58, 4, 2
	s_and_b32 s40, s12, 0xffffffc0
	s_waitcnt vmcnt(4)
	v_bfe_u32 v42, v58, 2, 4
	v_sub_u32_e32 v60, 0, v59
	s_add_i32 s40, s40, s54
	v_xor_b32_e32 v0, v58, v60
	v_or_b32_e32 v6, s40, v42
	v_lshlrev_b32_e32 v0, 4, v0
	v_min_i32_e32 v4, 0xa2f, v6
	v_and_b32_e32 v0, 48, v0
	v_ashrrev_i32_e32 v5, 31, v4
	v_lshl_add_u64 v[2:3], s[48:49], 0, v[0:1]
	v_lshlrev_b64 v[4:5], 11, v[4:5]
	v_lshl_add_u64 v[34:35], v[2:3], 0, v[4:5]
	v_or_b32_e32 v4, 16, v6
	v_min_i32_e32 v4, 0xa2f, v4
	v_ashrrev_i32_e32 v5, 31, v4
	v_lshlrev_b64 v[4:5], 11, v[4:5]
	v_lshl_add_u64 v[36:37], v[2:3], 0, v[4:5]
	v_or_b32_e32 v4, 32, v6
	v_min_i32_e32 v4, 0xa2f, v4
	s_ashr_i32 s13, s12, 6
	v_ashrrev_i32_e32 v5, 31, v4
	s_and_b32 s42, s13, 1
	v_lshlrev_b64 v[4:5], 11, v[4:5]
	v_lshl_add_u64 v[38:39], v[2:3], 0, v[4:5]
	v_or_b32_e32 v4, 48, v6
	s_lshl_b32 s40, s42, 6
	v_min_i32_e32 v4, 0xa2f, v4
	v_and_b32_e32 v61, 15, v58
	s_or_b32 s40, s40, s57
	v_ashrrev_i32_e32 v5, 31, v4
	s_waitcnt vmcnt(1)
	v_or_b32_e32 v14, s40, v61
	v_lshlrev_b64 v[4:5], 11, v[4:5]
	v_ashrrev_i32_e32 v15, 31, v14
	v_lshl_add_u64 v[40:41], v[2:3], 0, v[4:5]
	v_lshlrev_b64 v[2:3], 5, v[14:15]
	v_lshl_add_u64 v[6:7], s[46:47], 0, v[2:3]
	s_barrier
	global_load_dwordx4 v[2:5], v[6:7], off offset:16
	global_load_dwordx4 v[18:21], v[6:7], off
	v_or_b32_e32 v6, 16, v14
	v_ashrrev_i32_e32 v7, 31, v6
	v_lshlrev_b64 v[6:7], 5, v[6:7]
	v_lshl_add_u64 v[10:11], s[46:47], 0, v[6:7]
	global_load_dwordx4 v[6:9], v[10:11], off offset:16
	global_load_dwordx4 v[22:25], v[10:11], off
	v_or_b32_e32 v10, 32, v14
	v_or_b32_e32 v14, 48, v14
	v_ashrrev_i32_e32 v11, 31, v10
	v_ashrrev_i32_e32 v15, 31, v14
	v_lshlrev_b64 v[10:11], 5, v[10:11]
	v_lshlrev_b64 v[14:15], 5, v[14:15]
	v_lshl_add_u64 v[16:17], s[46:47], 0, v[10:11]
	v_lshl_add_u64 v[30:31], s[46:47], 0, v[14:15]
	global_load_dwordx4 v[10:13], v[16:17], off offset:16
	global_load_dwordx4 v[26:29], v[16:17], off
	s_nop 0
	global_load_dwordx4 v[14:17], v[30:31], off offset:16
	s_nop 0
	global_load_dwordx4 v[30:33], v[30:31], off
	s_lshl_b32 s40, s13, 1
	s_waitcnt vmcnt(8)
	v_or_b32_e32 v46, s57, v42
	v_lshl_add_u32 v44, s13, 5, v46
	s_lshl_b32 s41, s40, 10
	s_or_b32 s40, s40, 1
	v_ashrrev_i32_e32 v45, 31, v44
	v_lshl_add_u32 v46, s40, 4, v46
	v_lshl_add_u64 v[42:43], s[0:1], 0, v[0:1]
	v_lshlrev_b64 v[162:163], 10, v[44:45]
	v_lshlrev_b64 v[44:45], 11, v[44:45]
	v_ashrrev_i32_e32 v47, 31, v46
	v_lshl_add_u64 v[44:45], v[42:43], 0, v[44:45]
	v_lshlrev_b64 v[164:165], 10, v[46:47]
	v_lshlrev_b64 v[46:47], 11, v[46:47]
	s_mov_b32 s45, m0
	s_mov_b32 m0, s41
	s_nop 0
	global_load_lds_dwordx4 v[44:45], off
	s_mov_b32 m0, s45
	v_lshl_add_u64 v[42:43], v[42:43], 0, v[46:47]
	s_lshl_b32 s43, s13, 12
	s_add_i32 s44, s41, 0x6000
	s_lshl_b32 s40, s40, 10
	s_mov_b32 s41, m0
	s_mov_b32 m0, s40
	s_nop 0
	global_load_lds_dwordx4 v[42:43], off
	s_mov_b32 m0, s41
	s_add_i32 s41, s43, 0x2000
	s_mov_b32 s45, m0
	s_mov_b32 m0, s41
	s_nop 0
	global_load_lds_dwordx4 v[34:35], off
	s_mov_b32 m0, s45
	s_add_i32 s45, s43, 0x2400
	s_mov_b32 s55, m0
	s_mov_b32 m0, s45
	s_nop 0
	global_load_lds_dwordx4 v[36:37], off
	s_mov_b32 m0, s55
	s_add_i32 s45, s43, 0x2800
	s_mov_b32 s55, m0
	s_mov_b32 m0, s45
	s_nop 0
	global_load_lds_dwordx4 v[38:39], off
	s_mov_b32 m0, s55
	s_add_i32 s45, s43, 0x2c00
	s_mov_b32 s55, m0
	s_mov_b32 m0, s45
	s_nop 0
	global_load_lds_dwordx4 v[40:41], off
	s_mov_b32 m0, s55
	v_lshl_add_u64 v[46:47], v[44:45], 0, 64
	s_mov_b32 s45, m0
	s_mov_b32 m0, s44
	s_nop 0
	global_load_lds_dwordx4 v[46:47], off
	s_mov_b32 m0, s45
	v_lshl_add_u64 v[48:49], v[42:43], 0, 64
	s_add_i32 s44, s40, 0x6000
	s_mov_b32 s45, m0
	s_mov_b32 m0, s44
	s_nop 0
	global_load_lds_dwordx4 v[48:49], off
	s_mov_b32 m0, s45
	v_lshrrev_b32_e32 v0, 2, v58
	v_lshl_add_u64 v[50:51], v[34:35], 0, 64
	s_add_i32 s44, s43, 0x8000
	s_mov_b32 s45, m0
	s_mov_b32 m0, s44
	s_nop 0
	global_load_lds_dwordx4 v[50:51], off
	s_mov_b32 m0, s45
	v_sub_u32_e32 v0, 0, v0
	v_lshl_add_u64 v[52:53], v[36:37], 0, 64
	s_add_i32 s44, s43, 0x8400
	s_mov_b32 s45, m0
	s_mov_b32 m0, s44
	s_nop 0
	global_load_lds_dwordx4 v[52:53], off
	s_mov_b32 m0, s45
	v_bitop3_b32 v0, v59, v0, 3 bitop3:0x78
	s_and_b32 s12, s12, 0x3ffff80
	v_lshl_add_u64 v[54:55], v[38:39], 0, 64
	s_add_i32 s44, s43, 0x8800
	s_mov_b32 s45, m0
	s_mov_b32 m0, s44
	s_nop 0
	global_load_lds_dwordx4 v[54:55], off
	s_mov_b32 m0, s45
	v_lshlrev_b32_e32 v176, 4, v0
	v_or_b32_e32 v0, s12, v61
	v_lshl_add_u64 v[56:57], v[40:41], 0, 64
	s_add_i32 s43, s43, 0x8c00
	s_mov_b32 s44, m0
	s_mov_b32 m0, s43
	s_nop 0
	global_load_lds_dwordx4 v[56:57], off
	s_mov_b32 m0, s44
	v_lshlrev_b32_e32 v178, 6, v0
	v_bitop3_b32 v0, v58, 3, v60 bitop3:0x48
	v_lshl_add_u64 v[172:173], v[34:35], 0, s[6:7]
	v_lshlrev_b32_e32 v0, 4, v0
	v_mov_b32_e32 v34, 0
	s_lshl_b32 s55, s42, 12
	v_lshlrev_b32_e32 v177, 6, v61
	s_lshl_b32 s42, s13, 11
	v_lshl_add_u64 v[166:167], v[40:41], 0, s[6:7]
	v_lshl_add_u64 v[168:169], v[38:39], 0, s[6:7]
	v_lshl_add_u64 v[170:171], v[36:37], 0, s[6:7]
	v_lshl_add_u64 v[174:175], s[52:53], 0, v[0:1]
	s_mov_b64 s[12:13], 0
	s_mov_b32 s43, 0
	v_mov_b32_e32 v35, v34
	v_mov_b32_e32 v36, v34
	v_mov_b32_e32 v37, v34
	v_mov_b32_e32 v38, v34
	v_mov_b32_e32 v39, v34
	v_mov_b32_e32 v40, v34
	v_mov_b32_e32 v41, v34
	v_mov_b32_e32 v42, v34
	v_mov_b32_e32 v43, v34
	v_mov_b32_e32 v44, v34
	v_mov_b32_e32 v45, v34
	v_mov_b32_e32 v46, v34
	v_mov_b32_e32 v47, v34
	v_mov_b32_e32 v48, v34
	v_mov_b32_e32 v49, v34
	v_mov_b32_e32 v50, v34
	v_mov_b32_e32 v51, v34
	v_mov_b32_e32 v52, v34
	v_mov_b32_e32 v53, v34
	v_mov_b32_e32 v54, v34
	v_mov_b32_e32 v55, v34
	v_mov_b32_e32 v56, v34
	v_mov_b32_e32 v57, v34
	v_mov_b32_e32 v58, v34
	v_mov_b32_e32 v59, v34
	v_mov_b32_e32 v60, v34
	v_mov_b32_e32 v61, v34
	v_mov_b32_e32 v62, v34
	v_mov_b32_e32 v63, v34
	v_mov_b32_e32 v64, v34
	v_mov_b32_e32 v65, v34
	v_mov_b32_e32 v66, v34
	v_mov_b32_e32 v67, v34
	v_mov_b32_e32 v68, v34
	v_mov_b32_e32 v69, v34
	v_mov_b32_e32 v70, v34
	v_mov_b32_e32 v71, v34
	v_mov_b32_e32 v72, v34
	v_mov_b32_e32 v73, v34
	v_mov_b32_e32 v74, v34
	v_mov_b32_e32 v75, v34
	v_mov_b32_e32 v76, v34
	v_mov_b32_e32 v77, v34
	v_mov_b32_e32 v78, v34
	v_mov_b32_e32 v79, v34
	v_mov_b32_e32 v80, v34
	v_mov_b32_e32 v81, v34
	v_mov_b32_e32 v82, v34
	v_mov_b32_e32 v83, v34
	v_mov_b32_e32 v84, v34
	v_mov_b32_e32 v85, v34
	v_mov_b32_e32 v86, v34
	v_mov_b32_e32 v87, v34
	v_mov_b32_e32 v88, v34
	v_mov_b32_e32 v89, v34
	v_mov_b32_e32 v90, v34
	v_mov_b32_e32 v91, v34
	v_mov_b32_e32 v92, v34
	v_mov_b32_e32 v93, v34
	v_mov_b32_e32 v94, v34
	v_mov_b32_e32 v95, v34
	v_mov_b32_e32 v96, v34
	v_mov_b32_e32 v97, v34
	v_mov_b32_e32 v98, v34
	v_mov_b32_e32 v99, v34
	v_mov_b32_e32 v100, v34
	v_mov_b32_e32 v101, v34
	v_mov_b32_e32 v102, v34
	v_mov_b32_e32 v103, v34
	v_mov_b32_e32 v104, v34
	v_mov_b32_e32 v105, v34
	v_mov_b32_e32 v106, v34
	v_mov_b32_e32 v107, v34
	v_mov_b32_e32 v108, v34
	v_mov_b32_e32 v109, v34
	v_mov_b32_e32 v110, v34
	v_mov_b32_e32 v111, v34
	v_mov_b32_e32 v112, v34
	v_mov_b32_e32 v113, v34
	v_mov_b32_e32 v114, v34
	v_mov_b32_e32 v115, v34
	v_mov_b32_e32 v116, v34
	v_mov_b32_e32 v117, v34
	v_mov_b32_e32 v118, v34
	v_mov_b32_e32 v119, v34
	v_mov_b32_e32 v120, v34
	v_mov_b32_e32 v121, v34
	v_mov_b32_e32 v122, v34
	v_mov_b32_e32 v123, v34
	v_mov_b32_e32 v124, v34
	v_mov_b32_e32 v125, v34
	v_mov_b32_e32 v126, v34
	v_mov_b32_e32 v127, v34
	v_mov_b32_e32 v128, v34
	v_mov_b32_e32 v129, v34
	v_mov_b32_e32 v130, v34
	v_mov_b32_e32 v131, v34
	v_mov_b32_e32 v132, v34
	v_mov_b32_e32 v133, v34
	v_mov_b32_e32 v134, v34
	v_mov_b32_e32 v135, v34
	v_mov_b32_e32 v136, v34
	v_mov_b32_e32 v137, v34
	v_mov_b32_e32 v138, v34
	v_mov_b32_e32 v139, v34
	v_mov_b32_e32 v140, v34
	v_mov_b32_e32 v141, v34
	v_mov_b32_e32 v142, v34
	v_mov_b32_e32 v143, v34
	v_mov_b32_e32 v144, v34
	v_mov_b32_e32 v145, v34
	v_mov_b32_e32 v146, v34
	v_mov_b32_e32 v147, v34
	v_mov_b32_e32 v148, v34
	v_mov_b32_e32 v149, v34
	v_mov_b32_e32 v150, v34
	v_mov_b32_e32 v151, v34
	v_mov_b32_e32 v152, v34
	v_mov_b32_e32 v153, v34
	v_mov_b32_e32 v154, v34
	v_mov_b32_e32 v155, v34
	v_mov_b32_e32 v156, v34
	v_mov_b32_e32 v157, v34
	v_mov_b32_e32 v158, v34
	v_mov_b32_e32 v159, v34
	v_mov_b32_e32 v160, v34
	v_mov_b32_e32 v161, v34
	v_lshl_add_u64 v[162:163], v[162:163], 1, v[174:175]
	v_lshl_add_u64 v[164:165], v[164:165], 1, v[174:175]
.LBB0_643:
	s_mul_i32 s44, s43, 0x6000
	s_add_i32 s45, s44, 0xffffa000
	s_cmp_gt_i32 s43, 0
	s_waitcnt vmcnt(6)
	s_cselect_b32 s45, s45, 0xc000
	s_waitcnt lgkmcnt(0)
	s_barrier
	s_setprio 2
	v_add3_u32 v0, s44, v177, v176
	v_add_u32_e32 v0, s55, v0
	v_add3_u32 v212, s44, v178, v176
	ds_read_b128 v[202:205], v212 offset:8192
	ds_read_b128 v[180:183], v0
	ds_read_b128 v[184:187], v0 offset:1024
	ds_read_b128 v[188:191], v0 offset:2048
	ds_read_b128 v[198:201], v0 offset:3072
	ds_read_b128 v[234:237], v212 offset:9216
	ds_read_b128 v[238:241], v212 offset:10240
	ds_read_b128 v[242:245], v212 offset:11264
	ds_read_b128 v[246:249], v212 offset:12288
	ds_read_b128 v[226:229], v212 offset:13312
	ds_read_b128 v[216:219], v212 offset:14336
	ds_read_b128 v[230:233], v212 offset:15360
	s_add_i32 s68, s45, s42
	s_mov_b32 m0, s68
	s_nop 0
	global_load_lds_dwordx4 v[162:163], off
	s_add_i32 s68, s45, s40
	s_mov_b32 m0, s68
	s_nop 0
	global_load_lds_dwordx4 v[164:165], off
	s_add_i32 s45, s41, s45
	s_mov_b32 m0, s45
	s_nop 0
	global_load_lds_dwordx4 v[172:173], off
	s_add_i32 s68, s45, 0x400
	s_mov_b32 m0, s68
	s_nop 0
	global_load_lds_dwordx4 v[170:171], off
	s_add_i32 s68, s45, 0x800
	s_mov_b32 m0, s68
	s_nop 0
	global_load_lds_dwordx4 v[168:169], off
	s_addk_i32 s45, 0xc00
	s_mov_b32 m0, s45
	s_nop 0
	global_load_lds_dwordx4 v[166:167], off
	s_setprio 0
	s_waitcnt lgkmcnt(10)
	v_mfma_f32_16x16x32_bf16 v[34:37], v[202:205], v[180:183], v[34:37]
	s_waitcnt lgkmcnt(9)
	v_mfma_f32_16x16x32_bf16 v[38:41], v[202:205], v[184:187], v[38:41]
	s_waitcnt lgkmcnt(8)
	v_mfma_f32_16x16x32_bf16 v[42:45], v[202:205], v[188:191], v[42:45]
	s_waitcnt lgkmcnt(7)
	v_mfma_f32_16x16x32_bf16 v[46:49], v[202:205], v[198:201], v[46:49]
	s_waitcnt lgkmcnt(6)
	v_mfma_f32_16x16x32_bf16 v[50:53], v[234:237], v[180:183], v[50:53]
	v_mfma_f32_16x16x32_bf16 v[54:57], v[234:237], v[184:187], v[54:57]
	v_lshl_add_u64 v[162:163], v[162:163], 0, 64
	v_mfma_f32_16x16x32_bf16 v[58:61], v[234:237], v[188:191], v[58:61]
	v_mfma_f32_16x16x32_bf16 v[62:65], v[234:237], v[198:201], v[62:65]
	s_waitcnt lgkmcnt(5)
	v_mfma_f32_16x16x32_bf16 v[66:69], v[238:241], v[180:183], v[66:69]
	v_mfma_f32_16x16x32_bf16 v[70:73], v[238:241], v[184:187], v[70:73]
	v_lshl_add_u64 v[164:165], v[164:165], 0, 64
	v_mfma_f32_16x16x32_bf16 v[74:77], v[238:241], v[188:191], v[74:77]
	v_mfma_f32_16x16x32_bf16 v[78:81], v[238:241], v[198:201], v[78:81]
	s_waitcnt lgkmcnt(4)
	v_mfma_f32_16x16x32_bf16 v[82:85], v[242:245], v[180:183], v[82:85]
	v_mfma_f32_16x16x32_bf16 v[86:89], v[242:245], v[184:187], v[86:89]
	v_lshl_add_u64 v[172:173], v[172:173], 0, 64
	v_mfma_f32_16x16x32_bf16 v[90:93], v[242:245], v[188:191], v[90:93]
	v_mfma_f32_16x16x32_bf16 v[94:97], v[242:245], v[198:201], v[94:97]
	s_waitcnt lgkmcnt(3)
	v_mfma_f32_16x16x32_bf16 v[98:101], v[246:249], v[180:183], v[98:101]
	v_mfma_f32_16x16x32_bf16 v[102:105], v[246:249], v[184:187], v[102:105]
	v_lshl_add_u64 v[170:171], v[170:171], 0, 64
	v_mfma_f32_16x16x32_bf16 v[106:109], v[246:249], v[188:191], v[106:109]
	v_mfma_f32_16x16x32_bf16 v[110:113], v[246:249], v[198:201], v[110:113]
	s_waitcnt lgkmcnt(2)
	v_mfma_f32_16x16x32_bf16 v[114:117], v[226:229], v[180:183], v[114:117]
	v_mfma_f32_16x16x32_bf16 v[118:121], v[226:229], v[184:187], v[118:121]
	v_lshl_add_u64 v[168:169], v[168:169], 0, 64
	v_mfma_f32_16x16x32_bf16 v[122:125], v[226:229], v[188:191], v[122:125]
	v_mfma_f32_16x16x32_bf16 v[126:129], v[226:229], v[198:201], v[126:129]
	s_waitcnt lgkmcnt(1)
	v_mfma_f32_16x16x32_bf16 v[130:133], v[216:219], v[180:183], v[130:133]
	v_mfma_f32_16x16x32_bf16 v[134:137], v[216:219], v[184:187], v[134:137]
	v_lshl_add_u64 v[166:167], v[166:167], 0, 64
	v_mfma_f32_16x16x32_bf16 v[138:141], v[216:219], v[188:191], v[138:141]
	v_mfma_f32_16x16x32_bf16 v[142:145], v[216:219], v[198:201], v[142:145]
	s_waitcnt lgkmcnt(0)
	v_mfma_f32_16x16x32_bf16 v[146:149], v[230:233], v[180:183], v[146:149]
	v_mfma_f32_16x16x32_bf16 v[150:153], v[230:233], v[184:187], v[150:153]
	v_mfma_f32_16x16x32_bf16 v[154:157], v[230:233], v[188:191], v[154:157]
	v_mfma_f32_16x16x32_bf16 v[158:161], v[230:233], v[198:201], v[158:161]
	s_add_i32 s44, s43, 1
	s_cmp_lg_u32 s43, 2
	s_cselect_b32 s43, s44, 0
	s_add_u32 s12, s12, 64
	s_addc_u32 s13, s13, 0
	s_cmpk_eq_i32 s12, 0x780
	s_cbranch_scc0 .LBB0_643
	s_waitcnt vmcnt(6)
	v_mov_b32_e32 v162, v19
	v_mov_b32_e32 v163, v20
	v_mov_b32_e32 v19, v21
	v_mov_b32_e32 v164, v3
	v_mov_b32_e32 v165, v4
	v_pk_add_f32 v[18:19], v[162:163], v[18:19]
	v_mov_b32_e32 v3, v5
	v_pk_add_f32 v[2:3], v[164:165], v[2:3]
	v_add_f32_e32 v0, v18, v19
	v_add_f32_e32 v0, v0, v2
	v_add_f32_e32 v0, v0, v3
	v_fmamk_f32 v0, v0, 0x3a800000, v250
	s_waitcnt vmcnt(4)
	v_mov_b32_e32 v166, v23
	v_mov_b32_e32 v167, v24
	v_mul_f32_e32 v2, 0x4b800000, v0
	v_cmp_gt_f32_e32 vcc, s80, v0
	v_mov_b32_e32 v23, v25
	v_mov_b32_e32 v168, v7
	v_mov_b32_e32 v169, v8
	v_cndmask_b32_e32 v0, v0, v2, vcc
	v_pk_add_f32 v[2:3], v[166:167], v[22:23]
	v_mov_b32_e32 v7, v9
	v_pk_add_f32 v[4:5], v[168:169], v[6:7]
	v_add_f32_e32 v2, v2, v3
	v_add_f32_e32 v2, v2, v4
	v_add_f32_e32 v2, v2, v5
	v_fmamk_f32 v2, v2, 0x3a800000, v250
	v_mul_f32_e32 v3, 0x4b800000, v2
	v_cmp_gt_f32_e64 s[40:41], s80, v2
	s_waitcnt vmcnt(2)
	v_mov_b32_e32 v170, v27
	v_mov_b32_e32 v171, v28
	v_cndmask_b32_e64 v2, v2, v3, s[40:41]
	v_mov_b32_e32 v27, v29
	v_mov_b32_e32 v172, v11
	v_mov_b32_e32 v173, v12
	v_rsq_f32_e32 v179, v2
	v_pk_add_f32 v[2:3], v[170:171], v[26:27]
	v_mov_b32_e32 v11, v13
	v_pk_add_f32 v[4:5], v[172:173], v[10:11]
	v_add_f32_e32 v2, v2, v3
	v_add_f32_e32 v2, v2, v4
	v_add_f32_e32 v2, v2, v5
	v_fmamk_f32 v2, v2, 0x3a800000, v250
	v_mul_f32_e32 v3, 0x4b800000, v2
	v_cmp_gt_f32_e64 s[42:43], s80, v2
	s_waitcnt vmcnt(0)
	v_mov_b32_e32 v174, v31
	v_mov_b32_e32 v175, v32
	v_cndmask_b32_e64 v2, v2, v3, s[42:43]
	v_mov_b32_e32 v31, v33
	v_mov_b32_e32 v180, v15
	v_mov_b32_e32 v181, v16
	v_rsq_f32_e32 v182, v2
	v_pk_add_f32 v[2:3], v[174:175], v[30:31]
	v_mov_b32_e32 v15, v17
	v_pk_add_f32 v[4:5], v[180:181], v[14:15]
	v_add_f32_e32 v2, v2, v3
	v_add_f32_e32 v2, v2, v4
	v_add_f32_e32 v2, v2, v5
	v_fmamk_f32 v2, v2, 0x3a800000, v250
	v_mul_f32_e32 v3, 0x4b800000, v2
	v_cmp_gt_f32_e64 s[44:45], s80, v2
	s_waitcnt vmcnt(6)
	v_add_u32_e32 v183, v178, v176
	s_waitcnt lgkmcnt(0)
	s_barrier
	v_cndmask_b32_e64 v2, v2, v3, s[44:45]
	v_rsq_f32_e32 v180, v2
	ds_read_b128 v[2:5], v183 offset:15360
	ds_read_b128 v[6:9], v183 offset:14336
	ds_read_b128 v[10:13], v183 offset:13312
	ds_read_b128 v[14:17], v183 offset:12288
	ds_read_b128 v[18:21], v183 offset:11264
	ds_read_b128 v[22:25], v183 offset:10240
	ds_read_b128 v[26:29], v183 offset:9216
	ds_read_b128 v[30:33], v183 offset:8192
	v_add3_u32 v178, s55, v177, v176
	ds_read_b128 v[162:165], v178 offset:3072
	ds_read_b128 v[166:169], v178 offset:2048
	ds_read_b128 v[170:173], v178 offset:1024
	ds_read_b128 v[174:177], v178
	v_rsq_f32_e32 v0, v0
	v_mul_f32_e32 v184, 0x45800000, v179
	v_mul_f32_e32 v185, 0x45800000, v182
	v_mul_f32_e32 v186, 0x45800000, v180
	v_mul_f32_e32 v181, 0x45800000, v0
	s_waitcnt lgkmcnt(0)
	v_mfma_f32_16x16x32_bf16 v[34:37], v[30:33], v[174:177], v[34:37]
	v_mfma_f32_16x16x32_bf16 v[38:41], v[30:33], v[170:173], v[38:41]
	v_mfma_f32_16x16x32_bf16 v[42:45], v[30:33], v[166:169], v[42:45]
	v_mfma_f32_16x16x32_bf16 v[30:33], v[30:33], v[162:165], v[46:49]
	v_mfma_f32_16x16x32_bf16 v[46:49], v[26:29], v[174:177], v[50:53]
	v_mfma_f32_16x16x32_bf16 v[50:53], v[26:29], v[170:173], v[54:57]
	v_mfma_f32_16x16x32_bf16 v[54:57], v[26:29], v[166:169], v[58:61]
	v_mfma_f32_16x16x32_bf16 v[58:61], v[26:29], v[162:165], v[62:65]
	v_mfma_f32_16x16x32_bf16 v[62:65], v[22:25], v[174:177], v[66:69]
	v_mfma_f32_16x16x32_bf16 v[66:69], v[22:25], v[170:173], v[70:73]
	v_mfma_f32_16x16x32_bf16 v[70:73], v[22:25], v[166:169], v[74:77]
	v_mfma_f32_16x16x32_bf16 v[74:77], v[22:25], v[162:165], v[78:81]
	v_mfma_f32_16x16x32_bf16 v[78:81], v[18:21], v[174:177], v[82:85]
	v_mfma_f32_16x16x32_bf16 v[82:85], v[18:21], v[170:173], v[86:89]
	v_mfma_f32_16x16x32_bf16 v[86:89], v[18:21], v[166:169], v[90:93]
	v_mfma_f32_16x16x32_bf16 v[18:21], v[18:21], v[162:165], v[94:97]
	v_mfma_f32_16x16x32_bf16 v[90:93], v[14:17], v[174:177], v[98:101]
	v_mfma_f32_16x16x32_bf16 v[94:97], v[14:17], v[170:173], v[102:105]
	v_mfma_f32_16x16x32_bf16 v[98:101], v[14:17], v[166:169], v[106:109]
	v_mfma_f32_16x16x32_bf16 v[14:17], v[14:17], v[162:165], v[110:113]
	v_mfma_f32_16x16x32_bf16 v[102:105], v[10:13], v[174:177], v[114:117]
	v_mfma_f32_16x16x32_bf16 v[106:109], v[10:13], v[170:173], v[118:121]
	v_mfma_f32_16x16x32_bf16 v[110:113], v[10:13], v[166:169], v[122:125]
	v_mfma_f32_16x16x32_bf16 v[10:13], v[10:13], v[162:165], v[126:129]
	v_mfma_f32_16x16x32_bf16 v[114:117], v[6:9], v[174:177], v[130:133]
	v_mfma_f32_16x16x32_bf16 v[118:121], v[6:9], v[170:173], v[134:137]
	v_mfma_f32_16x16x32_bf16 v[122:125], v[6:9], v[166:169], v[138:141]
	v_mfma_f32_16x16x32_bf16 v[6:9], v[6:9], v[162:165], v[142:145]
	v_mfma_f32_16x16x32_bf16 v[126:129], v[2:5], v[174:177], v[146:149]
	v_mfma_f32_16x16x32_bf16 v[130:133], v[2:5], v[170:173], v[150:153]
	v_mfma_f32_16x16x32_bf16 v[134:137], v[2:5], v[166:169], v[154:157]
	v_mfma_f32_16x16x32_bf16 v[2:5], v[2:5], v[162:165], v[158:161]
	s_waitcnt vmcnt(0)
	v_cndmask_b32_e32 v26, v0, v181, vcc
	v_cndmask_b32_e64 v24, v179, v184, s[40:41]
	v_cndmask_b32_e64 v22, v182, v185, s[42:43]
	v_cndmask_b32_e64 v0, v180, v186, s[44:45]
	s_waitcnt lgkmcnt(0)
	s_barrier
	ds_read_b128 v[138:141], v178 offset:24576
	ds_read_b128 v[142:145], v178 offset:25600
	ds_read_b128 v[146:149], v178 offset:26624
	ds_read_b128 v[150:153], v178 offset:27648
	ds_read_b128 v[154:157], v183 offset:32768
	ds_read_b128 v[158:161], v183 offset:33792
	ds_read_b128 v[162:165], v183 offset:34816
	ds_read_b128 v[166:169], v183 offset:35840
	ds_read_b128 v[170:173], v183 offset:36864
	ds_read_b128 v[174:177], v183 offset:37888
	ds_read_b128 v[178:181], v183 offset:38912
	ds_read_b128 v[182:185], v183 offset:39936
	s_waitcnt lgkmcnt(7)
	v_mfma_f32_16x16x32_bf16 v[34:37], v[154:157], v[138:141], v[34:37]
	v_mfma_f32_16x16x32_bf16 v[38:41], v[154:157], v[142:145], v[38:41]
	v_mfma_f32_16x16x32_bf16 v[42:45], v[154:157], v[146:149], v[42:45]
	v_mfma_f32_16x16x32_bf16 v[28:31], v[154:157], v[150:153], v[30:33]
	s_waitcnt lgkmcnt(6)
	v_mfma_f32_16x16x32_bf16 v[46:49], v[158:161], v[138:141], v[46:49]
	v_mfma_f32_16x16x32_bf16 v[50:53], v[158:161], v[142:145], v[50:53]
	v_mfma_f32_16x16x32_bf16 v[54:57], v[158:161], v[146:149], v[54:57]
	v_mfma_f32_16x16x32_bf16 v[58:61], v[158:161], v[150:153], v[58:61]
	s_waitcnt lgkmcnt(5)
	v_mfma_f32_16x16x32_bf16 v[62:65], v[162:165], v[138:141], v[62:65]
	v_mfma_f32_16x16x32_bf16 v[66:69], v[162:165], v[142:145], v[66:69]
	v_mfma_f32_16x16x32_bf16 v[70:73], v[162:165], v[146:149], v[70:73]
	v_mfma_f32_16x16x32_bf16 v[74:77], v[162:165], v[150:153], v[74:77]
	s_waitcnt lgkmcnt(4)
	v_mfma_f32_16x16x32_bf16 v[78:81], v[166:169], v[138:141], v[78:81]
	v_mfma_f32_16x16x32_bf16 v[82:85], v[166:169], v[142:145], v[82:85]
	v_mfma_f32_16x16x32_bf16 v[86:89], v[166:169], v[146:149], v[86:89]
	v_mfma_f32_16x16x32_bf16 v[154:157], v[166:169], v[150:153], v[18:21]
	s_waitcnt lgkmcnt(3)
	v_mfma_f32_16x16x32_bf16 v[90:93], v[170:173], v[138:141], v[90:93]
	v_mfma_f32_16x16x32_bf16 v[94:97], v[170:173], v[142:145], v[94:97]
	v_mfma_f32_16x16x32_bf16 v[98:101], v[170:173], v[146:149], v[98:101]
	v_mfma_f32_16x16x32_bf16 v[158:161], v[170:173], v[150:153], v[14:17]
	s_waitcnt lgkmcnt(2)
	v_mfma_f32_16x16x32_bf16 v[102:105], v[174:177], v[138:141], v[102:105]
	v_mfma_f32_16x16x32_bf16 v[106:109], v[174:177], v[142:145], v[106:109]
	v_mfma_f32_16x16x32_bf16 v[110:113], v[174:177], v[146:149], v[110:113]
	v_mfma_f32_16x16x32_bf16 v[162:165], v[174:177], v[150:153], v[10:13]
	s_waitcnt lgkmcnt(1)
	v_mfma_f32_16x16x32_bf16 v[114:117], v[178:181], v[138:141], v[114:117]
	v_mfma_f32_16x16x32_bf16 v[118:121], v[178:181], v[142:145], v[118:121]
	v_mfma_f32_16x16x32_bf16 v[122:125], v[178:181], v[146:149], v[122:125]
	v_mfma_f32_16x16x32_bf16 v[18:21], v[178:181], v[150:153], v[6:9]
	s_waitcnt lgkmcnt(0)
	v_mfma_f32_16x16x32_bf16 v[14:17], v[182:185], v[138:141], v[126:129]
	v_mfma_f32_16x16x32_bf16 v[10:13], v[182:185], v[142:145], v[130:133]
	v_mfma_f32_16x16x32_bf16 v[6:9], v[182:185], v[146:149], v[134:137]
	v_mfma_f32_16x16x32_bf16 v[2:5], v[182:185], v[150:153], v[2:5]
	v_mov_b32_e32 v23, v224
	s_movk_i32 s12, 0x210
	v_lshrrev_b32_e32 v32, 1, v23
	v_and_b32_e32 v27, 0x7fffff80, v23
	v_and_b32_e32 v32, 24, v32
	v_and_b32_e32 v25, 0x4f, v23
	v_lshl_or_b32 v27, v27, 1, v32
	v_pk_mul_f32 v[32:33], v[26:27], v[34:35] op_sel_hi:[0,1]
	v_pk_mul_f32 v[34:35], v[26:27], v[36:37] op_sel_hi:[0,1]
	v_mad_u32_u24 v25, v25, s12, v27
	v_cvt_pk_bf16_f32 v32, v32, v33
	v_cvt_pk_bf16_f32 v33, v34, v35
	v_pk_mul_f32 v[34:35], v[24:25], v[38:39] op_sel_hi:[0,1]
	v_pk_mul_f32 v[36:37], v[24:25], v[40:41] op_sel_hi:[0,1]
	v_cvt_pk_bf16_f32 v34, v34, v35
	v_cvt_pk_bf16_f32 v35, v36, v37
	v_pk_mul_f32 v[36:37], v[22:23], v[42:43] op_sel_hi:[0,1]
	v_pk_mul_f32 v[38:39], v[22:23], v[44:45] op_sel_hi:[0,1]
	v_pk_mul_f32 v[28:29], v[0:1], v[28:29] op_sel_hi:[0,1]
	v_pk_mul_f32 v[30:31], v[0:1], v[30:31] op_sel_hi:[0,1]
	v_cvt_pk_bf16_f32 v36, v36, v37
	v_cvt_pk_bf16_f32 v37, v38, v39
	v_cvt_pk_bf16_f32 v28, v28, v29
	v_cvt_pk_bf16_f32 v29, v30, v31
	v_pk_mul_f32 v[30:31], v[26:27], v[46:47] op_sel_hi:[0,1]
	v_pk_mul_f32 v[38:39], v[26:27], v[48:49] op_sel_hi:[0,1]
	v_cvt_pk_bf16_f32 v30, v30, v31
	v_cvt_pk_bf16_f32 v31, v38, v39
	s_barrier
	ds_write2_b64 v25, v[32:33], v[30:31] offset1:4
	v_pk_mul_f32 v[30:31], v[24:25], v[50:51] op_sel_hi:[0,1]
	v_pk_mul_f32 v[32:33], v[24:25], v[52:53] op_sel_hi:[0,1]
	v_cvt_pk_bf16_f32 v30, v30, v31
	v_cvt_pk_bf16_f32 v31, v32, v33
	v_add_u32_e32 v27, 0x2000, v25
	ds_write2_b64 v27, v[34:35], v[30:31] offset0:32 offset1:36
	v_pk_mul_f32 v[30:31], v[22:23], v[54:55] op_sel_hi:[0,1]
	v_pk_mul_f32 v[32:33], v[22:23], v[56:57] op_sel_hi:[0,1]
	v_cvt_pk_bf16_f32 v30, v30, v31
	v_cvt_pk_bf16_f32 v31, v32, v33
	v_add_u32_e32 v40, 0x4000, v25
	ds_write2_b64 v40, v[36:37], v[30:31] offset0:64 offset1:68
	v_pk_mul_f32 v[30:31], v[0:1], v[58:59] op_sel_hi:[0,1]
	v_pk_mul_f32 v[32:33], v[0:1], v[60:61] op_sel_hi:[0,1]
	v_cvt_pk_bf16_f32 v30, v30, v31
	v_cvt_pk_bf16_f32 v31, v32, v33
	v_add_u32_e32 v41, 0x6000, v25
	ds_write2_b64 v41, v[28:29], v[30:31] offset0:96 offset1:100
	v_pk_mul_f32 v[28:29], v[26:27], v[62:63] op_sel_hi:[0,1]
	v_pk_mul_f32 v[30:31], v[26:27], v[64:65] op_sel_hi:[0,1]
	v_cvt_pk_bf16_f32 v28, v28, v29
	v_cvt_pk_bf16_f32 v29, v30, v31
	v_pk_mul_f32 v[30:31], v[24:25], v[66:67] op_sel_hi:[0,1]
	v_pk_mul_f32 v[32:33], v[24:25], v[68:69] op_sel_hi:[0,1]
	v_cvt_pk_bf16_f32 v30, v30, v31
	v_cvt_pk_bf16_f32 v31, v32, v33
	v_pk_mul_f32 v[32:33], v[22:23], v[70:71] op_sel_hi:[0,1]
	v_pk_mul_f32 v[34:35], v[22:23], v[72:73] op_sel_hi:[0,1]
	v_cvt_pk_bf16_f32 v32, v32, v33
	v_cvt_pk_bf16_f32 v33, v34, v35
	v_pk_mul_f32 v[34:35], v[0:1], v[74:75] op_sel_hi:[0,1]
	v_pk_mul_f32 v[36:37], v[0:1], v[76:77] op_sel_hi:[0,1]
	v_cvt_pk_bf16_f32 v34, v34, v35
	v_cvt_pk_bf16_f32 v35, v36, v37
	v_pk_mul_f32 v[36:37], v[26:27], v[78:79] op_sel_hi:[0,1]
	v_pk_mul_f32 v[38:39], v[26:27], v[80:81] op_sel_hi:[0,1]
	v_cvt_pk_bf16_f32 v36, v36, v37
	v_cvt_pk_bf16_f32 v37, v38, v39
	ds_write2_b64 v25, v[28:29], v[36:37] offset0:8 offset1:12
	v_pk_mul_f32 v[28:29], v[24:25], v[82:83] op_sel_hi:[0,1]
	v_pk_mul_f32 v[36:37], v[24:25], v[84:85] op_sel_hi:[0,1]
	v_cvt_pk_bf16_f32 v28, v28, v29
	v_cvt_pk_bf16_f32 v29, v36, v37
	ds_write2_b64 v27, v[30:31], v[28:29] offset0:40 offset1:44
	v_pk_mul_f32 v[28:29], v[22:23], v[86:87] op_sel_hi:[0,1]
	v_pk_mul_f32 v[30:31], v[22:23], v[88:89] op_sel_hi:[0,1]
	v_cvt_pk_bf16_f32 v28, v28, v29
	v_cvt_pk_bf16_f32 v29, v30, v31
	ds_write2_b64 v40, v[32:33], v[28:29] offset0:72 offset1:76
	v_pk_mul_f32 v[28:29], v[0:1], v[154:155] op_sel_hi:[0,1]
	v_pk_mul_f32 v[30:31], v[0:1], v[156:157] op_sel_hi:[0,1]
	v_cvt_pk_bf16_f32 v28, v28, v29
	v_cvt_pk_bf16_f32 v29, v30, v31
	ds_write2_b64 v41, v[34:35], v[28:29] offset0:104 offset1:108
	v_pk_mul_f32 v[28:29], v[26:27], v[90:91] op_sel_hi:[0,1]
	v_pk_mul_f32 v[30:31], v[26:27], v[92:93] op_sel_hi:[0,1]
	v_cvt_pk_bf16_f32 v28, v28, v29
	v_cvt_pk_bf16_f32 v29, v30, v31
	v_pk_mul_f32 v[30:31], v[24:25], v[94:95] op_sel_hi:[0,1]
	v_pk_mul_f32 v[32:33], v[24:25], v[96:97] op_sel_hi:[0,1]
	v_cvt_pk_bf16_f32 v30, v30, v31
	v_cvt_pk_bf16_f32 v31, v32, v33
	v_pk_mul_f32 v[32:33], v[22:23], v[98:99] op_sel_hi:[0,1]
	v_pk_mul_f32 v[34:35], v[22:23], v[100:101] op_sel_hi:[0,1]
	v_cvt_pk_bf16_f32 v32, v32, v33
	v_cvt_pk_bf16_f32 v33, v34, v35
	v_pk_mul_f32 v[34:35], v[0:1], v[158:159] op_sel_hi:[0,1]
	v_pk_mul_f32 v[36:37], v[0:1], v[160:161] op_sel_hi:[0,1]
	v_cvt_pk_bf16_f32 v34, v34, v35
	v_cvt_pk_bf16_f32 v35, v36, v37
	v_pk_mul_f32 v[36:37], v[26:27], v[102:103] op_sel_hi:[0,1]
	v_pk_mul_f32 v[38:39], v[26:27], v[104:105] op_sel_hi:[0,1]
	v_cvt_pk_bf16_f32 v36, v36, v37
	v_cvt_pk_bf16_f32 v37, v38, v39
	ds_write2_b64 v25, v[28:29], v[36:37] offset0:16 offset1:20
	v_pk_mul_f32 v[28:29], v[24:25], v[106:107] op_sel_hi:[0,1]
	v_pk_mul_f32 v[36:37], v[24:25], v[108:109] op_sel_hi:[0,1]
	v_cvt_pk_bf16_f32 v28, v28, v29
	v_cvt_pk_bf16_f32 v29, v36, v37
	ds_write2_b64 v27, v[30:31], v[28:29] offset0:48 offset1:52
	v_pk_mul_f32 v[28:29], v[22:23], v[110:111] op_sel_hi:[0,1]
	v_pk_mul_f32 v[30:31], v[22:23], v[112:113] op_sel_hi:[0,1]
	v_cvt_pk_bf16_f32 v28, v28, v29
	v_cvt_pk_bf16_f32 v29, v30, v31
	ds_write2_b64 v40, v[32:33], v[28:29] offset0:80 offset1:84
	v_pk_mul_f32 v[28:29], v[0:1], v[162:163] op_sel_hi:[0,1]
	v_pk_mul_f32 v[30:31], v[0:1], v[164:165] op_sel_hi:[0,1]
	v_cvt_pk_bf16_f32 v28, v28, v29
	v_cvt_pk_bf16_f32 v29, v30, v31
	ds_write2_b64 v41, v[34:35], v[28:29] offset0:112 offset1:116
	v_pk_mul_f32 v[28:29], v[26:27], v[114:115] op_sel_hi:[0,1]
	v_pk_mul_f32 v[30:31], v[26:27], v[116:117] op_sel_hi:[0,1]
	v_pk_mul_f32 v[18:19], v[0:1], v[18:19] op_sel_hi:[0,1]
	v_pk_mul_f32 v[20:21], v[0:1], v[20:21] op_sel_hi:[0,1]
	v_pk_mul_f32 v[2:3], v[0:1], v[2:3] op_sel_hi:[0,1]
	v_pk_mul_f32 v[4:5], v[0:1], v[4:5] op_sel_hi:[0,1]
	v_lshlrev_b32_e32 v0, 3, v23
	v_cvt_pk_bf16_f32 v28, v28, v29
	v_cvt_pk_bf16_f32 v29, v30, v31
	v_pk_mul_f32 v[30:31], v[24:25], v[118:119] op_sel_hi:[0,1]
	v_pk_mul_f32 v[32:33], v[24:25], v[120:121] op_sel_hi:[0,1]
	v_cvt_pk_bf16_f32 v18, v18, v19
	v_cvt_pk_bf16_f32 v19, v20, v21
	v_cvt_pk_bf16_f32 v2, v2, v3
	v_cvt_pk_bf16_f32 v3, v4, v5
	v_and_b32_e32 v0, 0xf8, v0
	v_cvt_pk_bf16_f32 v30, v30, v31
	v_cvt_pk_bf16_f32 v31, v32, v33
	v_pk_mul_f32 v[32:33], v[22:23], v[122:123] op_sel_hi:[0,1]
	v_pk_mul_f32 v[34:35], v[22:23], v[124:125] op_sel_hi:[0,1]
	v_pk_mul_f32 v[14:15], v[26:27], v[14:15] op_sel_hi:[0,1]
	v_pk_mul_f32 v[16:17], v[26:27], v[16:17] op_sel_hi:[0,1]
	v_pk_mul_f32 v[10:11], v[24:25], v[10:11] op_sel_hi:[0,1]
	v_pk_mul_f32 v[12:13], v[24:25], v[12:13] op_sel_hi:[0,1]
	v_pk_mul_f32 v[6:7], v[22:23], v[6:7] op_sel_hi:[0,1]
	v_pk_mul_f32 v[8:9], v[22:23], v[8:9] op_sel_hi:[0,1]
	ds_write2_b64 v41, v[18:19], v[2:3] offset0:120 offset1:124
	v_or_b32_e32 v2, s54, v0
	s_movk_i32 s12, 0xa30
	v_cvt_pk_bf16_f32 v32, v32, v33
	v_cvt_pk_bf16_f32 v33, v34, v35
	v_cvt_pk_bf16_f32 v14, v14, v15
	v_cvt_pk_bf16_f32 v15, v16, v17
	v_cvt_pk_bf16_f32 v10, v10, v11
	v_cvt_pk_bf16_f32 v11, v12, v13
	v_cvt_pk_bf16_f32 v6, v6, v7
	v_cvt_pk_bf16_f32 v7, v8, v9
	v_cmp_gt_i32_e32 vcc, s12, v2
	ds_write2_b64 v25, v[28:29], v[14:15] offset0:24 offset1:28
	ds_write2_b64 v27, v[30:31], v[10:11] offset0:56 offset1:60
	ds_write2_b64 v40, v[32:33], v[6:7] offset0:88 offset1:92
	s_waitcnt lgkmcnt(0)
	s_barrier
	s_and_saveexec_b64 s[12:13], vcc
	s_cbranch_execz .LBB0_641
	v_ashrrev_i32_e32 v8, 5, v23
	v_lshlrev_b32_e32 v0, 1, v0
	s_movk_i32 s40, 0x210
	v_mad_u64_u32 v[6:7], s[40:41], v8, s40, v[0:1]
	ds_read_b128 v[2:5], v6
	v_add_u32_e32 v7, s57, v8
	v_mov_b64_e32 v[8:9], s[4:5]
	s_ashr_i32 s55, s54, 31
	v_mad_i64_i32 v[10:11], s[40:41], v7, s16, v[8:9]
	s_lshl_b64 s[40:41], s[54:55], 1
	s_nop 0
	v_lshl_add_u64 v[10:11], v[10:11], 0, s[40:41]
	v_lshl_add_u64 v[10:11], v[10:11], 0, v[0:1]
	s_waitcnt lgkmcnt(0)
	global_store_dwordx4 v[10:11], v[2:5], off
	ds_read_b128 v[2:5], v6 offset:4224
	v_add_u32_e32 v10, 8, v7
	v_mad_i64_i32 v[10:11], s[42:43], v10, s16, v[8:9]
	v_lshl_add_u64 v[10:11], v[10:11], 0, s[40:41]
	v_lshl_add_u64 v[10:11], v[10:11], 0, v[0:1]
	s_waitcnt lgkmcnt(0)
	global_store_dwordx4 v[10:11], v[2:5], off
	ds_read_b128 v[2:5], v6 offset:8448
	v_add_u32_e32 v10, 16, v7
	v_mad_i64_i32 v[10:11], s[42:43], v10, s16, v[8:9]
	v_lshl_add_u64 v[10:11], v[10:11], 0, s[40:41]
	v_lshl_add_u64 v[10:11], v[10:11], 0, v[0:1]
	s_waitcnt lgkmcnt(0)
	global_store_dwordx4 v[10:11], v[2:5], off
	ds_read_b128 v[2:5], v6 offset:12672
	v_add_u32_e32 v10, 24, v7
	v_mad_i64_i32 v[10:11], s[42:43], v10, s16, v[8:9]
	v_lshl_add_u64 v[10:11], v[10:11], 0, s[40:41]
	v_lshl_add_u64 v[10:11], v[10:11], 0, v[0:1]
	s_waitcnt lgkmcnt(0)
	global_store_dwordx4 v[10:11], v[2:5], off
	ds_read_b128 v[2:5], v6 offset:16896
	v_add_u32_e32 v10, 32, v7
	v_mad_i64_i32 v[10:11], s[42:43], v10, s16, v[8:9]
	v_lshl_add_u64 v[10:11], v[10:11], 0, s[40:41]
	v_lshl_add_u64 v[10:11], v[10:11], 0, v[0:1]
	s_waitcnt lgkmcnt(0)
	global_store_dwordx4 v[10:11], v[2:5], off
	ds_read_b128 v[2:5], v6 offset:21120
	v_add_u32_e32 v10, 40, v7
	v_mad_i64_i32 v[10:11], s[42:43], v10, s16, v[8:9]
	v_lshl_add_u64 v[10:11], v[10:11], 0, s[40:41]
	v_lshl_add_u64 v[10:11], v[10:11], 0, v[0:1]
	s_waitcnt lgkmcnt(0)
	global_store_dwordx4 v[10:11], v[2:5], off
	ds_read_b128 v[2:5], v6 offset:25344
	v_add_u32_e32 v10, 48, v7
	v_mad_i64_i32 v[10:11], s[42:43], v10, s16, v[8:9]
	v_lshl_add_u64 v[10:11], v[10:11], 0, s[40:41]
	v_lshl_add_u64 v[10:11], v[10:11], 0, v[0:1]
	s_waitcnt lgkmcnt(0)
	global_store_dwordx4 v[10:11], v[2:5], off
	ds_read_b128 v[2:5], v6 offset:29568
	v_add_u32_e32 v10, 56, v7
	v_mad_i64_i32 v[10:11], s[42:43], v10, s16, v[8:9]
	v_lshl_add_u64 v[10:11], v[10:11], 0, s[40:41]
	v_lshl_add_u64 v[10:11], v[10:11], 0, v[0:1]
	s_waitcnt lgkmcnt(0)
	global_store_dwordx4 v[10:11], v[2:5], off
	ds_read_b128 v[2:5], v6 offset:33792
	v_add_u32_e32 v10, 64, v7
	v_mad_i64_i32 v[10:11], s[42:43], v10, s16, v[8:9]
	v_lshl_add_u64 v[10:11], v[10:11], 0, s[40:41]
	v_lshl_add_u64 v[10:11], v[10:11], 0, v[0:1]
	s_waitcnt lgkmcnt(0)
	global_store_dwordx4 v[10:11], v[2:5], off
	ds_read_b128 v[2:5], v6 offset:38016
	v_add_u32_e32 v10, 0x48, v7
	v_mad_i64_i32 v[10:11], s[42:43], v10, s16, v[8:9]
	v_lshl_add_u64 v[10:11], v[10:11], 0, s[40:41]
	v_lshl_add_u64 v[10:11], v[10:11], 0, v[0:1]
	s_waitcnt lgkmcnt(0)
	global_store_dwordx4 v[10:11], v[2:5], off
	ds_read_b128 v[2:5], v6 offset:42240
	v_add_u32_e32 v10, 0x50, v7
	v_mad_i64_i32 v[10:11], s[42:43], v10, s16, v[8:9]
	v_lshl_add_u64 v[10:11], v[10:11], 0, s[40:41]
	v_lshl_add_u64 v[10:11], v[10:11], 0, v[0:1]
	s_waitcnt lgkmcnt(0)
	global_store_dwordx4 v[10:11], v[2:5], off
	ds_read_b128 v[2:5], v6 offset:46464
	v_add_u32_e32 v10, 0x58, v7
	v_mad_i64_i32 v[10:11], s[42:43], v10, s16, v[8:9]
	v_lshl_add_u64 v[10:11], v[10:11], 0, s[40:41]
	v_lshl_add_u64 v[10:11], v[10:11], 0, v[0:1]
	s_waitcnt lgkmcnt(0)
	global_store_dwordx4 v[10:11], v[2:5], off
	ds_read_b128 v[2:5], v6 offset:50688
	v_add_u32_e32 v10, 0x60, v7
	v_mad_i64_i32 v[10:11], s[42:43], v10, s16, v[8:9]
	v_lshl_add_u64 v[10:11], v[10:11], 0, s[40:41]
	v_lshl_add_u64 v[10:11], v[10:11], 0, v[0:1]
	s_waitcnt lgkmcnt(0)
	global_store_dwordx4 v[10:11], v[2:5], off
	ds_read_b128 v[2:5], v6 offset:54912
	v_add_u32_e32 v10, 0x68, v7
	v_mad_i64_i32 v[10:11], s[42:43], v10, s16, v[8:9]
	v_lshl_add_u64 v[10:11], v[10:11], 0, s[40:41]
	v_lshl_add_u64 v[10:11], v[10:11], 0, v[0:1]
	s_waitcnt lgkmcnt(0)
	global_store_dwordx4 v[10:11], v[2:5], off
	ds_read_b128 v[2:5], v6 offset:59136
	v_add_u32_e32 v10, 0x70, v7
	v_mad_i64_i32 v[10:11], s[42:43], v10, s16, v[8:9]
	v_lshl_add_u64 v[10:11], v[10:11], 0, s[40:41]
	v_lshl_add_u64 v[10:11], v[10:11], 0, v[0:1]
	s_waitcnt lgkmcnt(0)
	global_store_dwordx4 v[10:11], v[2:5], off
	ds_read_b128 v[2:5], v6 offset:63360
	v_add_u32_e32 v6, 0x78, v7
	v_mad_i64_i32 v[6:7], s[42:43], v6, s16, v[8:9]
	v_lshl_add_u64 v[6:7], v[6:7], 0, s[40:41]
	v_lshl_add_u64 v[6:7], v[6:7], 0, v[0:1]
	s_waitcnt lgkmcnt(0)
	global_store_dwordx4 v[6:7], v[2:5], off
	s_branch .LBB0_641
